# norm/combine/final rows: dead denormal rescue around v_rsq_f32 removed (argument >= 1e-6 epsilon), 5 fewer dependent VALU ops per row chain, bit-identical
# speedup vs baseline: 1.0132x; 1.0010x over previous
.LBB0_99:
	s_or_b64 exec, exec, s[8:9]
	s_waitcnt vmcnt(7)
	v_mov_b32_e32 v50, v37
	s_waitcnt vmcnt(6)
	v_mov_b32_e32 v51, v33
	v_mov_b32_e32 v48, v36
	v_mov_b32_e32 v49, v32
	v_pk_mul_f32 v[50:51], v[50:51], v[50:51]
	s_waitcnt vmcnt(5)
	v_mov_b32_e32 v52, v29
	v_pk_fma_f32 v[48:49], v[48:49], v[48:49], v[50:51]
	v_mov_b32_e32 v50, v38
	v_mov_b32_e32 v51, v34
	v_pk_fma_f32 v[48:49], v[50:51], v[50:51], v[48:49]
	v_mov_b32_e32 v50, v39
	v_mov_b32_e32 v51, v35
	s_waitcnt vmcnt(4)
	v_mov_b32_e32 v53, v25
	v_pk_fma_f32 v[48:49], v[50:51], v[50:51], v[48:49]
	v_mov_b32_e32 v50, v28
	v_mov_b32_e32 v51, v24
	v_pk_mul_f32 v[52:53], v[52:53], v[52:53]
	v_add_f32_e32 v48, v48, v49
	v_pk_fma_f32 v[50:51], v[50:51], v[50:51], v[52:53]
	v_mov_b32_e32 v52, v30
	v_mov_b32_e32 v53, v26
	v_pk_fma_f32 v[50:51], v[52:53], v[52:53], v[50:51]
	v_mov_b32_e32 v52, v31
	v_mov_b32_e32 v53, v27
	v_pk_fma_f32 v[50:51], v[52:53], v[52:53], v[50:51]
	v_ashrrev_i32_e32 v163, 31, v162
	v_add_f32_e32 v48, v48, v50
	v_add_f32_e32 v48, v48, v51
	ds_bpermute_b32 v49, v178, v48
	v_lshlrev_b64 v[52:53], 11, v[162:163]
	v_lshl_add_u64 v[52:53], v[148:149], 0, v[52:53]
	s_waitcnt lgkmcnt(0)
	v_add_f32_e32 v48, v48, v49
	ds_bpermute_b32 v49, v179, v48
	s_waitcnt lgkmcnt(0)
	v_add_f32_e32 v48, v48, v49
	s_nop 1
	v_add_f32_dpp v48, v48, v48 row_ror:8 row_mask:0xf bank_mask:0xf
	s_nop 1
	v_add_f32_dpp v48, v48, v48 row_ror:4 row_mask:0xf bank_mask:0xf
	s_nop 1
	v_add_f32_dpp v50, v48, v48 quad_perm:[2,3,0,1] row_mask:0xf bank_mask:0xf
	v_pk_add_f32 v[48:49], v[22:23], 1.0 op_sel_hi:[1,0]
	s_nop 1
	v_add_f32_dpp v50, v50, v50 quad_perm:[1,0,3,2] row_mask:0xf bank_mask:0xf
	v_fmamk_f32 v50, v50, 0x3a800000, v184
	v_rsq_f32_e32 v54, v50
	v_pk_add_f32 v[50:51], v[20:21], 1.0 op_sel_hi:[1,0]
	v_pk_mul_f32 v[38:39], v[38:39], v[54:55] op_sel_hi:[1,0]
	v_pk_mul_f32 v[36:37], v[36:37], v[54:55] op_sel_hi:[1,0]
	v_pk_mul_f32 v[38:39], v[2:3], v[38:39]
	v_pk_mul_f32 v[36:37], v[0:1], v[36:37]
	v_pk_fma_f32 v[38:39], v[48:49], v[38:39], v[18:19]
	v_pk_fma_f32 v[36:37], v[50:51], v[36:37], v[16:17]
	v_pk_mul_f32 v[34:35], v[34:35], v[54:55] op_sel_hi:[1,0]
	v_cvt_pk_bf16_f32 v36, v36, v37
	v_cvt_pk_bf16_f32 v37, v38, v39
	v_pk_mul_f32 v[32:33], v[32:33], v[54:55] op_sel_hi:[1,0]
	global_store_dwordx2 v[52:53], v[36:37], off
	v_pk_mul_f32 v[32:33], v[4:5], v[32:33]
	v_pk_mul_f32 v[34:35], v[6:7], v[34:35]
	v_pk_add_f32 v[36:37], v[46:47], 1.0 op_sel_hi:[1,0]
	v_pk_add_f32 v[38:39], v[44:45], 1.0 op_sel_hi:[1,0]
	v_pk_fma_f32 v[34:35], v[36:37], v[34:35], v[42:43]
	v_pk_fma_f32 v[32:33], v[38:39], v[32:33], v[40:41]
	v_pk_mul_f32 v[30:31], v[30:31], v[54:55] op_sel_hi:[1,0]
	v_cvt_pk_bf16_f32 v32, v32, v33
	v_cvt_pk_bf16_f32 v33, v34, v35
	v_pk_mul_f32 v[28:29], v[28:29], v[54:55] op_sel_hi:[1,0]
	global_store_dwordx2 v[52:53], v[32:33], off offset:512
	v_pk_mul_f32 v[28:29], v[8:9], v[28:29]
	v_pk_mul_f32 v[30:31], v[10:11], v[30:31]
	v_pk_add_f32 v[32:33], v[70:71], 1.0 op_sel_hi:[1,0]
	v_pk_add_f32 v[34:35], v[68:69], 1.0 op_sel_hi:[1,0]
	v_pk_fma_f32 v[30:31], v[32:33], v[30:31], v[66:67]
	v_pk_fma_f32 v[28:29], v[34:35], v[28:29], v[64:65]
	v_pk_mul_f32 v[26:27], v[26:27], v[54:55] op_sel_hi:[1,0]
	v_cvt_pk_bf16_f32 v28, v28, v29
	v_cvt_pk_bf16_f32 v29, v30, v31
	v_pk_mul_f32 v[24:25], v[24:25], v[54:55] op_sel_hi:[1,0]
	global_store_dwordx2 v[52:53], v[28:29], off offset:1024
	v_pk_mul_f32 v[24:25], v[12:13], v[24:25]
	v_pk_mul_f32 v[26:27], v[14:15], v[26:27]
	v_pk_add_f32 v[28:29], v[94:95], 1.0 op_sel_hi:[1,0]
	v_pk_add_f32 v[30:31], v[92:93], 1.0 op_sel_hi:[1,0]
	v_pk_fma_f32 v[26:27], v[28:29], v[26:27], v[90:91]
	v_pk_fma_f32 v[24:25], v[30:31], v[24:25], v[88:89]
	s_nop 0
	v_cvt_pk_bf16_f32 v24, v24, v25
	v_cvt_pk_bf16_f32 v25, v26, v27
	global_store_dwordx2 v[52:53], v[24:25], off offset:1536

.LBB0_111:
	s_or_b64 exec, exec, s[6:7]
	s_waitcnt vmcnt(23)
	v_mov_b32_e32 v174, v141
	s_waitcnt vmcnt(22)
	v_mov_b32_e32 v175, v137
	v_mov_b32_e32 v172, v140
	v_mov_b32_e32 v173, v136
	v_pk_mul_f32 v[174:175], v[174:175], v[174:175]
	s_waitcnt vmcnt(21)
	v_mov_b32_e32 v186, v133
	v_pk_fma_f32 v[172:173], v[172:173], v[172:173], v[174:175]
	v_mov_b32_e32 v174, v142
	v_mov_b32_e32 v175, v138
	v_pk_fma_f32 v[172:173], v[174:175], v[174:175], v[172:173]
	v_mov_b32_e32 v174, v143
	v_mov_b32_e32 v175, v139
	s_waitcnt vmcnt(20)
	v_mov_b32_e32 v187, v129
	v_pk_fma_f32 v[172:173], v[174:175], v[174:175], v[172:173]
	v_mov_b32_e32 v174, v132
	v_mov_b32_e32 v175, v128
	v_pk_mul_f32 v[186:187], v[186:187], v[186:187]
	v_add_f32_e32 v145, v172, v173
	v_pk_fma_f32 v[174:175], v[174:175], v[174:175], v[186:187]
	v_mov_b32_e32 v186, v134
	v_mov_b32_e32 v187, v130
	v_pk_fma_f32 v[174:175], v[186:187], v[186:187], v[174:175]
	v_mov_b32_e32 v186, v135
	v_mov_b32_e32 v187, v131
	v_pk_fma_f32 v[174:175], v[186:187], v[186:187], v[174:175]
	v_pk_add_f32 v[172:173], v[22:23], 1.0 op_sel_hi:[1,0]
	v_add_f32_e32 v145, v145, v174
	v_add_f32_e32 v145, v145, v175
	ds_bpermute_b32 v163, v178, v145
	v_pk_add_f32 v[174:175], v[20:21], 1.0 op_sel_hi:[1,0]
	s_waitcnt lgkmcnt(0)
	v_add_f32_e32 v145, v145, v163
	ds_bpermute_b32 v163, v179, v145
	s_waitcnt lgkmcnt(0)
	v_add_f32_e32 v145, v145, v163
	s_nop 1
	v_add_f32_dpp v145, v145, v145 row_ror:8 row_mask:0xf bank_mask:0xf
	s_nop 1
	v_add_f32_dpp v145, v145, v145 row_ror:4 row_mask:0xf bank_mask:0xf
	s_nop 1
	v_add_f32_dpp v163, v145, v145 quad_perm:[2,3,0,1] row_mask:0xf bank_mask:0xf
	v_ashrrev_i32_e32 v145, 31, v144
	v_lshlrev_b64 v[186:187], 11, v[144:145]
	v_lshl_add_u64 v[186:187], v[148:149], 0, v[186:187]
	s_nop 1
	v_add_f32_dpp v163, v163, v163 quad_perm:[1,0,3,2] row_mask:0xf bank_mask:0xf
	v_fmamk_f32 v163, v163, 0x3a800000, v184
	v_rsq_f32_e32 v163, v163
	s_nop 0
	v_mov_b32_e32 v188, v163
	v_pk_mul_f32 v[142:143], v[142:143], v[188:189] op_sel_hi:[1,0]
	v_pk_mul_f32 v[140:141], v[140:141], v[188:189] op_sel_hi:[1,0]
	v_pk_mul_f32 v[142:143], v[2:3], v[142:143]
	v_pk_mul_f32 v[140:141], v[0:1], v[140:141]
	v_pk_fma_f32 v[142:143], v[172:173], v[142:143], v[18:19]
	v_pk_fma_f32 v[140:141], v[174:175], v[140:141], v[16:17]
	v_pk_mul_f32 v[138:139], v[138:139], v[188:189] op_sel_hi:[1,0]
	v_cvt_pk_bf16_f32 v140, v140, v141
	v_cvt_pk_bf16_f32 v141, v142, v143
	v_pk_mul_f32 v[136:137], v[136:137], v[188:189] op_sel_hi:[1,0]
	global_store_dwordx2 v[186:187], v[140:141], off
	v_pk_mul_f32 v[140:141], v[4:5], v[136:137]
	v_pk_mul_f32 v[142:143], v[6:7], v[138:139]
	v_pk_add_f32 v[136:137], v[46:47], 1.0 op_sel_hi:[1,0]
	v_pk_add_f32 v[138:139], v[44:45], 1.0 op_sel_hi:[1,0]
	v_pk_fma_f32 v[142:143], v[136:137], v[142:143], v[42:43]
	v_pk_fma_f32 v[140:141], v[138:139], v[140:141], v[40:41]
	v_pk_mul_f32 v[134:135], v[134:135], v[188:189] op_sel_hi:[1,0]
	v_cvt_pk_bf16_f32 v140, v140, v141
	v_cvt_pk_bf16_f32 v141, v142, v143
	v_pk_mul_f32 v[132:133], v[132:133], v[188:189] op_sel_hi:[1,0]
	global_store_dwordx2 v[186:187], v[140:141], off offset:512
	v_pk_mul_f32 v[140:141], v[8:9], v[132:133]
	v_pk_mul_f32 v[142:143], v[10:11], v[134:135]
	v_pk_add_f32 v[132:133], v[70:71], 1.0 op_sel_hi:[1,0]
	v_pk_add_f32 v[134:135], v[68:69], 1.0 op_sel_hi:[1,0]
	v_pk_fma_f32 v[142:143], v[132:133], v[142:143], v[66:67]
	v_pk_fma_f32 v[140:141], v[134:135], v[140:141], v[64:65]
	v_pk_mul_f32 v[130:131], v[130:131], v[188:189] op_sel_hi:[1,0]
	v_cvt_pk_bf16_f32 v140, v140, v141
	v_cvt_pk_bf16_f32 v141, v142, v143
	v_pk_mul_f32 v[128:129], v[128:129], v[188:189] op_sel_hi:[1,0]
	global_store_dwordx2 v[186:187], v[140:141], off offset:1024
	v_pk_mul_f32 v[140:141], v[12:13], v[128:129]
	v_pk_mul_f32 v[142:143], v[14:15], v[130:131]
	v_pk_add_f32 v[128:129], v[94:95], 1.0 op_sel_hi:[1,0]
	v_pk_add_f32 v[130:131], v[92:93], 1.0 op_sel_hi:[1,0]
	v_pk_fma_f32 v[142:143], v[128:129], v[142:143], v[90:91]
	v_pk_fma_f32 v[140:141], v[130:131], v[140:141], v[88:89]
	v_cmp_lt_i32_e32 vcc, v170, v176
	v_cvt_pk_bf16_f32 v140, v140, v141
	v_cvt_pk_bf16_f32 v141, v142, v143
	global_store_dwordx2 v[186:187], v[140:141], off offset:1536
	s_and_saveexec_b64 s[6:7], vcc
	s_cbranch_execz .LBB0_136
	v_add_u32_e32 v140, 0xffffe001, v144
	v_ashrrev_i32_e32 v140, 10, v140
	v_add_u32_e32 v140, 1, v140
	v_cmp_lt_i32_e32 vcc, s15, v144
	s_nop 1
	v_cndmask_b32_e32 v140, 0, v140, vcc
	v_cmp_ne_u32_e32 vcc, v140, v185
	s_and_saveexec_b64 s[8:9], vcc
	s_cbranch_execz .LBB0_122
	global_load_dwordx4 v[16:19], v[150:151], off
	global_load_dwordx4 v[20:23], v[152:153], off
	v_mad_i64_i32 v[128:129], s[10:11], v140, s3, v[160:161]
	s_mov_b64 s[10:11], 0

.LBB0_122:
	s_or_b64 exec, exec, s[8:9]
	s_waitcnt vmcnt(23)
	v_mov_b32_e32 v142, v125
	s_waitcnt vmcnt(22)
	v_mov_b32_e32 v143, v121
	v_mov_b32_e32 v140, v124
	v_mov_b32_e32 v141, v120
	v_pk_mul_f32 v[142:143], v[142:143], v[142:143]
	s_waitcnt vmcnt(21)
	v_mov_b32_e32 v186, v117
	v_pk_fma_f32 v[140:141], v[140:141], v[140:141], v[142:143]
	v_mov_b32_e32 v142, v126
	v_mov_b32_e32 v143, v122
	v_pk_fma_f32 v[140:141], v[142:143], v[142:143], v[140:141]
	v_mov_b32_e32 v142, v127
	v_mov_b32_e32 v143, v123
	s_waitcnt vmcnt(20)
	v_mov_b32_e32 v187, v113
	v_pk_fma_f32 v[140:141], v[142:143], v[142:143], v[140:141]
	v_mov_b32_e32 v142, v116
	v_mov_b32_e32 v143, v112
	v_pk_mul_f32 v[186:187], v[186:187], v[186:187]
	v_add_f32_e32 v140, v140, v141
	v_pk_fma_f32 v[142:143], v[142:143], v[142:143], v[186:187]
	v_mov_b32_e32 v186, v118
	v_mov_b32_e32 v187, v114
	v_pk_fma_f32 v[142:143], v[186:187], v[186:187], v[142:143]
	v_mov_b32_e32 v186, v119
	v_mov_b32_e32 v187, v115
	v_pk_fma_f32 v[142:143], v[186:187], v[186:187], v[142:143]
	v_ashrrev_i32_e32 v171, 31, v170
	v_add_f32_e32 v140, v140, v142
	v_add_f32_e32 v140, v140, v143
	ds_bpermute_b32 v141, v178, v140
	s_waitcnt lgkmcnt(0)
	v_add_f32_e32 v140, v140, v141
	ds_bpermute_b32 v141, v179, v140
	s_waitcnt lgkmcnt(0)
	v_add_f32_e32 v140, v140, v141
	s_nop 1
	v_add_f32_dpp v140, v140, v140 row_ror:8 row_mask:0xf bank_mask:0xf
	s_nop 1
	v_add_f32_dpp v140, v140, v140 row_ror:4 row_mask:0xf bank_mask:0xf
	s_nop 1
	v_add_f32_dpp v140, v140, v140 quad_perm:[2,3,0,1] row_mask:0xf bank_mask:0xf
	s_nop 1
	v_add_f32_dpp v140, v140, v140 quad_perm:[1,0,3,2] row_mask:0xf bank_mask:0xf
	v_fmamk_f32 v140, v140, 0x3a800000, v184
	v_rsq_f32_e32 v142, v140
	v_lshlrev_b64 v[140:141], 11, v[170:171]
	v_lshl_add_u64 v[140:141], v[148:149], 0, v[140:141]
	v_pk_mul_f32 v[126:127], v[126:127], v[142:143] op_sel_hi:[1,0]
	v_pk_mul_f32 v[124:125], v[124:125], v[142:143] op_sel_hi:[1,0]
	v_pk_mul_f32 v[122:123], v[122:123], v[142:143] op_sel_hi:[1,0]
	v_pk_mul_f32 v[120:121], v[120:121], v[142:143] op_sel_hi:[1,0]
	v_pk_mul_f32 v[118:119], v[118:119], v[142:143] op_sel_hi:[1,0]
	v_pk_mul_f32 v[116:117], v[116:117], v[142:143] op_sel_hi:[1,0]
	v_pk_mul_f32 v[114:115], v[114:115], v[142:143] op_sel_hi:[1,0]
	v_pk_mul_f32 v[112:113], v[112:113], v[142:143] op_sel_hi:[1,0]
	v_pk_mul_f32 v[124:125], v[0:1], v[124:125]
	v_pk_mul_f32 v[126:127], v[2:3], v[126:127]
	v_pk_mul_f32 v[120:121], v[4:5], v[120:121]
	v_pk_mul_f32 v[122:123], v[6:7], v[122:123]
	v_pk_mul_f32 v[116:117], v[8:9], v[116:117]
	v_pk_mul_f32 v[118:119], v[10:11], v[118:119]
	v_pk_mul_f32 v[112:113], v[12:13], v[112:113]
	v_pk_mul_f32 v[114:115], v[14:15], v[114:115]
	v_pk_fma_f32 v[126:127], v[172:173], v[126:127], v[18:19]
	v_pk_fma_f32 v[124:125], v[174:175], v[124:125], v[16:17]
	v_pk_fma_f32 v[122:123], v[136:137], v[122:123], v[42:43]
	v_pk_fma_f32 v[120:121], v[138:139], v[120:121], v[40:41]
	v_pk_fma_f32 v[118:119], v[132:133], v[118:119], v[66:67]
	v_pk_fma_f32 v[116:117], v[134:135], v[116:117], v[64:65]
	v_pk_fma_f32 v[114:115], v[128:129], v[114:115], v[90:91]
	v_pk_fma_f32 v[112:113], v[130:131], v[112:113], v[88:89]
	v_cvt_pk_bf16_f32 v124, v124, v125
	v_cvt_pk_bf16_f32 v125, v126, v127
	v_cvt_pk_bf16_f32 v120, v120, v121
	v_cvt_pk_bf16_f32 v121, v122, v123
	v_cvt_pk_bf16_f32 v116, v116, v117
	v_cvt_pk_bf16_f32 v117, v118, v119
	v_cvt_pk_bf16_f32 v112, v112, v113
	v_cvt_pk_bf16_f32 v113, v114, v115
	global_store_dwordx2 v[140:141], v[124:125], off
	global_store_dwordx2 v[140:141], v[120:121], off offset:512
	global_store_dwordx2 v[140:141], v[116:117], off offset:1024
	global_store_dwordx2 v[140:141], v[112:113], off offset:1536
	s_or_b64 exec, exec, s[6:7]
	v_cmp_lt_i32_e32 vcc, v168, v176
	s_and_saveexec_b64 s[6:7], vcc
	s_cbranch_execnz .LBB0_137

.LBB0_134:
	s_or_b64 exec, exec, s[8:9]
	s_waitcnt vmcnt(15)
	v_mov_b32_e32 v98, v85
	s_waitcnt vmcnt(14)
	v_mov_b32_e32 v99, v81
	v_mov_b32_e32 v96, v84
	v_mov_b32_e32 v97, v80
	v_pk_mul_f32 v[98:99], v[98:99], v[98:99]
	s_waitcnt vmcnt(13)
	v_mov_b32_e32 v100, v77
	v_pk_fma_f32 v[96:97], v[96:97], v[96:97], v[98:99]
	v_mov_b32_e32 v98, v86
	v_mov_b32_e32 v99, v82
	v_pk_fma_f32 v[96:97], v[98:99], v[98:99], v[96:97]
	v_mov_b32_e32 v98, v87
	v_mov_b32_e32 v99, v83
	s_waitcnt vmcnt(12)
	v_mov_b32_e32 v101, v73
	v_pk_fma_f32 v[96:97], v[98:99], v[98:99], v[96:97]
	v_mov_b32_e32 v98, v76
	v_mov_b32_e32 v99, v72
	v_pk_mul_f32 v[100:101], v[100:101], v[100:101]
	v_add_f32_e32 v96, v96, v97
	v_pk_fma_f32 v[98:99], v[98:99], v[98:99], v[100:101]
	v_mov_b32_e32 v100, v78
	v_mov_b32_e32 v101, v74
	v_pk_fma_f32 v[98:99], v[100:101], v[100:101], v[98:99]
	v_mov_b32_e32 v100, v79
	v_mov_b32_e32 v101, v75
	v_pk_fma_f32 v[98:99], v[100:101], v[100:101], v[98:99]
	v_ashrrev_i32_e32 v167, 31, v166
	v_add_f32_e32 v96, v96, v98
	v_add_f32_e32 v96, v96, v99
	ds_bpermute_b32 v97, v178, v96
	v_lshlrev_b64 v[100:101], 11, v[166:167]
	v_lshl_add_u64 v[100:101], v[148:149], 0, v[100:101]
	s_waitcnt lgkmcnt(0)
	v_add_f32_e32 v96, v96, v97
	ds_bpermute_b32 v97, v179, v96
	s_waitcnt lgkmcnt(0)
	v_add_f32_e32 v96, v96, v97
	s_nop 1
	v_add_f32_dpp v96, v96, v96 row_ror:8 row_mask:0xf bank_mask:0xf
	s_nop 1
	v_add_f32_dpp v96, v96, v96 row_ror:4 row_mask:0xf bank_mask:0xf
	s_nop 1
	v_add_f32_dpp v98, v96, v96 quad_perm:[2,3,0,1] row_mask:0xf bank_mask:0xf
	v_pk_add_f32 v[96:97], v[22:23], 1.0 op_sel_hi:[1,0]
	s_nop 1
	v_add_f32_dpp v98, v98, v98 quad_perm:[1,0,3,2] row_mask:0xf bank_mask:0xf
	v_fmamk_f32 v98, v98, 0x3a800000, v184
	v_rsq_f32_e32 v102, v98
	v_pk_add_f32 v[98:99], v[20:21], 1.0 op_sel_hi:[1,0]
	v_pk_mul_f32 v[86:87], v[86:87], v[102:103] op_sel_hi:[1,0]
	v_pk_mul_f32 v[84:85], v[84:85], v[102:103] op_sel_hi:[1,0]
	v_pk_mul_f32 v[86:87], v[2:3], v[86:87]
	v_pk_mul_f32 v[84:85], v[0:1], v[84:85]
	v_pk_fma_f32 v[86:87], v[96:97], v[86:87], v[18:19]
	v_pk_fma_f32 v[84:85], v[98:99], v[84:85], v[16:17]
	v_pk_mul_f32 v[82:83], v[82:83], v[102:103] op_sel_hi:[1,0]
	v_cvt_pk_bf16_f32 v84, v84, v85
	v_cvt_pk_bf16_f32 v85, v86, v87
	v_pk_mul_f32 v[80:81], v[80:81], v[102:103] op_sel_hi:[1,0]
	global_store_dwordx2 v[100:101], v[84:85], off
	v_pk_mul_f32 v[80:81], v[4:5], v[80:81]
	v_pk_mul_f32 v[82:83], v[6:7], v[82:83]
	v_pk_add_f32 v[84:85], v[46:47], 1.0 op_sel_hi:[1,0]
	v_pk_add_f32 v[86:87], v[44:45], 1.0 op_sel_hi:[1,0]
	v_pk_fma_f32 v[82:83], v[84:85], v[82:83], v[42:43]
	v_pk_fma_f32 v[80:81], v[86:87], v[80:81], v[40:41]
	v_pk_mul_f32 v[78:79], v[78:79], v[102:103] op_sel_hi:[1,0]
	v_cvt_pk_bf16_f32 v80, v80, v81
	v_cvt_pk_bf16_f32 v81, v82, v83
	v_pk_mul_f32 v[76:77], v[76:77], v[102:103] op_sel_hi:[1,0]
	global_store_dwordx2 v[100:101], v[80:81], off offset:512
	v_pk_mul_f32 v[76:77], v[8:9], v[76:77]
	v_pk_mul_f32 v[78:79], v[10:11], v[78:79]
	v_pk_add_f32 v[80:81], v[70:71], 1.0 op_sel_hi:[1,0]
	v_pk_add_f32 v[82:83], v[68:69], 1.0 op_sel_hi:[1,0]
	v_pk_fma_f32 v[78:79], v[80:81], v[78:79], v[66:67]
	v_pk_fma_f32 v[76:77], v[82:83], v[76:77], v[64:65]
	v_pk_mul_f32 v[74:75], v[74:75], v[102:103] op_sel_hi:[1,0]
	v_cvt_pk_bf16_f32 v76, v76, v77
	v_cvt_pk_bf16_f32 v77, v78, v79
	v_pk_mul_f32 v[72:73], v[72:73], v[102:103] op_sel_hi:[1,0]
	global_store_dwordx2 v[100:101], v[76:77], off offset:1024
	v_pk_mul_f32 v[72:73], v[12:13], v[72:73]
	v_pk_mul_f32 v[74:75], v[14:15], v[74:75]
	v_pk_add_f32 v[76:77], v[94:95], 1.0 op_sel_hi:[1,0]
	v_pk_add_f32 v[78:79], v[92:93], 1.0 op_sel_hi:[1,0]
	v_pk_fma_f32 v[74:75], v[76:77], v[74:75], v[90:91]
	v_pk_fma_f32 v[72:73], v[78:79], v[72:73], v[88:89]
	s_nop 0
	v_cvt_pk_bf16_f32 v72, v72, v73
	v_cvt_pk_bf16_f32 v73, v74, v75
	global_store_dwordx2 v[100:101], v[72:73], off offset:1536
	s_or_b64 exec, exec, s[6:7]
	v_cmp_lt_i32_e32 vcc, v164, v176
	s_and_saveexec_b64 s[6:7], vcc
	s_cbranch_execnz .LBB0_149

.LBB0_147:
	s_or_b64 exec, exec, s[8:9]
	s_waitcnt vmcnt(19)
	v_mov_b32_e32 v114, v109
	s_waitcnt vmcnt(18)
	v_mov_b32_e32 v115, v105
	v_mov_b32_e32 v112, v108
	v_mov_b32_e32 v113, v104
	v_pk_mul_f32 v[114:115], v[114:115], v[114:115]
	s_waitcnt vmcnt(17)
	v_mov_b32_e32 v116, v101
	v_pk_fma_f32 v[112:113], v[112:113], v[112:113], v[114:115]
	v_mov_b32_e32 v114, v110
	v_mov_b32_e32 v115, v106
	v_pk_fma_f32 v[112:113], v[114:115], v[114:115], v[112:113]
	v_mov_b32_e32 v114, v111
	v_mov_b32_e32 v115, v107
	s_waitcnt vmcnt(16)
	v_mov_b32_e32 v117, v97
	v_pk_fma_f32 v[112:113], v[114:115], v[114:115], v[112:113]
	v_mov_b32_e32 v114, v100
	v_mov_b32_e32 v115, v96
	v_pk_mul_f32 v[116:117], v[116:117], v[116:117]
	v_add_f32_e32 v112, v112, v113
	v_pk_fma_f32 v[114:115], v[114:115], v[114:115], v[116:117]
	v_mov_b32_e32 v116, v102
	v_mov_b32_e32 v117, v98
	v_pk_fma_f32 v[114:115], v[116:117], v[116:117], v[114:115]
	v_mov_b32_e32 v116, v103
	v_mov_b32_e32 v117, v99
	v_pk_fma_f32 v[114:115], v[116:117], v[116:117], v[114:115]
	v_ashrrev_i32_e32 v169, 31, v168
	v_add_f32_e32 v112, v112, v114
	v_add_f32_e32 v112, v112, v115
	ds_bpermute_b32 v113, v178, v112
	v_lshlrev_b64 v[116:117], 11, v[168:169]
	v_lshl_add_u64 v[116:117], v[148:149], 0, v[116:117]
	s_waitcnt lgkmcnt(0)
	v_add_f32_e32 v112, v112, v113
	ds_bpermute_b32 v113, v179, v112
	s_waitcnt lgkmcnt(0)
	v_add_f32_e32 v112, v112, v113
	s_nop 1
	v_add_f32_dpp v112, v112, v112 row_ror:8 row_mask:0xf bank_mask:0xf
	s_nop 1
	v_add_f32_dpp v112, v112, v112 row_ror:4 row_mask:0xf bank_mask:0xf
	s_nop 1
	v_add_f32_dpp v114, v112, v112 quad_perm:[2,3,0,1] row_mask:0xf bank_mask:0xf
	v_pk_add_f32 v[112:113], v[22:23], 1.0 op_sel_hi:[1,0]
	s_nop 1
	v_add_f32_dpp v114, v114, v114 quad_perm:[1,0,3,2] row_mask:0xf bank_mask:0xf
	v_fmamk_f32 v114, v114, 0x3a800000, v184
	v_rsq_f32_e32 v118, v114
	v_pk_add_f32 v[114:115], v[20:21], 1.0 op_sel_hi:[1,0]
	v_pk_mul_f32 v[110:111], v[110:111], v[118:119] op_sel_hi:[1,0]
	v_pk_mul_f32 v[108:109], v[108:109], v[118:119] op_sel_hi:[1,0]
	v_pk_mul_f32 v[110:111], v[2:3], v[110:111]
	v_pk_mul_f32 v[108:109], v[0:1], v[108:109]
	v_pk_fma_f32 v[110:111], v[112:113], v[110:111], v[18:19]
	v_pk_fma_f32 v[108:109], v[114:115], v[108:109], v[16:17]
	v_pk_mul_f32 v[106:107], v[106:107], v[118:119] op_sel_hi:[1,0]
	v_cvt_pk_bf16_f32 v108, v108, v109
	v_cvt_pk_bf16_f32 v109, v110, v111
	v_pk_mul_f32 v[104:105], v[104:105], v[118:119] op_sel_hi:[1,0]
	global_store_dwordx2 v[116:117], v[108:109], off
	v_pk_mul_f32 v[104:105], v[4:5], v[104:105]
	v_pk_mul_f32 v[106:107], v[6:7], v[106:107]
	v_pk_add_f32 v[108:109], v[46:47], 1.0 op_sel_hi:[1,0]
	v_pk_add_f32 v[110:111], v[44:45], 1.0 op_sel_hi:[1,0]
	v_pk_fma_f32 v[106:107], v[108:109], v[106:107], v[42:43]
	v_pk_fma_f32 v[104:105], v[110:111], v[104:105], v[40:41]
	v_pk_mul_f32 v[102:103], v[102:103], v[118:119] op_sel_hi:[1,0]
	v_cvt_pk_bf16_f32 v104, v104, v105
	v_cvt_pk_bf16_f32 v105, v106, v107
	v_pk_mul_f32 v[100:101], v[100:101], v[118:119] op_sel_hi:[1,0]
	global_store_dwordx2 v[116:117], v[104:105], off offset:512
	v_pk_mul_f32 v[100:101], v[8:9], v[100:101]
	v_pk_mul_f32 v[102:103], v[10:11], v[102:103]
	v_pk_add_f32 v[104:105], v[70:71], 1.0 op_sel_hi:[1,0]
	v_pk_add_f32 v[106:107], v[68:69], 1.0 op_sel_hi:[1,0]
	v_pk_fma_f32 v[102:103], v[104:105], v[102:103], v[66:67]
	v_pk_fma_f32 v[100:101], v[106:107], v[100:101], v[64:65]
	v_pk_mul_f32 v[98:99], v[98:99], v[118:119] op_sel_hi:[1,0]
	v_cvt_pk_bf16_f32 v100, v100, v101
	v_cvt_pk_bf16_f32 v101, v102, v103
	v_pk_mul_f32 v[96:97], v[96:97], v[118:119] op_sel_hi:[1,0]
	global_store_dwordx2 v[116:117], v[100:101], off offset:1024
	v_pk_mul_f32 v[96:97], v[12:13], v[96:97]
	v_pk_mul_f32 v[98:99], v[14:15], v[98:99]
	v_pk_add_f32 v[100:101], v[94:95], 1.0 op_sel_hi:[1,0]
	v_pk_add_f32 v[102:103], v[92:93], 1.0 op_sel_hi:[1,0]
	v_pk_fma_f32 v[98:99], v[100:101], v[98:99], v[90:91]
	v_pk_fma_f32 v[96:97], v[102:103], v[96:97], v[88:89]
	s_nop 0
	v_cvt_pk_bf16_f32 v96, v96, v97
	v_cvt_pk_bf16_f32 v97, v98, v99
	global_store_dwordx2 v[116:117], v[96:97], off offset:1536
	s_or_b64 exec, exec, s[6:7]
	v_cmp_lt_i32_e32 vcc, v166, v176
	s_and_saveexec_b64 s[6:7], vcc
	s_cbranch_execnz .LBB0_124

.LBB0_159:
	s_or_b64 exec, exec, s[8:9]
	s_waitcnt vmcnt(11)
	v_mov_b32_e32 v74, v61
	s_waitcnt vmcnt(10)
	v_mov_b32_e32 v75, v57
	v_mov_b32_e32 v72, v60
	v_mov_b32_e32 v73, v56
	v_pk_mul_f32 v[74:75], v[74:75], v[74:75]
	s_waitcnt vmcnt(9)
	v_mov_b32_e32 v76, v53
	v_pk_fma_f32 v[72:73], v[72:73], v[72:73], v[74:75]
	v_mov_b32_e32 v74, v62
	v_mov_b32_e32 v75, v58
	v_pk_fma_f32 v[72:73], v[74:75], v[74:75], v[72:73]
	v_mov_b32_e32 v74, v63
	v_mov_b32_e32 v75, v59
	s_waitcnt vmcnt(8)
	v_mov_b32_e32 v77, v49
	v_pk_fma_f32 v[72:73], v[74:75], v[74:75], v[72:73]
	v_mov_b32_e32 v74, v52
	v_mov_b32_e32 v75, v48
	v_pk_mul_f32 v[76:77], v[76:77], v[76:77]
	v_add_f32_e32 v72, v72, v73
	v_pk_fma_f32 v[74:75], v[74:75], v[74:75], v[76:77]
	v_mov_b32_e32 v76, v54
	v_mov_b32_e32 v77, v50
	v_pk_fma_f32 v[74:75], v[76:77], v[76:77], v[74:75]
	v_mov_b32_e32 v76, v55
	v_mov_b32_e32 v77, v51
	v_pk_fma_f32 v[74:75], v[76:77], v[76:77], v[74:75]
	v_ashrrev_i32_e32 v165, 31, v164
	v_add_f32_e32 v72, v72, v74
	v_add_f32_e32 v72, v72, v75
	ds_bpermute_b32 v73, v178, v72
	v_lshlrev_b64 v[76:77], 11, v[164:165]
	v_lshl_add_u64 v[76:77], v[148:149], 0, v[76:77]
	s_waitcnt lgkmcnt(0)
	v_add_f32_e32 v72, v72, v73
	ds_bpermute_b32 v73, v179, v72
	s_waitcnt lgkmcnt(0)
	v_add_f32_e32 v72, v72, v73
	s_nop 1
	v_add_f32_dpp v72, v72, v72 row_ror:8 row_mask:0xf bank_mask:0xf
	s_nop 1
	v_add_f32_dpp v72, v72, v72 row_ror:4 row_mask:0xf bank_mask:0xf
	s_nop 1
	v_add_f32_dpp v74, v72, v72 quad_perm:[2,3,0,1] row_mask:0xf bank_mask:0xf
	v_pk_add_f32 v[72:73], v[22:23], 1.0 op_sel_hi:[1,0]
	s_nop 1
	v_add_f32_dpp v74, v74, v74 quad_perm:[1,0,3,2] row_mask:0xf bank_mask:0xf
	v_fmamk_f32 v74, v74, 0x3a800000, v184
	v_rsq_f32_e32 v78, v74
	v_pk_add_f32 v[74:75], v[20:21], 1.0 op_sel_hi:[1,0]
	v_pk_mul_f32 v[62:63], v[62:63], v[78:79] op_sel_hi:[1,0]
	v_pk_mul_f32 v[60:61], v[60:61], v[78:79] op_sel_hi:[1,0]
	v_pk_mul_f32 v[62:63], v[2:3], v[62:63]
	v_pk_mul_f32 v[60:61], v[0:1], v[60:61]
	v_pk_fma_f32 v[62:63], v[72:73], v[62:63], v[18:19]
	v_pk_fma_f32 v[60:61], v[74:75], v[60:61], v[16:17]
	v_pk_mul_f32 v[58:59], v[58:59], v[78:79] op_sel_hi:[1,0]
	v_cvt_pk_bf16_f32 v60, v60, v61
	v_cvt_pk_bf16_f32 v61, v62, v63
	v_pk_mul_f32 v[56:57], v[56:57], v[78:79] op_sel_hi:[1,0]
	global_store_dwordx2 v[76:77], v[60:61], off
	v_pk_mul_f32 v[56:57], v[4:5], v[56:57]
	v_pk_mul_f32 v[58:59], v[6:7], v[58:59]
	v_pk_add_f32 v[60:61], v[46:47], 1.0 op_sel_hi:[1,0]
	v_pk_add_f32 v[62:63], v[44:45], 1.0 op_sel_hi:[1,0]
	v_pk_fma_f32 v[58:59], v[60:61], v[58:59], v[42:43]
	v_pk_fma_f32 v[56:57], v[62:63], v[56:57], v[40:41]
	v_pk_mul_f32 v[54:55], v[54:55], v[78:79] op_sel_hi:[1,0]
	v_cvt_pk_bf16_f32 v56, v56, v57
	v_cvt_pk_bf16_f32 v57, v58, v59
	v_pk_mul_f32 v[52:53], v[52:53], v[78:79] op_sel_hi:[1,0]
	global_store_dwordx2 v[76:77], v[56:57], off offset:512
	v_pk_mul_f32 v[52:53], v[8:9], v[52:53]
	v_pk_mul_f32 v[54:55], v[10:11], v[54:55]
	v_pk_add_f32 v[56:57], v[70:71], 1.0 op_sel_hi:[1,0]
	v_pk_add_f32 v[58:59], v[68:69], 1.0 op_sel_hi:[1,0]
	v_pk_fma_f32 v[54:55], v[56:57], v[54:55], v[66:67]
	v_pk_fma_f32 v[52:53], v[58:59], v[52:53], v[64:65]
	v_pk_mul_f32 v[50:51], v[50:51], v[78:79] op_sel_hi:[1,0]
	v_cvt_pk_bf16_f32 v52, v52, v53
	v_cvt_pk_bf16_f32 v53, v54, v55
	v_pk_mul_f32 v[48:49], v[48:49], v[78:79] op_sel_hi:[1,0]
	global_store_dwordx2 v[76:77], v[52:53], off offset:1024
	v_pk_mul_f32 v[48:49], v[12:13], v[48:49]
	v_pk_mul_f32 v[50:51], v[14:15], v[50:51]
	v_pk_add_f32 v[52:53], v[94:95], 1.0 op_sel_hi:[1,0]
	v_pk_add_f32 v[54:55], v[92:93], 1.0 op_sel_hi:[1,0]
	v_pk_fma_f32 v[50:51], v[52:53], v[50:51], v[90:91]
	v_pk_fma_f32 v[48:49], v[54:55], v[48:49], v[88:89]
	s_nop 0
	v_cvt_pk_bf16_f32 v48, v48, v49
	v_cvt_pk_bf16_f32 v49, v50, v51
	global_store_dwordx2 v[76:77], v[48:49], off offset:1536
	s_or_b64 exec, exec, s[6:7]
	v_cmp_lt_i32_e32 vcc, v162, v176
	s_and_saveexec_b64 s[6:7], vcc
	s_cbranch_execz .LBB0_100

.LBB0_996:
	s_or_b64 exec, exec, s[12:13]
	s_waitcnt vmcnt(27)
	v_lshlrev_b32_e32 v221, 16, v187
	v_lshlrev_b32_e32 v223, 16, v183
	v_and_b32_e32 v220, 0xffff0000, v187
	v_and_b32_e32 v222, 0xffff0000, v183
	s_waitcnt vmcnt(25)
	v_and_b32_e32 v218, 0xffff0000, v191
	v_lshlrev_b32_e32 v3, 16, v191
	v_pk_add_f32 v[220:221], v[220:221], v[222:223]
	v_lshlrev_b32_e32 v222, 16, v190
	v_and_b32_e32 v223, 0xffff0000, v190
	v_lshlrev_b32_e32 v190, 16, v186
	v_and_b32_e32 v191, 0xffff0000, v186
	v_lshlrev_b32_e32 v186, 16, v182
	v_and_b32_e32 v187, 0xffff0000, v182
	v_pk_add_f32 v[182:183], v[186:187], v[190:191]
	v_lshlrev_b32_e32 v190, 16, v189
	v_and_b32_e32 v191, 0xffff0000, v189
	v_lshlrev_b32_e32 v232, 16, v185
	v_and_b32_e32 v233, 0xffff0000, v185
	v_mul_f32_e32 v185, 0xbfb8aa3b, v190
	v_exp_f32_e32 v185, v185
	v_mul_f32_e32 v189, 0xbfb8aa3b, v191
	v_exp_f32_e32 v189, v189
	v_lshlrev_b32_e32 v234, 16, v181
	v_add_f32_e32 v185, 1.0, v185
	v_rcp_f32_e32 v236, v185
	v_add_f32_e32 v185, 1.0, v189
	v_rcp_f32_e32 v237, v185
	v_and_b32_e32 v235, 0xffff0000, v181
	v_and_b32_e32 v189, 0xffff0000, v184
	v_mad_i64_i32 v[24:25], s[12:13], v24, s19, v[202:203]
	v_pk_mul_f32 v[190:191], v[236:237], v[190:191]
	v_lshlrev_b32_e32 v236, 16, v188
	v_and_b32_e32 v237, 0xffff0000, v188
	v_mul_f32_e32 v181, 0xbfb8aa3b, v236
	v_lshlrev_b32_e32 v188, 16, v184
	v_exp_f32_e32 v181, v181
	v_mul_f32_e32 v184, 0xbfb8aa3b, v237
	v_exp_f32_e32 v185, v184
	v_lshlrev_b32_e32 v184, 16, v180
	v_add_f32_e32 v181, 1.0, v181
	v_rcp_f32_e32 v238, v181
	v_add_f32_e32 v181, 1.0, v185
	v_rcp_f32_e32 v239, v181
	v_and_b32_e32 v185, 0xffff0000, v180
	v_pk_add_f32 v[180:181], v[184:185], v[188:189]
	v_lshl_add_u64 v[28:29], v[194:195], 0, v[26:27]
	v_pk_mul_f32 v[188:189], v[238:239], v[236:237]
	s_waitcnt vmcnt(24)
	v_lshlrev_b32_e32 v236, 16, v171
	v_and_b32_e32 v237, 0xffff0000, v171
	v_mul_f32_e32 v171, 0xbfb8aa3b, v236
	v_lshl_add_u64 v[26:27], v[196:197], 0, v[26:27]
	v_lshlrev_b32_e32 v238, 16, v179
	v_and_b32_e32 v239, 0xffff0000, v179
	v_exp_f32_e32 v171, v171
	v_mul_f32_e32 v179, 0xbfb8aa3b, v237
	global_load_dwordx4 v[48:51], v[28:29], off offset:16
	global_load_dwordx4 v[32:35], v[28:29], off
	global_load_dwordx4 v[44:47], v[26:27], off offset:16
	s_nop 0
	global_load_dwordx4 v[28:31], v[26:27], off
	global_load_dwordx4 v[52:55], v[24:25], off offset:16
	s_nop 0
	global_load_dwordx4 v[24:27], v[24:25], off
	v_exp_f32_e32 v179, v179
	v_add_f32_e32 v171, 1.0, v171
	v_rcp_f32_e32 v242, v171
	v_lshlrev_b32_e32 v246, 16, v177
	v_add_f32_e32 v171, 1.0, v179
	v_rcp_f32_e32 v243, v171
	v_and_b32_e32 v247, 0xffff0000, v177
	v_lshlrev_b32_e32 v252, 16, v176
	v_and_b32_e32 v253, 0xffff0000, v176
	v_lshlrev_b32_e32 v176, 16, v172
	v_and_b32_e32 v177, 0xffff0000, v172
	v_lshlrev_b32_e32 v248, 16, v173
	v_and_b32_e32 v249, 0xffff0000, v173
	v_pk_add_f32 v[172:173], v[176:177], v[252:253]
	v_pk_mul_f32 v[236:237], v[242:243], v[236:237]
	v_lshlrev_b32_e32 v242, 16, v170
	v_pk_add_f32 v[246:247], v[248:249], v[246:247]
	v_pk_mul_f32 v[176:177], v[172:173], v[172:173]
	v_and_b32_e32 v243, 0xffff0000, v170
	v_lshlrev_b32_e32 v170, 16, v178
	v_and_b32_e32 v171, 0xffff0000, v178
	v_lshlrev_b32_e32 v178, 16, v174
	v_and_b32_e32 v179, 0xffff0000, v174
	v_mul_f32_e32 v174, 0xbfb8aa3b, v242
	v_pk_mul_f32 v[248:249], v[246:247], v[246:247]
	v_add_f32_e32 v176, v176, v177
	v_pk_add_f32 v[170:171], v[178:179], v[170:171]
	v_exp_f32_e32 v178, v174
	v_mul_f32_e32 v174, 0xbfb8aa3b, v243
	v_add_f32_e32 v176, v248, v176
	v_lshlrev_b32_e32 v240, 16, v175
	v_and_b32_e32 v241, 0xffff0000, v175
	v_exp_f32_e32 v179, v174
	v_pk_mul_f32 v[174:175], v[170:171], v[170:171]
	v_add_f32_e32 v176, v249, v176
	v_pk_add_f32 v[238:239], v[240:241], v[238:239]
	v_add_f32_e32 v174, v174, v176
	v_pk_mul_f32 v[240:241], v[238:239], v[238:239]
	v_add_f32_e32 v174, v175, v174
	v_add_f32_e32 v174, v240, v174
	v_pk_mul_f32 v[184:185], v[180:181], v[180:181]
	v_add_f32_e32 v174, v241, v174
	v_pk_add_f32 v[232:233], v[234:235], v[232:233]
	v_add_f32_e32 v174, v184, v174
	v_pk_mul_f32 v[234:235], v[232:233], v[232:233]
	v_lshlrev_b32_e32 v244, 16, v169
	v_add_f32_e32 v174, v185, v174
	v_and_b32_e32 v245, 0xffff0000, v169
	v_mul_f32_e32 v169, 0xbfb8aa3b, v244
	v_add_f32_e32 v174, v234, v174
	v_pk_mul_f32 v[186:187], v[182:183], v[182:183]
	v_exp_f32_e32 v169, v169
	v_add_f32_e32 v174, v235, v174
	v_add_f32_e32 v174, v186, v174
	v_pk_mul_f32 v[230:231], v[220:221], v[220:221]
	v_add_f32_e32 v174, v187, v174
	v_add_f32_e32 v174, v231, v174
	v_add_f32_e32 v169, 1.0, v169
	v_add_f32_e32 v176, v230, v174
	v_rcp_f32_e32 v250, v169
	v_mul_f32_e32 v169, 0xbfb8aa3b, v245
	ds_bpermute_b32 v177, v227, v176
	v_exp_f32_e32 v169, v169
	v_lshlrev_b32_e32 v174, 16, v168
	v_and_b32_e32 v175, 0xffff0000, v168
	v_add_f32_e32 v178, 1.0, v178
	v_add_f32_e32 v169, 1.0, v169
	s_waitcnt lgkmcnt(0)
	v_add_f32_e32 v168, v176, v177
	v_rcp_f32_e32 v251, v169
	ds_bpermute_b32 v169, v228, v168
	v_mul_f32_e32 v176, 0xbfb8aa3b, v174
	v_exp_f32_e32 v176, v176
	v_mul_f32_e32 v177, 0xbfb8aa3b, v175
	v_exp_f32_e32 v177, v177
	s_waitcnt lgkmcnt(0)
	v_add_f32_e32 v184, v168, v169
	ds_bpermute_b32 v185, v229, v184
	v_add_f32_e32 v168, 1.0, v176
	v_add_f32_e32 v169, 1.0, v177
	v_rcp_f32_e32 v168, v168
	v_rcp_f32_e32 v169, v169
	s_waitcnt lgkmcnt(0)
	v_add_f32_e32 v176, v184, v185
	v_fmamk_f32 v176, v176, 0x3c000000, v226
	v_add_f32_e32 v179, 1.0, v179
	v_pk_mul_f32 v[168:169], v[168:169], v[174:175]
	v_rsq_f32_e32 v184, v176
	v_rcp_f32_e32 v178, v178
	v_rcp_f32_e32 v179, v179
	v_mov_b32_e32 v174, v184
	v_pk_mul_f32 v[172:173], v[172:173], v[174:175] op_sel_hi:[1,0]
	v_pk_mul_f32 v[170:171], v[170:171], v[174:175] op_sel_hi:[1,0]
	v_pk_mul_f32 v[172:173], v[12:13], v[172:173]
	v_pk_mul_f32 v[176:177], v[178:179], v[242:243]
	v_pk_mul_f32 v[168:169], v[168:169], v[172:173]
	v_pk_mul_f32 v[172:173], v[246:247], v[174:175] op_sel_hi:[1,0]
	v_pk_mul_f32 v[178:179], v[250:251], v[244:245]
	v_pk_mul_f32 v[172:173], v[14:15], v[172:173]
	v_pk_mul_f32 v[170:171], v[8:9], v[170:171]
	v_pk_mul_f32 v[172:173], v[178:179], v[172:173]
	v_pk_mul_f32 v[170:171], v[176:177], v[170:171]
	v_pk_mul_f32 v[176:177], v[238:239], v[174:175] op_sel_hi:[1,0]
	v_pk_mul_f32 v[178:179], v[180:181], v[174:175] op_sel_hi:[1,0]
	v_pk_mul_f32 v[180:181], v[232:233], v[174:175] op_sel_hi:[1,0]
	v_mul_f32_e32 v175, 0xbfb8aa3b, v222
	v_exp_f32_e32 v175, v175
	v_mul_f32_e32 v184, 0xbfb8aa3b, v223
	v_exp_f32_e32 v185, v184
	v_mul_f32_e32 v219, v220, v174
	v_add_f32_e32 v175, 1.0, v175
	v_rcp_f32_e32 v184, v175
	v_add_f32_e32 v175, 1.0, v185
	v_rcp_f32_e32 v185, v175
	v_pk_mul_f32 v[182:183], v[182:183], v[174:175] op_sel_hi:[1,0]
	v_mul_f32_e32 v175, 0xbfb8aa3b, v3
	v_pk_mul_f32 v[182:183], v[0:1], v[182:183]
	v_pk_mul_f32 v[184:185], v[184:185], v[222:223]
	v_exp_f32_e32 v175, v175
	v_pk_mul_f32 v[182:183], v[184:185], v[182:183]
	v_mul_f32_e32 v184, 0xbfb8aa3b, v218
	v_exp_f32_e32 v184, v184
	v_add_f32_e32 v175, 1.0, v175
	v_rcp_f32_e32 v175, v175
	v_pk_mul_f32 v[176:177], v[10:11], v[176:177]
	v_add_f32_e32 v184, 1.0, v184
	v_rcp_f32_e32 v204, v184
	v_mul_f32_e32 v185, v221, v174
	v_mul_f32_e32 v186, v175, v3
	v_pk_mul_f32 v[176:177], v[236:237], v[176:177]
	v_pk_mul_f32 v[174:175], v[204:205], v[218:219]
	v_pk_mul_f32 v[178:179], v[4:5], v[178:179]
	v_pk_mul_f32 v[180:181], v[6:7], v[180:181]
	v_mul_f32_e32 v184, v2, v185
	v_mov_b32_e32 v187, v174
	v_mov_b32_e32 v185, v175
	v_pk_mul_f32 v[178:179], v[188:189], v[178:179]
	v_pk_mul_f32 v[180:181], v[190:191], v[180:181]
	v_cvt_pk_bf16_f32 v168, v168, v169
	v_cvt_pk_bf16_f32 v169, v172, v173
	v_cvt_pk_bf16_f32 v170, v170, v171
	v_cvt_pk_bf16_f32 v171, v176, v177
	v_lshl_add_u64 v[172:173], v[192:193], 0, v[216:217]
	v_pk_mul_f32 v[174:175], v[186:187], v[184:185]
	global_store_dwordx4 v[172:173], v[168:171], off
	v_cmp_gt_i32_e32 vcc, s3, v214
	s_nop 0
	v_cvt_pk_bf16_f32 v168, v178, v179
	v_cvt_pk_bf16_f32 v169, v180, v181
	v_cvt_pk_bf16_f32 v170, v182, v183
	v_cvt_pk_bf16_f32 v171, v174, v175
	global_store_dwordx4 v[172:173], v[168:171], off offset:16
	s_and_saveexec_b64 s[12:13], vcc
	s_cbranch_execz .LBB0_998
	s_waitcnt vmcnt(29)
	v_lshlrev_b32_e32 v171, 16, v163
	v_lshlrev_b32_e32 v173, 16, v159
	v_and_b32_e32 v170, 0xffff0000, v163
	v_and_b32_e32 v172, 0xffff0000, v159
	s_waitcnt vmcnt(27)
	v_and_b32_e32 v168, 0xffff0000, v167
	v_lshlrev_b32_e32 v3, 16, v167
	v_pk_add_f32 v[170:171], v[170:171], v[172:173]
	v_lshlrev_b32_e32 v172, 16, v166
	v_and_b32_e32 v173, 0xffff0000, v166
	v_lshlrev_b32_e32 v166, 16, v162
	v_and_b32_e32 v167, 0xffff0000, v162
	v_lshlrev_b32_e32 v162, 16, v158
	v_and_b32_e32 v163, 0xffff0000, v158
	v_pk_add_f32 v[158:159], v[162:163], v[166:167]
	v_lshlrev_b32_e32 v166, 16, v165
	v_and_b32_e32 v167, 0xffff0000, v165
	v_lshlrev_b32_e32 v176, 16, v161
	v_and_b32_e32 v177, 0xffff0000, v161
	v_mul_f32_e32 v161, 0xbfb8aa3b, v166
	v_exp_f32_e32 v161, v161
	v_mul_f32_e32 v165, 0xbfb8aa3b, v167
	v_exp_f32_e32 v165, v165
	v_lshlrev_b32_e32 v178, 16, v157
	v_add_f32_e32 v161, 1.0, v161
	v_rcp_f32_e32 v180, v161
	v_add_f32_e32 v161, 1.0, v165
	v_rcp_f32_e32 v181, v161
	v_and_b32_e32 v179, 0xffff0000, v157
	v_and_b32_e32 v165, 0xffff0000, v160
	v_lshlrev_b32_e32 v190, 16, v153
	v_pk_mul_f32 v[166:167], v[180:181], v[166:167]
	v_lshlrev_b32_e32 v180, 16, v164
	v_and_b32_e32 v181, 0xffff0000, v164
	v_mul_f32_e32 v157, 0xbfb8aa3b, v180
	v_lshlrev_b32_e32 v164, 16, v160
	v_exp_f32_e32 v157, v157
	v_mul_f32_e32 v160, 0xbfb8aa3b, v181
	v_exp_f32_e32 v161, v160
	v_lshlrev_b32_e32 v160, 16, v156
	v_add_f32_e32 v157, 1.0, v157
	v_rcp_f32_e32 v182, v157
	v_add_f32_e32 v157, 1.0, v161
	v_rcp_f32_e32 v183, v157
	v_and_b32_e32 v161, 0xffff0000, v156
	v_pk_add_f32 v[156:157], v[160:161], v[164:165]
	v_and_b32_e32 v191, 0xffff0000, v153
	v_pk_mul_f32 v[164:165], v[182:183], v[180:181]
	s_waitcnt vmcnt(26)
	v_lshlrev_b32_e32 v180, 16, v147
	v_and_b32_e32 v181, 0xffff0000, v147
	v_mul_f32_e32 v147, 0xbfb8aa3b, v180
	v_lshlrev_b32_e32 v182, 16, v155
	v_and_b32_e32 v183, 0xffff0000, v155
	v_exp_f32_e32 v147, v147
	v_mul_f32_e32 v155, 0xbfb8aa3b, v181
	v_exp_f32_e32 v155, v155
	v_lshlrev_b32_e32 v220, 16, v152
	v_add_f32_e32 v147, 1.0, v147
	v_rcp_f32_e32 v186, v147
	v_add_f32_e32 v147, 1.0, v155
	v_rcp_f32_e32 v187, v147
	v_and_b32_e32 v221, 0xffff0000, v152
	v_lshlrev_b32_e32 v152, 16, v148
	v_and_b32_e32 v153, 0xffff0000, v148
	v_lshlrev_b32_e32 v216, 16, v149
	v_and_b32_e32 v217, 0xffff0000, v149
	v_pk_add_f32 v[148:149], v[152:153], v[220:221]
	v_pk_mul_f32 v[180:181], v[186:187], v[180:181]
	v_lshlrev_b32_e32 v186, 16, v146
	v_pk_add_f32 v[190:191], v[216:217], v[190:191]
	v_pk_mul_f32 v[152:153], v[148:149], v[148:149]
	v_and_b32_e32 v187, 0xffff0000, v146
	v_lshlrev_b32_e32 v146, 16, v154
	v_and_b32_e32 v147, 0xffff0000, v154
	v_lshlrev_b32_e32 v154, 16, v150
	v_and_b32_e32 v155, 0xffff0000, v150
	v_mul_f32_e32 v150, 0xbfb8aa3b, v186
	v_pk_mul_f32 v[216:217], v[190:191], v[190:191]
	v_add_f32_e32 v152, v152, v153
	v_pk_add_f32 v[146:147], v[154:155], v[146:147]
	v_exp_f32_e32 v154, v150
	v_mul_f32_e32 v150, 0xbfb8aa3b, v187
	v_add_f32_e32 v152, v216, v152
	v_lshlrev_b32_e32 v184, 16, v151
	v_and_b32_e32 v185, 0xffff0000, v151
	v_exp_f32_e32 v155, v150
	v_pk_mul_f32 v[150:151], v[146:147], v[146:147]
	v_add_f32_e32 v152, v217, v152
	v_pk_add_f32 v[182:183], v[184:185], v[182:183]
	v_add_f32_e32 v150, v150, v152
	v_pk_mul_f32 v[184:185], v[182:183], v[182:183]
	v_add_f32_e32 v150, v151, v150
	v_add_f32_e32 v150, v184, v150
	v_pk_mul_f32 v[160:161], v[156:157], v[156:157]
	v_add_f32_e32 v150, v185, v150
	v_pk_add_f32 v[176:177], v[178:179], v[176:177]
	v_add_f32_e32 v150, v160, v150
	v_pk_mul_f32 v[178:179], v[176:177], v[176:177]
	v_lshlrev_b32_e32 v188, 16, v145
	v_add_f32_e32 v150, v161, v150
	v_and_b32_e32 v189, 0xffff0000, v145
	v_mul_f32_e32 v145, 0xbfb8aa3b, v188
	v_add_f32_e32 v150, v178, v150
	v_pk_mul_f32 v[162:163], v[158:159], v[158:159]
	v_exp_f32_e32 v145, v145
	v_add_f32_e32 v150, v179, v150
	v_add_f32_e32 v150, v162, v150
	v_pk_mul_f32 v[174:175], v[170:171], v[170:171]
	v_add_f32_e32 v150, v163, v150
	v_add_f32_e32 v150, v175, v150
	v_add_f32_e32 v145, 1.0, v145
	v_add_f32_e32 v152, v174, v150
	v_rcp_f32_e32 v218, v145
	v_mul_f32_e32 v145, 0xbfb8aa3b, v189
	ds_bpermute_b32 v153, v227, v152
	v_exp_f32_e32 v145, v145
	v_lshlrev_b32_e32 v150, 16, v144
	v_and_b32_e32 v151, 0xffff0000, v144
	v_add_f32_e32 v154, 1.0, v154
	v_add_f32_e32 v145, 1.0, v145
	s_waitcnt lgkmcnt(0)
	v_add_f32_e32 v144, v152, v153
	v_rcp_f32_e32 v219, v145
	ds_bpermute_b32 v145, v228, v144
	v_mul_f32_e32 v152, 0xbfb8aa3b, v150
	v_exp_f32_e32 v152, v152
	v_mul_f32_e32 v153, 0xbfb8aa3b, v151
	v_exp_f32_e32 v153, v153
	s_waitcnt lgkmcnt(0)
	v_add_f32_e32 v160, v144, v145
	ds_bpermute_b32 v161, v229, v160
	v_add_f32_e32 v144, 1.0, v152
	v_add_f32_e32 v145, 1.0, v153
	v_rcp_f32_e32 v144, v144
	v_rcp_f32_e32 v145, v145
	s_waitcnt lgkmcnt(0)
	v_add_f32_e32 v152, v160, v161
	v_fmamk_f32 v152, v152, 0x3c000000, v226
	v_add_f32_e32 v155, 1.0, v155
	v_pk_mul_f32 v[144:145], v[144:145], v[150:151]
	v_rsq_f32_e32 v160, v152
	v_rcp_f32_e32 v154, v154
	v_rcp_f32_e32 v155, v155
	v_ashrrev_i32_e32 v215, 31, v214
	v_mov_b32_e32 v150, v160
	v_pk_mul_f32 v[148:149], v[148:149], v[150:151] op_sel_hi:[1,0]
	v_pk_mul_f32 v[146:147], v[146:147], v[150:151] op_sel_hi:[1,0]
	v_pk_mul_f32 v[148:149], v[12:13], v[148:149]
	v_pk_mul_f32 v[152:153], v[154:155], v[186:187]
	v_pk_mul_f32 v[144:145], v[144:145], v[148:149]
	v_pk_mul_f32 v[148:149], v[190:191], v[150:151] op_sel_hi:[1,0]
	v_pk_mul_f32 v[154:155], v[218:219], v[188:189]
	v_pk_mul_f32 v[148:149], v[14:15], v[148:149]
	v_pk_mul_f32 v[146:147], v[8:9], v[146:147]
	v_pk_mul_f32 v[148:149], v[154:155], v[148:149]
	v_pk_mul_f32 v[146:147], v[152:153], v[146:147]
	v_pk_mul_f32 v[152:153], v[182:183], v[150:151] op_sel_hi:[1,0]
	v_pk_mul_f32 v[154:155], v[156:157], v[150:151] op_sel_hi:[1,0]
	v_pk_mul_f32 v[156:157], v[176:177], v[150:151] op_sel_hi:[1,0]
	v_mul_f32_e32 v151, 0xbfb8aa3b, v172
	v_exp_f32_e32 v151, v151
	v_mul_f32_e32 v160, 0xbfb8aa3b, v173
	v_exp_f32_e32 v161, v160
	v_mul_f32_e32 v169, v170, v150
	v_add_f32_e32 v151, 1.0, v151
	v_rcp_f32_e32 v160, v151
	v_add_f32_e32 v151, 1.0, v161
	v_rcp_f32_e32 v161, v151
	v_pk_mul_f32 v[158:159], v[158:159], v[150:151] op_sel_hi:[1,0]
	v_mul_f32_e32 v151, 0xbfb8aa3b, v3
	v_pk_mul_f32 v[158:159], v[0:1], v[158:159]
	v_pk_mul_f32 v[160:161], v[160:161], v[172:173]
	v_exp_f32_e32 v151, v151
	v_pk_mul_f32 v[158:159], v[160:161], v[158:159]
	v_mul_f32_e32 v160, 0xbfb8aa3b, v168
	v_exp_f32_e32 v160, v160
	v_add_f32_e32 v151, 1.0, v151
	v_rcp_f32_e32 v151, v151
	v_pk_mul_f32 v[152:153], v[10:11], v[152:153]
	v_add_f32_e32 v160, 1.0, v160
	v_rcp_f32_e32 v204, v160
	v_mul_f32_e32 v161, v171, v150
	v_mul_f32_e32 v162, v151, v3
	v_pk_mul_f32 v[152:153], v[180:181], v[152:153]
	v_pk_mul_f32 v[150:151], v[204:205], v[168:169]
	v_pk_mul_f32 v[154:155], v[4:5], v[154:155]
	v_pk_mul_f32 v[156:157], v[6:7], v[156:157]
	v_mul_f32_e32 v160, v2, v161
	v_mov_b32_e32 v163, v150
	v_mov_b32_e32 v161, v151
	v_cvt_pk_bf16_f32 v144, v144, v145
	v_cvt_pk_bf16_f32 v145, v148, v149
	v_lshlrev_b64 v[148:149], 11, v[214:215]
	v_pk_mul_f32 v[154:155], v[164:165], v[154:155]
	v_pk_mul_f32 v[156:157], v[166:167], v[156:157]
	v_cvt_pk_bf16_f32 v146, v146, v147
	v_cvt_pk_bf16_f32 v147, v152, v153
	v_lshl_add_u64 v[148:149], v[192:193], 0, v[148:149]
	v_pk_mul_f32 v[150:151], v[162:163], v[160:161]
	global_store_dwordx4 v[148:149], v[144:147], off
	s_nop 1
	v_cvt_pk_bf16_f32 v144, v154, v155
	v_cvt_pk_bf16_f32 v145, v156, v157
	v_cvt_pk_bf16_f32 v146, v158, v159
	v_cvt_pk_bf16_f32 v147, v150, v151
	global_store_dwordx4 v[148:149], v[144:147], off offset:16
.LBB0_998:
	s_or_b64 exec, exec, s[12:13]
	v_add_u32_e32 v3, s33, v214
	v_cmp_gt_i32_e32 vcc, s3, v3
	s_and_saveexec_b64 s[12:13], vcc
	s_cbranch_execz .LBB0_1000
	s_waitcnt vmcnt(23)
	v_lshlrev_b32_e32 v147, 16, v139
	v_lshlrev_b32_e32 v149, 16, v135
	v_and_b32_e32 v146, 0xffff0000, v139
	v_and_b32_e32 v148, 0xffff0000, v135
	s_waitcnt vmcnt(21)
	v_and_b32_e32 v144, 0xffff0000, v143
	v_lshlrev_b32_e32 v145, 16, v143
	v_pk_add_f32 v[146:147], v[146:147], v[148:149]
	v_lshlrev_b32_e32 v148, 16, v142
	v_and_b32_e32 v149, 0xffff0000, v142
	v_lshlrev_b32_e32 v142, 16, v138
	v_and_b32_e32 v143, 0xffff0000, v138
	v_lshlrev_b32_e32 v138, 16, v134
	v_and_b32_e32 v139, 0xffff0000, v134
	v_pk_add_f32 v[134:135], v[138:139], v[142:143]
	v_lshlrev_b32_e32 v142, 16, v141
	v_and_b32_e32 v143, 0xffff0000, v141
	v_lshlrev_b32_e32 v152, 16, v137
	v_and_b32_e32 v153, 0xffff0000, v137
	v_mul_f32_e32 v137, 0xbfb8aa3b, v142
	v_exp_f32_e32 v137, v137
	v_mul_f32_e32 v141, 0xbfb8aa3b, v143
	v_exp_f32_e32 v141, v141
	v_lshlrev_b32_e32 v154, 16, v133
	v_add_f32_e32 v137, 1.0, v137
	v_rcp_f32_e32 v156, v137
	v_add_f32_e32 v137, 1.0, v141
	v_rcp_f32_e32 v157, v137
	v_and_b32_e32 v155, 0xffff0000, v133
	v_and_b32_e32 v141, 0xffff0000, v136
	v_lshlrev_b32_e32 v166, 16, v129
	v_pk_mul_f32 v[142:143], v[156:157], v[142:143]
	v_lshlrev_b32_e32 v156, 16, v140
	v_and_b32_e32 v157, 0xffff0000, v140
	v_mul_f32_e32 v133, 0xbfb8aa3b, v156
	v_lshlrev_b32_e32 v140, 16, v136
	v_exp_f32_e32 v133, v133
	v_mul_f32_e32 v136, 0xbfb8aa3b, v157
	v_exp_f32_e32 v137, v136
	v_lshlrev_b32_e32 v136, 16, v132
	v_add_f32_e32 v133, 1.0, v133
	v_rcp_f32_e32 v158, v133
	v_add_f32_e32 v133, 1.0, v137
	v_rcp_f32_e32 v159, v133
	v_and_b32_e32 v137, 0xffff0000, v132
	v_pk_add_f32 v[132:133], v[136:137], v[140:141]
	v_and_b32_e32 v167, 0xffff0000, v129
	v_pk_mul_f32 v[140:141], v[158:159], v[156:157]
	s_waitcnt vmcnt(20)
	v_lshlrev_b32_e32 v156, 16, v123
	v_and_b32_e32 v157, 0xffff0000, v123
	v_mul_f32_e32 v123, 0xbfb8aa3b, v156
	v_lshlrev_b32_e32 v158, 16, v131
	v_and_b32_e32 v159, 0xffff0000, v131
	v_exp_f32_e32 v123, v123
	v_mul_f32_e32 v131, 0xbfb8aa3b, v157
	v_exp_f32_e32 v131, v131
	v_lshlrev_b32_e32 v172, 16, v128
	v_add_f32_e32 v123, 1.0, v123
	v_rcp_f32_e32 v162, v123
	v_add_f32_e32 v123, 1.0, v131
	v_rcp_f32_e32 v163, v123
	v_and_b32_e32 v173, 0xffff0000, v128
	v_lshlrev_b32_e32 v128, 16, v124
	v_and_b32_e32 v129, 0xffff0000, v124
	v_lshlrev_b32_e32 v168, 16, v125
	v_and_b32_e32 v169, 0xffff0000, v125
	v_pk_add_f32 v[124:125], v[128:129], v[172:173]
	v_pk_mul_f32 v[156:157], v[162:163], v[156:157]
	v_lshlrev_b32_e32 v162, 16, v122
	v_pk_add_f32 v[166:167], v[168:169], v[166:167]
	v_pk_mul_f32 v[128:129], v[124:125], v[124:125]
	v_and_b32_e32 v163, 0xffff0000, v122
	v_lshlrev_b32_e32 v122, 16, v130
	v_and_b32_e32 v123, 0xffff0000, v130
	v_lshlrev_b32_e32 v130, 16, v126
	v_and_b32_e32 v131, 0xffff0000, v126
	v_mul_f32_e32 v126, 0xbfb8aa3b, v162
	v_pk_mul_f32 v[168:169], v[166:167], v[166:167]
	v_add_f32_e32 v128, v128, v129
	v_pk_add_f32 v[122:123], v[130:131], v[122:123]
	v_exp_f32_e32 v130, v126
	v_mul_f32_e32 v126, 0xbfb8aa3b, v163
	v_add_f32_e32 v128, v168, v128
	v_lshlrev_b32_e32 v160, 16, v127
	v_and_b32_e32 v161, 0xffff0000, v127
	v_exp_f32_e32 v131, v126
	v_pk_mul_f32 v[126:127], v[122:123], v[122:123]
	v_add_f32_e32 v128, v169, v128
	v_pk_add_f32 v[158:159], v[160:161], v[158:159]
	v_add_f32_e32 v126, v126, v128
	v_pk_mul_f32 v[160:161], v[158:159], v[158:159]
	v_add_f32_e32 v126, v127, v126
	v_add_f32_e32 v126, v160, v126
	v_pk_mul_f32 v[136:137], v[132:133], v[132:133]
	v_add_f32_e32 v126, v161, v126
	v_pk_add_f32 v[152:153], v[154:155], v[152:153]
	v_add_f32_e32 v126, v136, v126
	v_pk_mul_f32 v[154:155], v[152:153], v[152:153]
	v_lshlrev_b32_e32 v164, 16, v121
	v_add_f32_e32 v126, v137, v126
	v_and_b32_e32 v165, 0xffff0000, v121
	v_mul_f32_e32 v121, 0xbfb8aa3b, v164
	v_add_f32_e32 v126, v154, v126
	v_pk_mul_f32 v[138:139], v[134:135], v[134:135]
	v_exp_f32_e32 v121, v121
	v_add_f32_e32 v126, v155, v126
	v_add_f32_e32 v126, v138, v126
	v_pk_mul_f32 v[150:151], v[146:147], v[146:147]
	v_add_f32_e32 v126, v139, v126
	v_add_f32_e32 v126, v151, v126
	v_add_f32_e32 v121, 1.0, v121
	v_add_f32_e32 v128, v150, v126
	v_rcp_f32_e32 v170, v121
	v_mul_f32_e32 v121, 0xbfb8aa3b, v165
	ds_bpermute_b32 v129, v227, v128
	v_exp_f32_e32 v121, v121
	v_lshlrev_b32_e32 v126, 16, v120
	v_and_b32_e32 v127, 0xffff0000, v120
	v_add_f32_e32 v130, 1.0, v130
	v_add_f32_e32 v121, 1.0, v121
	s_waitcnt lgkmcnt(0)
	v_add_f32_e32 v120, v128, v129
	v_rcp_f32_e32 v171, v121
	ds_bpermute_b32 v121, v228, v120
	v_mul_f32_e32 v128, 0xbfb8aa3b, v126
	v_exp_f32_e32 v128, v128
	v_mul_f32_e32 v129, 0xbfb8aa3b, v127
	v_exp_f32_e32 v129, v129
	s_waitcnt lgkmcnt(0)
	v_add_f32_e32 v136, v120, v121
	ds_bpermute_b32 v137, v229, v136
	v_add_f32_e32 v120, 1.0, v128
	v_add_f32_e32 v121, 1.0, v129
	v_rcp_f32_e32 v120, v120
	v_rcp_f32_e32 v121, v121
	s_waitcnt lgkmcnt(0)
	v_add_f32_e32 v128, v136, v137
	v_fmamk_f32 v128, v128, 0x3c000000, v226
	v_add_f32_e32 v131, 1.0, v131
	v_pk_mul_f32 v[120:121], v[120:121], v[126:127]
	v_rsq_f32_e32 v136, v128
	v_rcp_f32_e32 v130, v130
	v_rcp_f32_e32 v131, v131
	v_ashrrev_i32_e32 v213, 31, v212
	v_mov_b32_e32 v126, v136
	v_pk_mul_f32 v[124:125], v[124:125], v[126:127] op_sel_hi:[1,0]
	v_pk_mul_f32 v[122:123], v[122:123], v[126:127] op_sel_hi:[1,0]
	v_pk_mul_f32 v[124:125], v[12:13], v[124:125]
	v_pk_mul_f32 v[128:129], v[130:131], v[162:163]
	v_pk_mul_f32 v[120:121], v[120:121], v[124:125]
	v_pk_mul_f32 v[124:125], v[166:167], v[126:127] op_sel_hi:[1,0]
	v_pk_mul_f32 v[130:131], v[170:171], v[164:165]
	v_pk_mul_f32 v[124:125], v[14:15], v[124:125]
	v_pk_mul_f32 v[122:123], v[8:9], v[122:123]
	v_pk_mul_f32 v[124:125], v[130:131], v[124:125]
	v_pk_mul_f32 v[122:123], v[128:129], v[122:123]
	v_pk_mul_f32 v[128:129], v[158:159], v[126:127] op_sel_hi:[1,0]
	v_pk_mul_f32 v[130:131], v[132:133], v[126:127] op_sel_hi:[1,0]
	v_pk_mul_f32 v[132:133], v[152:153], v[126:127] op_sel_hi:[1,0]
	v_mul_f32_e32 v127, 0xbfb8aa3b, v148
	v_exp_f32_e32 v127, v127
	v_mul_f32_e32 v136, 0xbfb8aa3b, v149
	v_exp_f32_e32 v137, v136
	v_pk_mul_f32 v[128:129], v[10:11], v[128:129]
	v_add_f32_e32 v127, 1.0, v127
	v_rcp_f32_e32 v136, v127
	v_add_f32_e32 v127, 1.0, v137
	v_rcp_f32_e32 v137, v127
	v_pk_mul_f32 v[134:135], v[134:135], v[126:127] op_sel_hi:[1,0]
	v_mul_f32_e32 v127, 0xbfb8aa3b, v145
	v_pk_mul_f32 v[134:135], v[0:1], v[134:135]
	v_pk_mul_f32 v[136:137], v[136:137], v[148:149]
	v_exp_f32_e32 v127, v127
	v_pk_mul_f32 v[134:135], v[136:137], v[134:135]
	v_mul_f32_e32 v136, 0xbfb8aa3b, v144
	v_exp_f32_e32 v136, v136
	v_add_f32_e32 v127, 1.0, v127
	v_rcp_f32_e32 v127, v127
	v_mul_f32_e32 v137, v147, v126
	v_add_f32_e32 v136, 1.0, v136
	v_rcp_f32_e32 v204, v136
	v_mul_f32_e32 v138, v127, v145
	v_mul_f32_e32 v145, v146, v126
	v_pk_mul_f32 v[128:129], v[156:157], v[128:129]
	v_pk_mul_f32 v[126:127], v[204:205], v[144:145]
	v_pk_mul_f32 v[130:131], v[4:5], v[130:131]
	v_pk_mul_f32 v[132:133], v[6:7], v[132:133]
	v_mul_f32_e32 v136, v2, v137
	v_mov_b32_e32 v139, v126
	v_mov_b32_e32 v137, v127
	v_cvt_pk_bf16_f32 v120, v120, v121
	v_cvt_pk_bf16_f32 v121, v124, v125
	v_lshlrev_b64 v[124:125], 11, v[212:213]
	v_pk_mul_f32 v[130:131], v[140:141], v[130:131]
	v_pk_mul_f32 v[132:133], v[142:143], v[132:133]
	v_cvt_pk_bf16_f32 v122, v122, v123
	v_cvt_pk_bf16_f32 v123, v128, v129
	v_lshl_add_u64 v[124:125], v[192:193], 0, v[124:125]
	v_pk_mul_f32 v[126:127], v[138:139], v[136:137]
	global_store_dwordx4 v[124:125], v[120:123], off
	s_nop 1
	v_cvt_pk_bf16_f32 v120, v130, v131
	v_cvt_pk_bf16_f32 v121, v132, v133
	v_cvt_pk_bf16_f32 v122, v134, v135
	v_cvt_pk_bf16_f32 v123, v126, v127
	global_store_dwordx4 v[124:125], v[120:123], off offset:16
.LBB0_1000:
	s_or_b64 exec, exec, s[12:13]
	v_add_u32_e32 v3, s33, v3
	v_cmp_gt_i32_e32 vcc, s3, v3
	s_and_saveexec_b64 s[12:13], vcc
	s_cbranch_execz .LBB0_1002
	s_waitcnt vmcnt(17)
	v_lshlrev_b32_e32 v123, 16, v115
	v_lshlrev_b32_e32 v125, 16, v111
	v_and_b32_e32 v122, 0xffff0000, v115
	v_and_b32_e32 v124, 0xffff0000, v111
	s_waitcnt vmcnt(15)
	v_and_b32_e32 v120, 0xffff0000, v119
	v_lshlrev_b32_e32 v121, 16, v119
	v_pk_add_f32 v[122:123], v[122:123], v[124:125]
	v_lshlrev_b32_e32 v124, 16, v118
	v_and_b32_e32 v125, 0xffff0000, v118
	v_lshlrev_b32_e32 v118, 16, v114
	v_and_b32_e32 v119, 0xffff0000, v114
	v_lshlrev_b32_e32 v114, 16, v110
	v_and_b32_e32 v115, 0xffff0000, v110
	v_pk_add_f32 v[110:111], v[114:115], v[118:119]
	v_lshlrev_b32_e32 v118, 16, v117
	v_and_b32_e32 v119, 0xffff0000, v117
	v_lshlrev_b32_e32 v128, 16, v113
	v_and_b32_e32 v129, 0xffff0000, v113
	v_mul_f32_e32 v113, 0xbfb8aa3b, v118
	v_exp_f32_e32 v113, v113
	v_mul_f32_e32 v117, 0xbfb8aa3b, v119
	v_exp_f32_e32 v117, v117
	v_lshlrev_b32_e32 v130, 16, v109
	v_add_f32_e32 v113, 1.0, v113
	v_rcp_f32_e32 v132, v113
	v_add_f32_e32 v113, 1.0, v117
	v_rcp_f32_e32 v133, v113
	v_and_b32_e32 v131, 0xffff0000, v109
	v_and_b32_e32 v117, 0xffff0000, v112
	v_lshlrev_b32_e32 v142, 16, v105
	v_pk_mul_f32 v[118:119], v[132:133], v[118:119]
	v_lshlrev_b32_e32 v132, 16, v116
	v_and_b32_e32 v133, 0xffff0000, v116
	v_mul_f32_e32 v109, 0xbfb8aa3b, v132
	v_lshlrev_b32_e32 v116, 16, v112
	v_exp_f32_e32 v109, v109
	v_mul_f32_e32 v112, 0xbfb8aa3b, v133
	v_exp_f32_e32 v113, v112
	v_lshlrev_b32_e32 v112, 16, v108
	v_add_f32_e32 v109, 1.0, v109
	v_rcp_f32_e32 v134, v109
	v_add_f32_e32 v109, 1.0, v113
	v_rcp_f32_e32 v135, v109
	v_and_b32_e32 v113, 0xffff0000, v108
	v_pk_add_f32 v[108:109], v[112:113], v[116:117]
	v_and_b32_e32 v143, 0xffff0000, v105
	v_pk_mul_f32 v[116:117], v[134:135], v[132:133]
	s_waitcnt vmcnt(14)
	v_lshlrev_b32_e32 v132, 16, v99
	v_and_b32_e32 v133, 0xffff0000, v99
	v_mul_f32_e32 v99, 0xbfb8aa3b, v132
	v_lshlrev_b32_e32 v134, 16, v107
	v_and_b32_e32 v135, 0xffff0000, v107
	v_exp_f32_e32 v99, v99
	v_mul_f32_e32 v107, 0xbfb8aa3b, v133
	v_exp_f32_e32 v107, v107
	v_lshlrev_b32_e32 v148, 16, v104
	v_add_f32_e32 v99, 1.0, v99
	v_rcp_f32_e32 v138, v99
	v_add_f32_e32 v99, 1.0, v107
	v_rcp_f32_e32 v139, v99
	v_and_b32_e32 v149, 0xffff0000, v104
	v_lshlrev_b32_e32 v104, 16, v100
	v_and_b32_e32 v105, 0xffff0000, v100
	v_lshlrev_b32_e32 v144, 16, v101
	v_and_b32_e32 v145, 0xffff0000, v101
	v_pk_add_f32 v[100:101], v[104:105], v[148:149]
	v_pk_mul_f32 v[132:133], v[138:139], v[132:133]
	v_lshlrev_b32_e32 v138, 16, v98
	v_pk_add_f32 v[142:143], v[144:145], v[142:143]
	v_pk_mul_f32 v[104:105], v[100:101], v[100:101]
	v_and_b32_e32 v139, 0xffff0000, v98
	v_lshlrev_b32_e32 v98, 16, v106
	v_and_b32_e32 v99, 0xffff0000, v106
	v_lshlrev_b32_e32 v106, 16, v102
	v_and_b32_e32 v107, 0xffff0000, v102
	v_mul_f32_e32 v102, 0xbfb8aa3b, v138
	v_pk_mul_f32 v[144:145], v[142:143], v[142:143]
	v_add_f32_e32 v104, v104, v105
	v_pk_add_f32 v[98:99], v[106:107], v[98:99]
	v_exp_f32_e32 v106, v102
	v_mul_f32_e32 v102, 0xbfb8aa3b, v139
	v_add_f32_e32 v104, v144, v104
	v_lshlrev_b32_e32 v136, 16, v103
	v_and_b32_e32 v137, 0xffff0000, v103
	v_exp_f32_e32 v107, v102
	v_pk_mul_f32 v[102:103], v[98:99], v[98:99]
	v_add_f32_e32 v104, v145, v104
	v_pk_add_f32 v[134:135], v[136:137], v[134:135]
	v_add_f32_e32 v102, v102, v104
	v_pk_mul_f32 v[136:137], v[134:135], v[134:135]
	v_add_f32_e32 v102, v103, v102
	v_add_f32_e32 v102, v136, v102
	v_pk_mul_f32 v[112:113], v[108:109], v[108:109]
	v_add_f32_e32 v102, v137, v102
	v_pk_add_f32 v[128:129], v[130:131], v[128:129]
	v_add_f32_e32 v102, v112, v102
	v_pk_mul_f32 v[130:131], v[128:129], v[128:129]
	v_lshlrev_b32_e32 v140, 16, v97
	v_add_f32_e32 v102, v113, v102
	v_and_b32_e32 v141, 0xffff0000, v97
	v_mul_f32_e32 v97, 0xbfb8aa3b, v140
	v_add_f32_e32 v102, v130, v102
	v_pk_mul_f32 v[114:115], v[110:111], v[110:111]
	v_exp_f32_e32 v97, v97
	v_add_f32_e32 v102, v131, v102
	v_add_f32_e32 v102, v114, v102
	v_pk_mul_f32 v[126:127], v[122:123], v[122:123]
	v_add_f32_e32 v102, v115, v102
	v_add_f32_e32 v102, v127, v102
	v_add_f32_e32 v97, 1.0, v97
	v_add_f32_e32 v104, v126, v102
	v_rcp_f32_e32 v146, v97
	v_mul_f32_e32 v97, 0xbfb8aa3b, v141
	ds_bpermute_b32 v105, v227, v104
	v_exp_f32_e32 v97, v97
	v_lshlrev_b32_e32 v102, 16, v96
	v_and_b32_e32 v103, 0xffff0000, v96
	v_add_f32_e32 v106, 1.0, v106
	v_add_f32_e32 v97, 1.0, v97
	s_waitcnt lgkmcnt(0)
	v_add_f32_e32 v96, v104, v105
	v_rcp_f32_e32 v147, v97
	ds_bpermute_b32 v97, v228, v96
	v_mul_f32_e32 v104, 0xbfb8aa3b, v102
	v_exp_f32_e32 v104, v104
	v_mul_f32_e32 v105, 0xbfb8aa3b, v103
	v_exp_f32_e32 v105, v105
	s_waitcnt lgkmcnt(0)
	v_add_f32_e32 v112, v96, v97
	ds_bpermute_b32 v113, v229, v112
	v_add_f32_e32 v96, 1.0, v104
	v_add_f32_e32 v97, 1.0, v105
	v_rcp_f32_e32 v96, v96
	v_rcp_f32_e32 v97, v97
	s_waitcnt lgkmcnt(0)
	v_add_f32_e32 v104, v112, v113
	v_fmamk_f32 v104, v104, 0x3c000000, v226
	v_add_f32_e32 v107, 1.0, v107
	v_pk_mul_f32 v[96:97], v[96:97], v[102:103]
	v_rsq_f32_e32 v112, v104
	v_rcp_f32_e32 v106, v106
	v_rcp_f32_e32 v107, v107
	v_ashrrev_i32_e32 v211, 31, v210
	v_mov_b32_e32 v102, v112
	v_pk_mul_f32 v[100:101], v[100:101], v[102:103] op_sel_hi:[1,0]
	v_pk_mul_f32 v[98:99], v[98:99], v[102:103] op_sel_hi:[1,0]
	v_pk_mul_f32 v[100:101], v[12:13], v[100:101]
	v_pk_mul_f32 v[104:105], v[106:107], v[138:139]
	v_pk_mul_f32 v[96:97], v[96:97], v[100:101]
	v_pk_mul_f32 v[100:101], v[142:143], v[102:103] op_sel_hi:[1,0]
	v_pk_mul_f32 v[106:107], v[146:147], v[140:141]
	v_pk_mul_f32 v[100:101], v[14:15], v[100:101]
	v_pk_mul_f32 v[98:99], v[8:9], v[98:99]
	v_pk_mul_f32 v[100:101], v[106:107], v[100:101]
	v_pk_mul_f32 v[98:99], v[104:105], v[98:99]
	v_pk_mul_f32 v[104:105], v[134:135], v[102:103] op_sel_hi:[1,0]
	v_pk_mul_f32 v[106:107], v[108:109], v[102:103] op_sel_hi:[1,0]
	v_pk_mul_f32 v[108:109], v[128:129], v[102:103] op_sel_hi:[1,0]
	v_mul_f32_e32 v103, 0xbfb8aa3b, v124
	v_exp_f32_e32 v103, v103
	v_mul_f32_e32 v112, 0xbfb8aa3b, v125
	v_exp_f32_e32 v113, v112
	v_pk_mul_f32 v[104:105], v[10:11], v[104:105]
	v_add_f32_e32 v103, 1.0, v103
	v_rcp_f32_e32 v112, v103
	v_add_f32_e32 v103, 1.0, v113
	v_rcp_f32_e32 v113, v103
	v_pk_mul_f32 v[110:111], v[110:111], v[102:103] op_sel_hi:[1,0]
	v_mul_f32_e32 v103, 0xbfb8aa3b, v121
	v_pk_mul_f32 v[110:111], v[0:1], v[110:111]
	v_pk_mul_f32 v[112:113], v[112:113], v[124:125]
	v_exp_f32_e32 v103, v103
	v_pk_mul_f32 v[110:111], v[112:113], v[110:111]
	v_mul_f32_e32 v112, 0xbfb8aa3b, v120
	v_exp_f32_e32 v112, v112
	v_add_f32_e32 v103, 1.0, v103
	v_rcp_f32_e32 v103, v103
	v_mul_f32_e32 v113, v123, v102
	v_add_f32_e32 v112, 1.0, v112
	v_rcp_f32_e32 v204, v112
	v_mul_f32_e32 v114, v103, v121
	v_mul_f32_e32 v121, v122, v102
	v_pk_mul_f32 v[104:105], v[132:133], v[104:105]
	v_pk_mul_f32 v[102:103], v[204:205], v[120:121]
	v_pk_mul_f32 v[106:107], v[4:5], v[106:107]
	v_pk_mul_f32 v[108:109], v[6:7], v[108:109]
	v_mul_f32_e32 v112, v2, v113
	v_mov_b32_e32 v115, v102
	v_mov_b32_e32 v113, v103
	v_cvt_pk_bf16_f32 v96, v96, v97
	v_cvt_pk_bf16_f32 v97, v100, v101
	v_lshlrev_b64 v[100:101], 11, v[210:211]
	v_pk_mul_f32 v[106:107], v[116:117], v[106:107]
	v_pk_mul_f32 v[108:109], v[118:119], v[108:109]
	v_cvt_pk_bf16_f32 v98, v98, v99
	v_cvt_pk_bf16_f32 v99, v104, v105
	v_lshl_add_u64 v[100:101], v[192:193], 0, v[100:101]
	v_pk_mul_f32 v[102:103], v[114:115], v[112:113]
	global_store_dwordx4 v[100:101], v[96:99], off
	s_nop 1
	v_cvt_pk_bf16_f32 v96, v106, v107
	v_cvt_pk_bf16_f32 v97, v108, v109
	v_cvt_pk_bf16_f32 v98, v110, v111
	v_cvt_pk_bf16_f32 v99, v102, v103
	global_store_dwordx4 v[100:101], v[96:99], off offset:16
.LBB0_1002:
	s_or_b64 exec, exec, s[12:13]
	v_add_u32_e32 v3, s33, v3
	v_cmp_gt_i32_e32 vcc, s3, v3
	s_and_saveexec_b64 s[12:13], vcc
	s_cbranch_execz .LBB0_1004
	s_waitcnt vmcnt(15)
	v_and_b32_e32 v101, 0xffff0000, v83
	v_and_b32_e32 v100, 0xffff0000, v79
	s_waitcnt vmcnt(11)
	v_and_b32_e32 v103, 0xffff0000, v87
	v_and_b32_e32 v102, 0xffff0000, v91
	s_waitcnt vmcnt(9)
	v_lshlrev_b32_e32 v97, 16, v95
	v_and_b32_e32 v96, 0xffff0000, v95
	v_lshlrev_b32_e32 v95, 16, v79
	v_lshlrev_b32_e32 v98, 16, v91
	v_pk_add_f32 v[100:101], v[100:101], v[102:103]
	v_add_f32_e32 v99, v95, v98
	v_lshlrev_b32_e32 v79, 16, v83
	v_lshlrev_b32_e32 v83, 16, v87
	v_mov_b32_e32 v98, v100
	v_mov_b32_e32 v102, v101
	v_lshlrev_b32_e32 v100, 16, v94
	v_and_b32_e32 v101, 0xffff0000, v94
	v_lshlrev_b32_e32 v94, 16, v90
	v_and_b32_e32 v95, 0xffff0000, v90
	v_lshlrev_b32_e32 v90, 16, v78
	v_and_b32_e32 v91, 0xffff0000, v78
	v_add_f32_e32 v103, v79, v83
	v_pk_add_f32 v[78:79], v[90:91], v[94:95]
	v_lshlrev_b32_e32 v90, 16, v82
	v_and_b32_e32 v91, 0xffff0000, v82
	v_lshlrev_b32_e32 v82, 16, v86
	v_and_b32_e32 v83, 0xffff0000, v86
	v_pk_add_f32 v[82:83], v[90:91], v[82:83]
	v_lshlrev_b32_e32 v86, 16, v89
	v_pk_add_f32 v[78:79], v[78:79], v[82:83]
	v_lshlrev_b32_e32 v82, 16, v93
	v_and_b32_e32 v83, 0xffff0000, v93
	v_and_b32_e32 v87, 0xffff0000, v89
	v_lshlrev_b32_e32 v94, 16, v77
	v_and_b32_e32 v95, 0xffff0000, v77
	v_mul_f32_e32 v77, 0xbfb8aa3b, v82
	v_pk_add_f32 v[86:87], v[94:95], v[86:87]
	v_lshlrev_b32_e32 v94, 16, v81
	v_and_b32_e32 v95, 0xffff0000, v81
	v_exp_f32_e32 v77, v77
	v_mul_f32_e32 v81, 0xbfb8aa3b, v83
	v_exp_f32_e32 v81, v81
	v_lshlrev_b32_e32 v104, 16, v85
	v_and_b32_e32 v105, 0xffff0000, v85
	v_add_f32_e32 v77, 1.0, v77
	v_pk_add_f32 v[94:95], v[94:95], v[104:105]
	v_lshlrev_b32_e32 v104, 16, v92
	v_rcp_f32_e32 v106, v77
	v_add_f32_e32 v77, 1.0, v81
	v_and_b32_e32 v105, 0xffff0000, v92
	v_mul_f32_e32 v81, 0xbfb8aa3b, v104
	v_lshlrev_b32_e32 v92, 16, v88
	v_and_b32_e32 v93, 0xffff0000, v88
	v_lshlrev_b32_e32 v88, 16, v76
	v_and_b32_e32 v89, 0xffff0000, v76
	v_exp_f32_e32 v85, v81
	v_mul_f32_e32 v81, 0xbfb8aa3b, v105
	v_rcp_f32_e32 v107, v77
	v_pk_add_f32 v[76:77], v[88:89], v[92:93]
	v_exp_f32_e32 v92, v81
	v_lshlrev_b32_e32 v88, 16, v80
	v_and_b32_e32 v89, 0xffff0000, v80
	v_lshlrev_b32_e32 v80, 16, v84
	v_and_b32_e32 v81, 0xffff0000, v84
	v_add_f32_e32 v84, 1.0, v85
	v_add_f32_e32 v85, 1.0, v92
	v_rcp_f32_e32 v84, v84
	v_rcp_f32_e32 v85, v85
	v_pk_add_f32 v[80:81], v[88:89], v[80:81]
	s_waitcnt vmcnt(8)
	v_lshlrev_b32_e32 v88, 16, v67
	v_and_b32_e32 v89, 0xffff0000, v67
	v_pk_mul_f32 v[84:85], v[84:85], v[104:105]
	v_lshlrev_b32_e32 v92, 16, v75
	v_and_b32_e32 v93, 0xffff0000, v75
	v_lshlrev_b32_e32 v104, 16, v59
	v_and_b32_e32 v105, 0xffff0000, v59
	v_mul_f32_e32 v59, 0xbfb8aa3b, v88
	v_pk_add_f32 v[92:93], v[104:105], v[92:93]
	v_lshlrev_b32_e32 v104, 16, v63
	v_and_b32_e32 v105, 0xffff0000, v63
	v_exp_f32_e32 v59, v59
	v_mul_f32_e32 v63, 0xbfb8aa3b, v89
	v_exp_f32_e32 v63, v63
	v_pk_mul_f32 v[82:83], v[106:107], v[82:83]
	v_add_f32_e32 v59, 1.0, v59
	v_rcp_f32_e32 v108, v59
	v_add_f32_e32 v59, 1.0, v63
	v_rcp_f32_e32 v109, v59
	v_lshlrev_b32_e32 v106, 16, v71
	v_and_b32_e32 v107, 0xffff0000, v71
	v_pk_add_f32 v[104:105], v[104:105], v[106:107]
	v_lshlrev_b32_e32 v106, 16, v66
	v_and_b32_e32 v107, 0xffff0000, v66
	v_lshlrev_b32_e32 v66, 16, v74
	v_and_b32_e32 v67, 0xffff0000, v74
	v_lshlrev_b32_e32 v74, 16, v58
	v_and_b32_e32 v75, 0xffff0000, v58
	v_pk_add_f32 v[58:59], v[74:75], v[66:67]
	v_lshlrev_b32_e32 v66, 16, v62
	v_and_b32_e32 v67, 0xffff0000, v62
	v_lshlrev_b32_e32 v62, 16, v70
	v_and_b32_e32 v63, 0xffff0000, v70
	v_lshlrev_b32_e32 v70, 16, v65
	v_pk_mul_f32 v[88:89], v[108:109], v[88:89]
	v_lshlrev_b32_e32 v108, 16, v57
	v_and_b32_e32 v109, 0xffff0000, v57
	v_mul_f32_e32 v57, 0xbfb8aa3b, v70
	v_exp_f32_e32 v57, v57
	v_lshlrev_b32_e32 v74, 16, v73
	v_and_b32_e32 v75, 0xffff0000, v73
	v_and_b32_e32 v71, 0xffff0000, v65
	v_pk_add_f32 v[74:75], v[108:109], v[74:75]
	v_lshlrev_b32_e32 v108, 16, v61
	v_and_b32_e32 v109, 0xffff0000, v61
	v_lshlrev_b32_e32 v110, 16, v69
	v_and_b32_e32 v111, 0xffff0000, v69
	v_add_f32_e32 v57, 1.0, v57
	v_pk_add_f32 v[108:109], v[108:109], v[110:111]
	v_rcp_f32_e32 v110, v57
	v_mul_f32_e32 v57, 0xbfb8aa3b, v71
	v_lshlrev_b32_e32 v112, 16, v72
	v_and_b32_e32 v113, 0xffff0000, v72
	v_lshlrev_b32_e32 v72, 16, v56
	v_and_b32_e32 v73, 0xffff0000, v56
	v_exp_f32_e32 v65, v57
	v_pk_add_f32 v[56:57], v[72:73], v[112:113]
	v_lshlrev_b32_e32 v72, 16, v60
	v_and_b32_e32 v73, 0xffff0000, v60
	v_lshlrev_b32_e32 v60, 16, v68
	v_and_b32_e32 v61, 0xffff0000, v68
	v_pk_add_f32 v[60:61], v[72:73], v[60:61]
	v_pk_add_f32 v[62:63], v[66:67], v[62:63]
	v_pk_add_f32 v[56:57], v[56:57], v[60:61]
	v_pk_add_f32 v[74:75], v[74:75], v[108:109]
	v_pk_mul_f32 v[60:61], v[56:57], v[56:57]
	v_pk_add_f32 v[58:59], v[58:59], v[62:63]
	v_mul_f32_e32 v62, 0xbfb8aa3b, v106
	v_pk_mul_f32 v[108:109], v[74:75], v[74:75]
	v_add_f32_e32 v60, v60, v61
	v_exp_f32_e32 v66, v62
	v_mul_f32_e32 v62, 0xbfb8aa3b, v107
	v_add_f32_e32 v60, v108, v60
	v_exp_f32_e32 v67, v62
	v_pk_mul_f32 v[62:63], v[58:59], v[58:59]
	v_add_f32_e32 v60, v109, v60
	v_pk_add_f32 v[92:93], v[92:93], v[104:105]
	v_add_f32_e32 v60, v62, v60
	v_pk_mul_f32 v[104:105], v[92:93], v[92:93]
	v_add_f32_e32 v60, v63, v60
	v_pk_add_f32 v[76:77], v[76:77], v[80:81]
	v_add_f32_e32 v60, v104, v60
	v_pk_mul_f32 v[80:81], v[76:77], v[76:77]
	v_add_f32_e32 v60, v105, v60
	v_pk_add_f32 v[86:87], v[86:87], v[94:95]
	v_add_f32_e32 v60, v80, v60
	v_pk_mul_f32 v[94:95], v[86:87], v[86:87]
	v_add_f32_e32 v60, v81, v60
	v_add_f32_e32 v60, v94, v60
	v_pk_mul_f32 v[90:91], v[78:79], v[78:79]
	v_add_f32_e32 v60, v95, v60
	v_pk_add_f32 v[98:99], v[98:99], v[102:103]
	v_add_f32_e32 v60, v90, v60
	v_pk_mul_f32 v[102:103], v[98:99], v[98:99]
	v_add_f32_e32 v60, v91, v60
	v_add_f32_e32 v60, v103, v60
	v_add_f32_e32 v62, v102, v60
	ds_bpermute_b32 v63, v227, v62
	v_add_f32_e32 v60, 1.0, v65
	v_rcp_f32_e32 v111, v60
	v_lshlrev_b32_e32 v60, 16, v64
	v_and_b32_e32 v61, 0xffff0000, v64
	s_waitcnt lgkmcnt(0)
	v_add_f32_e32 v62, v62, v63
	ds_bpermute_b32 v63, v228, v62
	v_mul_f32_e32 v64, 0xbfb8aa3b, v60
	v_exp_f32_e32 v64, v64
	v_mul_f32_e32 v65, 0xbfb8aa3b, v61
	v_exp_f32_e32 v65, v65
	s_waitcnt lgkmcnt(0)
	v_add_f32_e32 v68, v62, v63
	ds_bpermute_b32 v69, v229, v68
	v_add_f32_e32 v62, 1.0, v64
	v_add_f32_e32 v63, 1.0, v65
	v_rcp_f32_e32 v62, v62
	v_rcp_f32_e32 v63, v63
	s_waitcnt lgkmcnt(0)
	v_add_f32_e32 v64, v68, v69
	v_fmamk_f32 v64, v64, 0x3c000000, v226
	v_add_f32_e32 v66, 1.0, v66
	v_add_f32_e32 v67, 1.0, v67
	v_rsq_f32_e32 v68, v64
	v_pk_mul_f32 v[60:61], v[62:63], v[60:61]
	v_rcp_f32_e32 v66, v66
	v_rcp_f32_e32 v67, v67
	v_mov_b32_e32 v62, v68
	v_pk_mul_f32 v[56:57], v[56:57], v[62:63] op_sel_hi:[1,0]
	v_pk_mul_f32 v[58:59], v[58:59], v[62:63] op_sel_hi:[1,0]
	v_pk_mul_f32 v[56:57], v[12:13], v[56:57]
	v_pk_mul_f32 v[64:65], v[66:67], v[106:107]
	v_pk_mul_f32 v[56:57], v[60:61], v[56:57]
	v_pk_mul_f32 v[60:61], v[74:75], v[62:63] op_sel_hi:[1,0]
	v_pk_mul_f32 v[66:67], v[110:111], v[70:71]
	v_pk_mul_f32 v[60:61], v[14:15], v[60:61]
	v_pk_mul_f32 v[58:59], v[8:9], v[58:59]
	v_pk_mul_f32 v[60:61], v[66:67], v[60:61]
	v_pk_mul_f32 v[58:59], v[64:65], v[58:59]
	v_pk_mul_f32 v[64:65], v[92:93], v[62:63] op_sel_hi:[1,0]
	v_pk_mul_f32 v[66:67], v[76:77], v[62:63] op_sel_hi:[1,0]
	v_pk_mul_f32 v[68:69], v[86:87], v[62:63] op_sel_hi:[1,0]
	v_mul_f32_e32 v63, 0xbfb8aa3b, v100
	v_exp_f32_e32 v63, v63
	v_mul_f32_e32 v70, 0xbfb8aa3b, v101
	v_exp_f32_e32 v71, v70
	v_pk_mul_f32 v[64:65], v[10:11], v[64:65]
	v_add_f32_e32 v63, 1.0, v63
	v_rcp_f32_e32 v70, v63
	v_add_f32_e32 v63, 1.0, v71
	v_rcp_f32_e32 v71, v63
	v_pk_mul_f32 v[72:73], v[78:79], v[62:63] op_sel_hi:[1,0]
	v_mul_f32_e32 v63, 0xbfb8aa3b, v97
	v_pk_mul_f32 v[72:73], v[0:1], v[72:73]
	v_pk_mul_f32 v[70:71], v[70:71], v[100:101]
	v_exp_f32_e32 v63, v63
	v_pk_mul_f32 v[70:71], v[70:71], v[72:73]
	v_mul_f32_e32 v72, 0xbfb8aa3b, v96
	v_exp_f32_e32 v72, v72
	v_add_f32_e32 v63, 1.0, v63
	v_rcp_f32_e32 v63, v63
	v_mul_f32_e32 v73, v99, v62
	v_add_f32_e32 v72, 1.0, v72
	v_rcp_f32_e32 v204, v72
	v_mul_f32_e32 v74, v63, v97
	v_mul_f32_e32 v97, v98, v62
	v_ashrrev_i32_e32 v209, 31, v208
	v_pk_mul_f32 v[62:63], v[204:205], v[96:97]
	v_pk_mul_f32 v[64:65], v[88:89], v[64:65]
	v_pk_mul_f32 v[66:67], v[4:5], v[66:67]
	v_pk_mul_f32 v[68:69], v[6:7], v[68:69]
	v_mul_f32_e32 v72, v2, v73
	v_mov_b32_e32 v75, v62
	v_mov_b32_e32 v73, v63
	v_cvt_pk_bf16_f32 v56, v56, v57
	v_cvt_pk_bf16_f32 v57, v60, v61
	v_lshlrev_b64 v[60:61], 11, v[208:209]
	v_pk_mul_f32 v[66:67], v[84:85], v[66:67]
	v_pk_mul_f32 v[68:69], v[82:83], v[68:69]
	v_cvt_pk_bf16_f32 v58, v58, v59
	v_cvt_pk_bf16_f32 v59, v64, v65
	v_lshl_add_u64 v[60:61], v[192:193], 0, v[60:61]
	v_pk_mul_f32 v[62:63], v[74:75], v[72:73]
	global_store_dwordx4 v[60:61], v[56:59], off
	s_nop 1
	v_cvt_pk_bf16_f32 v56, v66, v67
	v_cvt_pk_bf16_f32 v57, v68, v69
	v_cvt_pk_bf16_f32 v58, v70, v71
	v_cvt_pk_bf16_f32 v59, v62, v63
	global_store_dwordx4 v[60:61], v[56:59], off offset:16
.LBB0_1004:
	s_or_b64 exec, exec, s[12:13]
	v_add_u32_e32 v3, s33, v3
	v_cmp_gt_i32_e32 vcc, s3, v3
	s_and_saveexec_b64 s[12:13], vcc
	s_cbranch_execz .LBB0_991
	s_waitcnt vmcnt(9)
	v_and_b32_e32 v61, 0xffff0000, v43
	v_and_b32_e32 v60, 0xffff0000, v39
	s_waitcnt vmcnt(5)
	v_and_b32_e32 v63, 0xffff0000, v47
	v_and_b32_e32 v62, 0xffff0000, v51
	s_waitcnt vmcnt(3)
	v_lshlrev_b32_e32 v57, 16, v55
	v_and_b32_e32 v56, 0xffff0000, v55
	v_lshlrev_b32_e32 v55, 16, v39
	v_lshlrev_b32_e32 v58, 16, v51
	v_pk_add_f32 v[60:61], v[60:61], v[62:63]
	v_add_f32_e32 v59, v55, v58
	v_lshlrev_b32_e32 v39, 16, v43
	v_lshlrev_b32_e32 v43, 16, v47
	v_mov_b32_e32 v58, v60
	v_mov_b32_e32 v62, v61
	v_lshlrev_b32_e32 v60, 16, v54
	v_and_b32_e32 v61, 0xffff0000, v54
	v_lshlrev_b32_e32 v54, 16, v50
	v_and_b32_e32 v55, 0xffff0000, v50
	v_lshlrev_b32_e32 v50, 16, v38
	v_and_b32_e32 v51, 0xffff0000, v38
	v_add_f32_e32 v63, v39, v43
	v_pk_add_f32 v[38:39], v[50:51], v[54:55]
	v_lshlrev_b32_e32 v50, 16, v42
	v_and_b32_e32 v51, 0xffff0000, v42
	v_lshlrev_b32_e32 v42, 16, v46
	v_and_b32_e32 v43, 0xffff0000, v46
	v_pk_add_f32 v[42:43], v[50:51], v[42:43]
	v_lshlrev_b32_e32 v46, 16, v49
	v_pk_add_f32 v[38:39], v[38:39], v[42:43]
	v_lshlrev_b32_e32 v42, 16, v53
	v_and_b32_e32 v43, 0xffff0000, v53
	v_and_b32_e32 v47, 0xffff0000, v49
	v_lshlrev_b32_e32 v54, 16, v37
	v_and_b32_e32 v55, 0xffff0000, v37
	v_mul_f32_e32 v37, 0xbfb8aa3b, v42
	v_pk_add_f32 v[46:47], v[54:55], v[46:47]
	v_lshlrev_b32_e32 v54, 16, v41
	v_and_b32_e32 v55, 0xffff0000, v41
	v_exp_f32_e32 v37, v37
	v_mul_f32_e32 v41, 0xbfb8aa3b, v43
	v_exp_f32_e32 v41, v41
	v_lshlrev_b32_e32 v64, 16, v45
	v_and_b32_e32 v65, 0xffff0000, v45
	v_add_f32_e32 v37, 1.0, v37
	v_pk_add_f32 v[54:55], v[54:55], v[64:65]
	v_lshlrev_b32_e32 v64, 16, v52
	v_rcp_f32_e32 v66, v37
	v_add_f32_e32 v37, 1.0, v41
	v_and_b32_e32 v65, 0xffff0000, v52
	v_mul_f32_e32 v41, 0xbfb8aa3b, v64
	v_lshlrev_b32_e32 v52, 16, v48
	v_and_b32_e32 v53, 0xffff0000, v48
	v_lshlrev_b32_e32 v48, 16, v36
	v_and_b32_e32 v49, 0xffff0000, v36
	v_exp_f32_e32 v45, v41
	v_mul_f32_e32 v41, 0xbfb8aa3b, v65
	v_rcp_f32_e32 v67, v37
	v_pk_add_f32 v[36:37], v[48:49], v[52:53]
	v_exp_f32_e32 v52, v41
	v_lshlrev_b32_e32 v48, 16, v40
	v_and_b32_e32 v49, 0xffff0000, v40
	v_lshlrev_b32_e32 v40, 16, v44
	v_and_b32_e32 v41, 0xffff0000, v44
	v_add_f32_e32 v44, 1.0, v45
	v_add_f32_e32 v45, 1.0, v52
	v_rcp_f32_e32 v44, v44
	v_rcp_f32_e32 v45, v45
	v_pk_add_f32 v[40:41], v[48:49], v[40:41]
	s_waitcnt vmcnt(2)
	v_lshlrev_b32_e32 v48, 16, v27
	v_and_b32_e32 v49, 0xffff0000, v27
	v_pk_mul_f32 v[44:45], v[44:45], v[64:65]
	v_lshlrev_b32_e32 v52, 16, v35
	v_and_b32_e32 v53, 0xffff0000, v35
	v_lshlrev_b32_e32 v64, 16, v19
	v_and_b32_e32 v65, 0xffff0000, v19
	v_mul_f32_e32 v19, 0xbfb8aa3b, v48
	v_pk_add_f32 v[52:53], v[64:65], v[52:53]
	v_lshlrev_b32_e32 v64, 16, v23
	v_and_b32_e32 v65, 0xffff0000, v23
	v_exp_f32_e32 v19, v19
	v_mul_f32_e32 v23, 0xbfb8aa3b, v49
	v_exp_f32_e32 v23, v23
	v_pk_mul_f32 v[42:43], v[66:67], v[42:43]
	v_add_f32_e32 v19, 1.0, v19
	v_rcp_f32_e32 v68, v19
	v_add_f32_e32 v19, 1.0, v23
	v_rcp_f32_e32 v69, v19
	v_lshlrev_b32_e32 v66, 16, v31
	v_and_b32_e32 v67, 0xffff0000, v31
	v_pk_add_f32 v[64:65], v[64:65], v[66:67]
	v_lshlrev_b32_e32 v66, 16, v26
	v_and_b32_e32 v67, 0xffff0000, v26
	v_lshlrev_b32_e32 v26, 16, v34
	v_and_b32_e32 v27, 0xffff0000, v34
	v_lshlrev_b32_e32 v34, 16, v18
	v_and_b32_e32 v35, 0xffff0000, v18
	v_pk_add_f32 v[18:19], v[34:35], v[26:27]
	v_lshlrev_b32_e32 v26, 16, v22
	v_and_b32_e32 v27, 0xffff0000, v22
	v_lshlrev_b32_e32 v22, 16, v30
	v_and_b32_e32 v23, 0xffff0000, v30
	v_lshlrev_b32_e32 v30, 16, v25
	v_pk_mul_f32 v[48:49], v[68:69], v[48:49]
	v_lshlrev_b32_e32 v68, 16, v17
	v_and_b32_e32 v69, 0xffff0000, v17
	v_mul_f32_e32 v17, 0xbfb8aa3b, v30
	v_exp_f32_e32 v17, v17
	v_lshlrev_b32_e32 v34, 16, v33
	v_and_b32_e32 v35, 0xffff0000, v33
	v_and_b32_e32 v31, 0xffff0000, v25
	v_pk_add_f32 v[34:35], v[68:69], v[34:35]
	v_lshlrev_b32_e32 v68, 16, v21
	v_and_b32_e32 v69, 0xffff0000, v21
	v_lshlrev_b32_e32 v70, 16, v29
	v_and_b32_e32 v71, 0xffff0000, v29
	v_add_f32_e32 v17, 1.0, v17
	v_pk_add_f32 v[68:69], v[68:69], v[70:71]
	v_rcp_f32_e32 v70, v17
	v_mul_f32_e32 v17, 0xbfb8aa3b, v31
	v_lshlrev_b32_e32 v72, 16, v32
	v_and_b32_e32 v73, 0xffff0000, v32
	v_lshlrev_b32_e32 v32, 16, v16
	v_and_b32_e32 v33, 0xffff0000, v16
	v_exp_f32_e32 v25, v17
	v_pk_add_f32 v[16:17], v[32:33], v[72:73]
	v_lshlrev_b32_e32 v32, 16, v20
	v_and_b32_e32 v33, 0xffff0000, v20
	v_lshlrev_b32_e32 v20, 16, v28
	v_and_b32_e32 v21, 0xffff0000, v28
	v_pk_add_f32 v[20:21], v[32:33], v[20:21]
	v_pk_add_f32 v[22:23], v[26:27], v[22:23]
	v_pk_add_f32 v[16:17], v[16:17], v[20:21]
	v_pk_add_f32 v[34:35], v[34:35], v[68:69]
	v_pk_mul_f32 v[20:21], v[16:17], v[16:17]
	v_pk_add_f32 v[18:19], v[18:19], v[22:23]
	v_mul_f32_e32 v22, 0xbfb8aa3b, v66
	v_pk_mul_f32 v[68:69], v[34:35], v[34:35]
	v_add_f32_e32 v20, v20, v21
	v_exp_f32_e32 v26, v22
	v_mul_f32_e32 v22, 0xbfb8aa3b, v67
	v_add_f32_e32 v20, v68, v20
	v_exp_f32_e32 v27, v22
	v_pk_mul_f32 v[22:23], v[18:19], v[18:19]
	v_add_f32_e32 v20, v69, v20
	v_pk_add_f32 v[52:53], v[52:53], v[64:65]
	v_add_f32_e32 v20, v22, v20
	v_pk_mul_f32 v[64:65], v[52:53], v[52:53]
	v_add_f32_e32 v20, v23, v20
	v_pk_add_f32 v[36:37], v[36:37], v[40:41]
	v_add_f32_e32 v20, v64, v20
	v_pk_mul_f32 v[40:41], v[36:37], v[36:37]
	v_add_f32_e32 v20, v65, v20
	v_pk_add_f32 v[46:47], v[46:47], v[54:55]
	v_add_f32_e32 v20, v40, v20
	v_pk_mul_f32 v[54:55], v[46:47], v[46:47]
	v_add_f32_e32 v20, v41, v20
	v_add_f32_e32 v20, v54, v20
	v_pk_mul_f32 v[50:51], v[38:39], v[38:39]
	v_add_f32_e32 v20, v55, v20
	v_pk_add_f32 v[58:59], v[58:59], v[62:63]
	v_add_f32_e32 v20, v50, v20
	v_pk_mul_f32 v[62:63], v[58:59], v[58:59]
	v_add_f32_e32 v20, v51, v20
	v_add_f32_e32 v20, v63, v20
	v_add_f32_e32 v22, v62, v20
	ds_bpermute_b32 v23, v227, v22
	v_add_f32_e32 v20, 1.0, v25
	v_rcp_f32_e32 v71, v20
	v_lshlrev_b32_e32 v20, 16, v24
	v_and_b32_e32 v21, 0xffff0000, v24
	s_waitcnt lgkmcnt(0)
	v_add_f32_e32 v22, v22, v23
	ds_bpermute_b32 v23, v228, v22
	v_mul_f32_e32 v24, 0xbfb8aa3b, v20
	v_exp_f32_e32 v24, v24
	v_mul_f32_e32 v25, 0xbfb8aa3b, v21
	v_exp_f32_e32 v25, v25
	s_waitcnt lgkmcnt(0)
	v_add_f32_e32 v28, v22, v23
	ds_bpermute_b32 v29, v229, v28
	v_add_f32_e32 v22, 1.0, v24
	v_add_f32_e32 v23, 1.0, v25
	v_rcp_f32_e32 v22, v22
	v_rcp_f32_e32 v23, v23
	s_waitcnt lgkmcnt(0)
	v_add_f32_e32 v24, v28, v29
	v_fmamk_f32 v24, v24, 0x3c000000, v226
	v_add_f32_e32 v26, 1.0, v26
	v_add_f32_e32 v27, 1.0, v27
	v_rsq_f32_e32 v28, v24
	v_pk_mul_f32 v[20:21], v[22:23], v[20:21]
	v_rcp_f32_e32 v26, v26
	v_rcp_f32_e32 v27, v27
	v_mov_b32_e32 v22, v28
	v_pk_mul_f32 v[16:17], v[16:17], v[22:23] op_sel_hi:[1,0]
	v_pk_mul_f32 v[18:19], v[18:19], v[22:23] op_sel_hi:[1,0]
	v_pk_mul_f32 v[16:17], v[12:13], v[16:17]
	v_pk_mul_f32 v[24:25], v[26:27], v[66:67]
	v_pk_mul_f32 v[16:17], v[20:21], v[16:17]
	v_pk_mul_f32 v[20:21], v[34:35], v[22:23] op_sel_hi:[1,0]
	v_pk_mul_f32 v[26:27], v[70:71], v[30:31]
	v_pk_mul_f32 v[20:21], v[14:15], v[20:21]
	v_pk_mul_f32 v[18:19], v[8:9], v[18:19]
	v_pk_mul_f32 v[20:21], v[26:27], v[20:21]
	v_pk_mul_f32 v[18:19], v[24:25], v[18:19]
	v_pk_mul_f32 v[24:25], v[52:53], v[22:23] op_sel_hi:[1,0]
	v_pk_mul_f32 v[26:27], v[36:37], v[22:23] op_sel_hi:[1,0]
	v_pk_mul_f32 v[28:29], v[46:47], v[22:23] op_sel_hi:[1,0]
	v_mul_f32_e32 v23, 0xbfb8aa3b, v60
	v_exp_f32_e32 v23, v23
	v_mul_f32_e32 v30, 0xbfb8aa3b, v61
	v_exp_f32_e32 v31, v30
	v_pk_mul_f32 v[24:25], v[10:11], v[24:25]
	v_add_f32_e32 v23, 1.0, v23
	v_rcp_f32_e32 v30, v23
	v_add_f32_e32 v23, 1.0, v31
	v_rcp_f32_e32 v31, v23
	v_pk_mul_f32 v[32:33], v[38:39], v[22:23] op_sel_hi:[1,0]
	v_mul_f32_e32 v23, 0xbfb8aa3b, v57
	v_pk_mul_f32 v[32:33], v[0:1], v[32:33]
	v_pk_mul_f32 v[30:31], v[30:31], v[60:61]
	v_exp_f32_e32 v23, v23
	v_pk_mul_f32 v[30:31], v[30:31], v[32:33]
	v_mul_f32_e32 v32, 0xbfb8aa3b, v56
	v_exp_f32_e32 v32, v32
	v_add_f32_e32 v23, 1.0, v23
	v_rcp_f32_e32 v23, v23
	v_mul_f32_e32 v33, v59, v22
	v_add_f32_e32 v32, 1.0, v32
	v_rcp_f32_e32 v204, v32
	v_mul_f32_e32 v34, v23, v57
	v_mul_f32_e32 v57, v58, v22
	v_ashrrev_i32_e32 v207, 31, v206
	v_pk_mul_f32 v[22:23], v[204:205], v[56:57]
	v_pk_mul_f32 v[24:25], v[48:49], v[24:25]
	v_pk_mul_f32 v[26:27], v[4:5], v[26:27]
	v_pk_mul_f32 v[28:29], v[6:7], v[28:29]
	v_mul_f32_e32 v32, v2, v33
	v_mov_b32_e32 v35, v22
	v_mov_b32_e32 v33, v23
	v_cvt_pk_bf16_f32 v16, v16, v17
	v_cvt_pk_bf16_f32 v17, v20, v21
	v_lshlrev_b64 v[20:21], 11, v[206:207]
	v_pk_mul_f32 v[26:27], v[44:45], v[26:27]
	v_pk_mul_f32 v[28:29], v[42:43], v[28:29]
	v_cvt_pk_bf16_f32 v18, v18, v19
	v_cvt_pk_bf16_f32 v19, v24, v25
	v_lshl_add_u64 v[20:21], v[192:193], 0, v[20:21]
	v_pk_mul_f32 v[22:23], v[34:35], v[32:33]
	global_store_dwordx4 v[20:21], v[16:19], off
	s_nop 1
	v_cvt_pk_bf16_f32 v16, v26, v27
	v_cvt_pk_bf16_f32 v17, v28, v29
	v_cvt_pk_bf16_f32 v18, v30, v31
	v_cvt_pk_bf16_f32 v19, v22, v23
	global_store_dwordx4 v[20:21], v[16:19], off offset:16
	s_branch .LBB0_991

.LBB0_1130:
	s_or_b64 exec, exec, s[40:41]
	v_mov_b32_e32 v60, v45
	v_mov_b32_e32 v61, v41
	v_mov_b32_e32 v58, v44
	v_mov_b32_e32 v59, v40
	v_pk_mul_f32 v[60:61], v[60:61], v[60:61]
	v_mov_b32_e32 v62, v37
	v_pk_fma_f32 v[58:59], v[58:59], v[58:59], v[60:61]
	v_mov_b32_e32 v60, v46
	v_mov_b32_e32 v61, v42
	v_pk_fma_f32 v[58:59], v[60:61], v[60:61], v[58:59]
	v_mov_b32_e32 v60, v47
	v_mov_b32_e32 v61, v43
	v_mov_b32_e32 v63, v33
	v_pk_fma_f32 v[58:59], v[60:61], v[60:61], v[58:59]
	v_mov_b32_e32 v60, v36
	v_mov_b32_e32 v61, v32
	v_pk_mul_f32 v[62:63], v[62:63], v[62:63]
	v_add_f32_e32 v58, v58, v59
	v_pk_fma_f32 v[60:61], v[60:61], v[60:61], v[62:63]
	v_mov_b32_e32 v62, v38
	v_mov_b32_e32 v63, v34
	v_pk_fma_f32 v[60:61], v[62:63], v[62:63], v[60:61]
	v_mov_b32_e32 v62, v39
	v_mov_b32_e32 v63, v35
	v_pk_fma_f32 v[60:61], v[62:63], v[62:63], v[60:61]
	v_lshl_add_u64 v[56:57], v[132:133], 0, v[56:57]
	v_add_f32_e32 v58, v58, v60
	v_add_f32_e32 v58, v58, v61
	ds_bpermute_b32 v59, v228, v58
	v_pk_add_f32 v[60:61], v[20:21], 1.0 op_sel_hi:[1,0]
	s_waitcnt lgkmcnt(0)
	v_add_f32_e32 v58, v58, v59
	ds_bpermute_b32 v59, v229, v58
	s_waitcnt lgkmcnt(0)
	v_add_f32_e32 v58, v58, v59
	s_nop 1
	v_add_f32_dpp v58, v58, v58 row_ror:8 row_mask:0xf bank_mask:0xf
	s_nop 1
	v_add_f32_dpp v58, v58, v58 row_ror:4 row_mask:0xf bank_mask:0xf
	s_nop 1
	v_add_f32_dpp v58, v58, v58 quad_perm:[2,3,0,1] row_mask:0xf bank_mask:0xf
	s_nop 1
	v_add_f32_dpp v58, v58, v58 quad_perm:[1,0,3,2] row_mask:0xf bank_mask:0xf
	v_fmamk_f32 v58, v58, 0x3a800000, v234
	v_rsq_f32_e32 v62, v58
	v_pk_add_f32 v[58:59], v[22:23], 1.0 op_sel_hi:[1,0]
	v_pk_mul_f32 v[46:47], v[46:47], v[62:63] op_sel_hi:[1,0]
	v_pk_mul_f32 v[44:45], v[44:45], v[62:63] op_sel_hi:[1,0]
	v_pk_mul_f32 v[46:47], v[10:11], v[46:47]
	v_pk_mul_f32 v[44:45], v[8:9], v[44:45]
	v_pk_fma_f32 v[46:47], v[58:59], v[46:47], v[18:19]
	v_pk_fma_f32 v[44:45], v[60:61], v[44:45], v[16:17]
	v_pk_mul_f32 v[42:43], v[42:43], v[62:63] op_sel_hi:[1,0]
	v_cvt_pk_bf16_f32 v44, v44, v45
	v_cvt_pk_bf16_f32 v45, v46, v47
	v_pk_mul_f32 v[40:41], v[40:41], v[62:63] op_sel_hi:[1,0]
	global_store_dwordx2 v[56:57], v[44:45], off
	v_pk_mul_f32 v[40:41], v[0:1], v[40:41]
	v_pk_mul_f32 v[42:43], v[2:3], v[42:43]
	v_pk_add_f32 v[44:45], v[30:31], 1.0 op_sel_hi:[1,0]
	v_pk_add_f32 v[46:47], v[28:29], 1.0 op_sel_hi:[1,0]
	v_pk_fma_f32 v[42:43], v[44:45], v[42:43], v[26:27]
	v_pk_fma_f32 v[40:41], v[46:47], v[40:41], v[24:25]
	v_pk_mul_f32 v[38:39], v[38:39], v[62:63] op_sel_hi:[1,0]
	v_cvt_pk_bf16_f32 v40, v40, v41
	v_cvt_pk_bf16_f32 v41, v42, v43
	v_pk_mul_f32 v[36:37], v[36:37], v[62:63] op_sel_hi:[1,0]
	global_store_dwordx2 v[56:57], v[40:41], off offset:512
	v_pk_mul_f32 v[36:37], v[4:5], v[36:37]
	v_pk_mul_f32 v[38:39], v[6:7], v[38:39]
	v_pk_add_f32 v[40:41], v[54:55], 1.0 op_sel_hi:[1,0]
	v_pk_add_f32 v[42:43], v[52:53], 1.0 op_sel_hi:[1,0]
	v_pk_fma_f32 v[38:39], v[40:41], v[38:39], v[50:51]
	v_pk_fma_f32 v[36:37], v[42:43], v[36:37], v[48:49]
	v_pk_mul_f32 v[34:35], v[34:35], v[62:63] op_sel_hi:[1,0]
	v_cvt_pk_bf16_f32 v36, v36, v37
	v_cvt_pk_bf16_f32 v37, v38, v39
	v_pk_mul_f32 v[32:33], v[32:33], v[62:63] op_sel_hi:[1,0]
	global_store_dwordx2 v[56:57], v[36:37], off offset:1024
	v_pk_mul_f32 v[32:33], v[12:13], v[32:33]
	v_pk_mul_f32 v[34:35], v[14:15], v[34:35]
	v_pk_add_f32 v[36:37], v[78:79], 1.0 op_sel_hi:[1,0]
	v_pk_add_f32 v[38:39], v[76:77], 1.0 op_sel_hi:[1,0]
	v_pk_fma_f32 v[34:35], v[36:37], v[34:35], v[74:75]
	v_pk_fma_f32 v[32:33], v[38:39], v[32:33], v[72:73]
	s_nop 0
	v_cvt_pk_bf16_f32 v32, v32, v33
	v_cvt_pk_bf16_f32 v33, v34, v35
	global_store_dwordx2 v[56:57], v[32:33], off offset:1536

.LBB0_1142:
	s_or_b64 exec, exec, s[6:7]
	v_mov_b32_e32 v236, v217
	v_mov_b32_e32 v237, v213
	v_mov_b32_e32 v222, v216
	v_mov_b32_e32 v223, v212
	v_pk_mul_f32 v[236:237], v[236:237], v[236:237]
	v_mov_b32_e32 v238, v209
	v_pk_fma_f32 v[222:223], v[222:223], v[222:223], v[236:237]
	v_mov_b32_e32 v236, v218
	v_mov_b32_e32 v237, v214
	v_pk_fma_f32 v[222:223], v[236:237], v[236:237], v[222:223]
	v_mov_b32_e32 v236, v219
	v_mov_b32_e32 v237, v215
	v_mov_b32_e32 v239, v205
	v_pk_fma_f32 v[222:223], v[236:237], v[236:237], v[222:223]
	v_mov_b32_e32 v236, v208
	v_mov_b32_e32 v237, v204
	v_pk_mul_f32 v[238:239], v[238:239], v[238:239]
	v_add_f32_e32 v129, v222, v223
	v_pk_fma_f32 v[236:237], v[236:237], v[236:237], v[238:239]
	v_mov_b32_e32 v238, v210
	v_mov_b32_e32 v239, v206
	v_pk_fma_f32 v[236:237], v[238:239], v[238:239], v[236:237]
	v_mov_b32_e32 v238, v211
	v_mov_b32_e32 v239, v207
	v_pk_fma_f32 v[236:237], v[238:239], v[238:239], v[236:237]
	v_pk_add_f32 v[222:223], v[20:21], 1.0 op_sel_hi:[1,0]
	v_add_f32_e32 v129, v129, v236
	v_add_f32_e32 v129, v129, v237
	ds_bpermute_b32 v155, v228, v129
	v_lshl_add_u64 v[236:237], v[132:133], 0, v[220:221]
	v_pk_add_f32 v[220:221], v[22:23], 1.0 op_sel_hi:[1,0]
	s_waitcnt lgkmcnt(0)
	v_add_f32_e32 v129, v129, v155
	ds_bpermute_b32 v155, v229, v129
	s_waitcnt lgkmcnt(0)
	v_add_f32_e32 v129, v129, v155
	s_nop 1
	v_add_f32_dpp v129, v129, v129 row_ror:8 row_mask:0xf bank_mask:0xf
	s_nop 1
	v_add_f32_dpp v129, v129, v129 row_ror:4 row_mask:0xf bank_mask:0xf
	s_nop 1
	v_add_f32_dpp v129, v129, v129 quad_perm:[2,3,0,1] row_mask:0xf bank_mask:0xf
	s_nop 1
	v_add_f32_dpp v129, v129, v129 quad_perm:[1,0,3,2] row_mask:0xf bank_mask:0xf
	v_fmamk_f32 v129, v129, 0x3a800000, v234
	v_rsq_f32_e32 v129, v129
	s_nop 0
	v_mov_b32_e32 v238, v129
	v_pk_mul_f32 v[218:219], v[218:219], v[238:239] op_sel_hi:[1,0]
	v_pk_mul_f32 v[216:217], v[216:217], v[238:239] op_sel_hi:[1,0]
	v_pk_mul_f32 v[218:219], v[10:11], v[218:219]
	v_pk_mul_f32 v[216:217], v[8:9], v[216:217]
	v_pk_fma_f32 v[218:219], v[220:221], v[218:219], v[18:19]
	v_pk_fma_f32 v[216:217], v[222:223], v[216:217], v[16:17]
	v_pk_mul_f32 v[214:215], v[214:215], v[238:239] op_sel_hi:[1,0]
	v_cvt_pk_bf16_f32 v216, v216, v217
	v_cvt_pk_bf16_f32 v217, v218, v219
	v_pk_mul_f32 v[212:213], v[212:213], v[238:239] op_sel_hi:[1,0]
	global_store_dwordx2 v[236:237], v[216:217], off
	v_pk_mul_f32 v[216:217], v[0:1], v[212:213]
	v_pk_mul_f32 v[218:219], v[2:3], v[214:215]
	v_pk_add_f32 v[212:213], v[30:31], 1.0 op_sel_hi:[1,0]
	v_pk_add_f32 v[214:215], v[28:29], 1.0 op_sel_hi:[1,0]
	v_pk_fma_f32 v[218:219], v[212:213], v[218:219], v[26:27]
	v_pk_fma_f32 v[216:217], v[214:215], v[216:217], v[24:25]
	v_pk_mul_f32 v[210:211], v[210:211], v[238:239] op_sel_hi:[1,0]
	v_cvt_pk_bf16_f32 v216, v216, v217
	v_cvt_pk_bf16_f32 v217, v218, v219
	v_pk_mul_f32 v[208:209], v[208:209], v[238:239] op_sel_hi:[1,0]
	global_store_dwordx2 v[236:237], v[216:217], off offset:512
	v_pk_mul_f32 v[216:217], v[4:5], v[208:209]
	v_pk_mul_f32 v[218:219], v[6:7], v[210:211]
	v_pk_add_f32 v[208:209], v[54:55], 1.0 op_sel_hi:[1,0]
	v_pk_add_f32 v[210:211], v[52:53], 1.0 op_sel_hi:[1,0]
	v_pk_fma_f32 v[218:219], v[208:209], v[218:219], v[50:51]
	v_pk_fma_f32 v[216:217], v[210:211], v[216:217], v[48:49]
	v_pk_mul_f32 v[206:207], v[206:207], v[238:239] op_sel_hi:[1,0]
	v_cvt_pk_bf16_f32 v216, v216, v217
	v_cvt_pk_bf16_f32 v217, v218, v219
	v_pk_mul_f32 v[204:205], v[204:205], v[238:239] op_sel_hi:[1,0]
	global_store_dwordx2 v[236:237], v[216:217], off offset:1024
	v_pk_mul_f32 v[216:217], v[12:13], v[204:205]
	v_pk_mul_f32 v[218:219], v[14:15], v[206:207]
	v_pk_add_f32 v[204:205], v[78:79], 1.0 op_sel_hi:[1,0]
	v_pk_add_f32 v[206:207], v[76:77], 1.0 op_sel_hi:[1,0]
	v_pk_fma_f32 v[218:219], v[204:205], v[218:219], v[74:75]
	v_pk_fma_f32 v[216:217], v[206:207], v[216:217], v[72:73]
	v_cmp_lt_i32_e32 vcc, v194, v226
	v_cvt_pk_bf16_f32 v216, v216, v217
	v_cvt_pk_bf16_f32 v217, v218, v219
	global_store_dwordx2 v[236:237], v[216:217], off offset:1536
	s_and_saveexec_b64 s[6:7], vcc
	s_cbranch_execz .LBB0_1167
	s_waitcnt vmcnt(43)
	v_lshlrev_b32_e32 v216, 16, v202
	v_and_b32_e32 v217, 0xffff0000, v202
	v_lshlrev_b32_e32 v202, 16, v203
	v_and_b32_e32 v203, 0xffff0000, v203
	v_pk_add_f32 v[126:127], v[126:127], v[202:203]
	s_waitcnt vmcnt(42)
	v_lshlrev_b32_e32 v202, 16, v200
	v_and_b32_e32 v203, 0xffff0000, v200
	v_lshlrev_b32_e32 v200, 16, v201
	v_and_b32_e32 v201, 0xffff0000, v201
	v_pk_add_f32 v[122:123], v[122:123], v[200:201]
	s_waitcnt vmcnt(41)
	v_lshlrev_b32_e32 v200, 16, v198
	v_and_b32_e32 v201, 0xffff0000, v198
	v_lshlrev_b32_e32 v198, 16, v199
	v_and_b32_e32 v199, 0xffff0000, v199
	v_ashrrev_i32_e32 v195, 31, v194
	v_pk_add_f32 v[124:125], v[124:125], v[216:217]
	v_pk_add_f32 v[118:119], v[118:119], v[198:199]
	s_waitcnt vmcnt(40)
	v_lshlrev_b32_e32 v198, 16, v196
	v_and_b32_e32 v199, 0xffff0000, v196
	v_lshlrev_b32_e32 v196, 16, v197
	v_and_b32_e32 v197, 0xffff0000, v197
	v_add_u32_e32 v129, 0xffffe001, v128
	v_lshlrev_b64 v[194:195], 11, v[194:195]
	v_pk_add_f32 v[120:121], v[120:121], v[202:203]
	v_pk_add_f32 v[114:115], v[114:115], v[196:197]
	v_pk_add_f32 v[112:113], v[112:113], v[198:199]
	v_ashrrev_i32_e32 v129, 10, v129
	v_lshl_add_u64 v[196:197], v[134:135], 0, v[194:195]
	v_cvt_pk_bf16_f32 v198, v124, v125
	v_cvt_pk_bf16_f32 v199, v126, v127
	v_pk_add_f32 v[116:117], v[116:117], v[200:201]
	v_add_u32_e32 v129, 1, v129
	v_cmp_lt_i32_e32 vcc, s29, v128
	global_store_dwordx2 v[196:197], v[198:199], off
	v_cvt_pk_bf16_f32 v198, v120, v121
	v_cvt_pk_bf16_f32 v199, v122, v123
	v_cndmask_b32_e32 v129, 0, v129, vcc
	global_store_dwordx2 v[196:197], v[198:199], off offset:512
	v_cvt_pk_bf16_f32 v198, v116, v117
	v_cvt_pk_bf16_f32 v199, v118, v119
	global_store_dwordx2 v[196:197], v[198:199], off offset:1024
	v_cvt_pk_bf16_f32 v198, v112, v113
	v_cvt_pk_bf16_f32 v199, v114, v115
	v_cmp_ne_u32_e32 vcc, v129, v235
	global_store_dwordx2 v[196:197], v[198:199], off offset:1536
	s_and_saveexec_b64 s[40:41], vcc
	s_cbranch_execz .LBB0_1153
	global_load_dwordx4 v[16:19], v[136:137], off
	global_load_dwordx4 v[20:23], v[138:139], off
	v_mad_i64_i32 v[196:197], s[42:43], v129, s16, v[152:153]
	s_mov_b64 s[42:43], 0

.LBB0_1153:
	s_or_b64 exec, exec, s[40:41]
	v_mov_b32_e32 v198, v125
	v_mov_b32_e32 v199, v121
	v_mov_b32_e32 v196, v124
	v_mov_b32_e32 v197, v120
	v_pk_mul_f32 v[198:199], v[198:199], v[198:199]
	v_mov_b32_e32 v200, v117
	v_pk_fma_f32 v[196:197], v[196:197], v[196:197], v[198:199]
	v_mov_b32_e32 v198, v126
	v_mov_b32_e32 v199, v122
	v_pk_fma_f32 v[196:197], v[198:199], v[198:199], v[196:197]
	v_mov_b32_e32 v198, v127
	v_mov_b32_e32 v199, v123
	v_mov_b32_e32 v201, v113
	v_pk_fma_f32 v[196:197], v[198:199], v[198:199], v[196:197]
	v_mov_b32_e32 v198, v116
	v_mov_b32_e32 v199, v112
	v_pk_mul_f32 v[200:201], v[200:201], v[200:201]
	v_add_f32_e32 v129, v196, v197
	v_pk_fma_f32 v[198:199], v[198:199], v[198:199], v[200:201]
	v_mov_b32_e32 v200, v118
	v_mov_b32_e32 v201, v114
	v_pk_fma_f32 v[198:199], v[200:201], v[200:201], v[198:199]
	v_mov_b32_e32 v200, v119
	v_mov_b32_e32 v201, v115
	v_pk_fma_f32 v[198:199], v[200:201], v[200:201], v[198:199]
	v_lshl_add_u64 v[194:195], v[132:133], 0, v[194:195]
	v_add_f32_e32 v129, v129, v198
	v_add_f32_e32 v129, v129, v199
	ds_bpermute_b32 v155, v228, v129
	s_waitcnt lgkmcnt(0)
	v_add_f32_e32 v129, v129, v155
	ds_bpermute_b32 v155, v229, v129
	s_waitcnt lgkmcnt(0)
	v_add_f32_e32 v129, v129, v155
	s_nop 1
	v_add_f32_dpp v129, v129, v129 row_ror:8 row_mask:0xf bank_mask:0xf
	s_nop 1
	v_add_f32_dpp v129, v129, v129 row_ror:4 row_mask:0xf bank_mask:0xf
	s_nop 1
	v_add_f32_dpp v129, v129, v129 quad_perm:[2,3,0,1] row_mask:0xf bank_mask:0xf
	s_nop 1
	v_add_f32_dpp v129, v129, v129 quad_perm:[1,0,3,2] row_mask:0xf bank_mask:0xf
	v_fmamk_f32 v129, v129, 0x3a800000, v234
	v_rsq_f32_e32 v129, v129
	s_nop 0
	v_mov_b32_e32 v196, v129
	v_pk_mul_f32 v[126:127], v[126:127], v[196:197] op_sel_hi:[1,0]
	v_pk_mul_f32 v[124:125], v[124:125], v[196:197] op_sel_hi:[1,0]
	v_pk_mul_f32 v[122:123], v[122:123], v[196:197] op_sel_hi:[1,0]
	v_pk_mul_f32 v[120:121], v[120:121], v[196:197] op_sel_hi:[1,0]
	v_pk_mul_f32 v[118:119], v[118:119], v[196:197] op_sel_hi:[1,0]
	v_pk_mul_f32 v[116:117], v[116:117], v[196:197] op_sel_hi:[1,0]
	v_pk_mul_f32 v[114:115], v[114:115], v[196:197] op_sel_hi:[1,0]
	v_pk_mul_f32 v[112:113], v[112:113], v[196:197] op_sel_hi:[1,0]
	v_pk_mul_f32 v[124:125], v[8:9], v[124:125]
	v_pk_mul_f32 v[126:127], v[10:11], v[126:127]
	v_pk_mul_f32 v[120:121], v[0:1], v[120:121]
	v_pk_mul_f32 v[122:123], v[2:3], v[122:123]
	v_pk_mul_f32 v[116:117], v[4:5], v[116:117]
	v_pk_mul_f32 v[118:119], v[6:7], v[118:119]
	v_pk_mul_f32 v[112:113], v[12:13], v[112:113]
	v_pk_mul_f32 v[114:115], v[14:15], v[114:115]
	v_pk_fma_f32 v[126:127], v[220:221], v[126:127], v[18:19]
	v_pk_fma_f32 v[124:125], v[222:223], v[124:125], v[16:17]
	v_pk_fma_f32 v[122:123], v[212:213], v[122:123], v[26:27]
	v_pk_fma_f32 v[120:121], v[214:215], v[120:121], v[24:25]
	v_pk_fma_f32 v[118:119], v[208:209], v[118:119], v[50:51]
	v_pk_fma_f32 v[116:117], v[210:211], v[116:117], v[48:49]
	v_pk_fma_f32 v[114:115], v[204:205], v[114:115], v[74:75]
	v_pk_fma_f32 v[112:113], v[206:207], v[112:113], v[72:73]
	v_cvt_pk_bf16_f32 v124, v124, v125
	v_cvt_pk_bf16_f32 v125, v126, v127
	v_cvt_pk_bf16_f32 v120, v120, v121
	v_cvt_pk_bf16_f32 v121, v122, v123
	v_cvt_pk_bf16_f32 v116, v116, v117
	v_cvt_pk_bf16_f32 v117, v118, v119
	v_cvt_pk_bf16_f32 v112, v112, v113
	v_cvt_pk_bf16_f32 v113, v114, v115
	global_store_dwordx2 v[194:195], v[124:125], off
	global_store_dwordx2 v[194:195], v[120:121], off offset:512
	global_store_dwordx2 v[194:195], v[116:117], off offset:1024
	global_store_dwordx2 v[194:195], v[112:113], off offset:1536
	s_or_b64 exec, exec, s[6:7]
	v_cmp_lt_i32_e32 vcc, v184, v226
	s_and_saveexec_b64 s[6:7], vcc
	s_cbranch_execnz .LBB0_1168

.LBB0_1165:
	s_or_b64 exec, exec, s[40:41]
	v_mov_b32_e32 v100, v93
	v_mov_b32_e32 v101, v89
	v_mov_b32_e32 v98, v92
	v_mov_b32_e32 v99, v88
	v_pk_mul_f32 v[100:101], v[100:101], v[100:101]
	v_mov_b32_e32 v102, v85
	v_pk_fma_f32 v[98:99], v[98:99], v[98:99], v[100:101]
	v_mov_b32_e32 v100, v94
	v_mov_b32_e32 v101, v90
	v_pk_fma_f32 v[98:99], v[100:101], v[100:101], v[98:99]
	v_mov_b32_e32 v100, v95
	v_mov_b32_e32 v101, v91
	v_mov_b32_e32 v103, v81
	v_pk_fma_f32 v[98:99], v[100:101], v[100:101], v[98:99]
	v_mov_b32_e32 v100, v84
	v_mov_b32_e32 v101, v80
	v_pk_mul_f32 v[102:103], v[102:103], v[102:103]
	v_add_f32_e32 v98, v98, v99
	v_pk_fma_f32 v[100:101], v[100:101], v[100:101], v[102:103]
	v_mov_b32_e32 v102, v86
	v_mov_b32_e32 v103, v82
	v_pk_fma_f32 v[100:101], v[102:103], v[102:103], v[100:101]
	v_mov_b32_e32 v102, v87
	v_mov_b32_e32 v103, v83
	v_pk_fma_f32 v[100:101], v[102:103], v[102:103], v[100:101]
	v_lshl_add_u64 v[96:97], v[132:133], 0, v[96:97]
	v_add_f32_e32 v98, v98, v100
	v_add_f32_e32 v98, v98, v101
	ds_bpermute_b32 v99, v228, v98
	v_pk_add_f32 v[100:101], v[20:21], 1.0 op_sel_hi:[1,0]
	s_waitcnt lgkmcnt(0)
	v_add_f32_e32 v98, v98, v99
	ds_bpermute_b32 v99, v229, v98
	s_waitcnt lgkmcnt(0)
	v_add_f32_e32 v98, v98, v99
	s_nop 1
	v_add_f32_dpp v98, v98, v98 row_ror:8 row_mask:0xf bank_mask:0xf
	s_nop 1
	v_add_f32_dpp v98, v98, v98 row_ror:4 row_mask:0xf bank_mask:0xf
	s_nop 1
	v_add_f32_dpp v98, v98, v98 quad_perm:[2,3,0,1] row_mask:0xf bank_mask:0xf
	s_nop 1
	v_add_f32_dpp v98, v98, v98 quad_perm:[1,0,3,2] row_mask:0xf bank_mask:0xf
	v_fmamk_f32 v98, v98, 0x3a800000, v234
	v_rsq_f32_e32 v102, v98
	v_pk_add_f32 v[98:99], v[22:23], 1.0 op_sel_hi:[1,0]
	v_pk_mul_f32 v[94:95], v[94:95], v[102:103] op_sel_hi:[1,0]
	v_pk_mul_f32 v[92:93], v[92:93], v[102:103] op_sel_hi:[1,0]
	v_pk_mul_f32 v[94:95], v[10:11], v[94:95]
	v_pk_mul_f32 v[92:93], v[8:9], v[92:93]
	v_pk_fma_f32 v[94:95], v[98:99], v[94:95], v[18:19]
	v_pk_fma_f32 v[92:93], v[100:101], v[92:93], v[16:17]
	v_pk_mul_f32 v[90:91], v[90:91], v[102:103] op_sel_hi:[1,0]
	v_cvt_pk_bf16_f32 v92, v92, v93
	v_cvt_pk_bf16_f32 v93, v94, v95
	v_pk_mul_f32 v[88:89], v[88:89], v[102:103] op_sel_hi:[1,0]
	global_store_dwordx2 v[96:97], v[92:93], off
	v_pk_mul_f32 v[88:89], v[0:1], v[88:89]
	v_pk_mul_f32 v[90:91], v[2:3], v[90:91]
	v_pk_add_f32 v[92:93], v[30:31], 1.0 op_sel_hi:[1,0]
	v_pk_add_f32 v[94:95], v[28:29], 1.0 op_sel_hi:[1,0]
	v_pk_fma_f32 v[90:91], v[92:93], v[90:91], v[26:27]
	v_pk_fma_f32 v[88:89], v[94:95], v[88:89], v[24:25]
	v_pk_mul_f32 v[86:87], v[86:87], v[102:103] op_sel_hi:[1,0]
	v_cvt_pk_bf16_f32 v88, v88, v89
	v_cvt_pk_bf16_f32 v89, v90, v91
	v_pk_mul_f32 v[84:85], v[84:85], v[102:103] op_sel_hi:[1,0]
	global_store_dwordx2 v[96:97], v[88:89], off offset:512
	v_pk_mul_f32 v[84:85], v[4:5], v[84:85]
	v_pk_mul_f32 v[86:87], v[6:7], v[86:87]
	v_pk_add_f32 v[88:89], v[54:55], 1.0 op_sel_hi:[1,0]
	v_pk_add_f32 v[90:91], v[52:53], 1.0 op_sel_hi:[1,0]
	v_pk_fma_f32 v[86:87], v[88:89], v[86:87], v[50:51]
	v_pk_fma_f32 v[84:85], v[90:91], v[84:85], v[48:49]
	v_pk_mul_f32 v[82:83], v[82:83], v[102:103] op_sel_hi:[1,0]
	v_cvt_pk_bf16_f32 v84, v84, v85
	v_cvt_pk_bf16_f32 v85, v86, v87
	v_pk_mul_f32 v[80:81], v[80:81], v[102:103] op_sel_hi:[1,0]
	global_store_dwordx2 v[96:97], v[84:85], off offset:1024
	v_pk_mul_f32 v[80:81], v[12:13], v[80:81]
	v_pk_mul_f32 v[82:83], v[14:15], v[82:83]
	v_pk_add_f32 v[84:85], v[78:79], 1.0 op_sel_hi:[1,0]
	v_pk_add_f32 v[86:87], v[76:77], 1.0 op_sel_hi:[1,0]
	v_pk_fma_f32 v[82:83], v[84:85], v[82:83], v[74:75]
	v_pk_fma_f32 v[80:81], v[86:87], v[80:81], v[72:73]
	s_nop 0
	v_cvt_pk_bf16_f32 v80, v80, v81
	v_cvt_pk_bf16_f32 v81, v82, v83
	global_store_dwordx2 v[96:97], v[80:81], off offset:1536
	s_or_b64 exec, exec, s[6:7]
	v_cmp_lt_i32_e32 vcc, v164, v226
	s_and_saveexec_b64 s[6:7], vcc
	s_cbranch_execnz .LBB0_1180

.LBB0_1178:
	s_or_b64 exec, exec, s[40:41]
	v_mov_b32_e32 v116, v109
	v_mov_b32_e32 v117, v105
	v_mov_b32_e32 v114, v108
	v_mov_b32_e32 v115, v104
	v_pk_mul_f32 v[116:117], v[116:117], v[116:117]
	v_mov_b32_e32 v118, v101
	v_pk_fma_f32 v[114:115], v[114:115], v[114:115], v[116:117]
	v_mov_b32_e32 v116, v110
	v_mov_b32_e32 v117, v106
	v_pk_fma_f32 v[114:115], v[116:117], v[116:117], v[114:115]
	v_mov_b32_e32 v116, v111
	v_mov_b32_e32 v117, v107
	v_mov_b32_e32 v119, v97
	v_pk_fma_f32 v[114:115], v[116:117], v[116:117], v[114:115]
	v_mov_b32_e32 v116, v100
	v_mov_b32_e32 v117, v96
	v_pk_mul_f32 v[118:119], v[118:119], v[118:119]
	v_add_f32_e32 v114, v114, v115
	v_pk_fma_f32 v[116:117], v[116:117], v[116:117], v[118:119]
	v_mov_b32_e32 v118, v102
	v_mov_b32_e32 v119, v98
	v_pk_fma_f32 v[116:117], v[118:119], v[118:119], v[116:117]
	v_mov_b32_e32 v118, v103
	v_mov_b32_e32 v119, v99
	v_pk_fma_f32 v[116:117], v[118:119], v[118:119], v[116:117]
	v_lshl_add_u64 v[112:113], v[132:133], 0, v[112:113]
	v_add_f32_e32 v114, v114, v116
	v_add_f32_e32 v114, v114, v117
	ds_bpermute_b32 v115, v228, v114
	v_pk_add_f32 v[116:117], v[20:21], 1.0 op_sel_hi:[1,0]
	s_waitcnt lgkmcnt(0)
	v_add_f32_e32 v114, v114, v115
	ds_bpermute_b32 v115, v229, v114
	s_waitcnt lgkmcnt(0)
	v_add_f32_e32 v114, v114, v115
	s_nop 1
	v_add_f32_dpp v114, v114, v114 row_ror:8 row_mask:0xf bank_mask:0xf
	s_nop 1
	v_add_f32_dpp v114, v114, v114 row_ror:4 row_mask:0xf bank_mask:0xf
	s_nop 1
	v_add_f32_dpp v114, v114, v114 quad_perm:[2,3,0,1] row_mask:0xf bank_mask:0xf
	s_nop 1
	v_add_f32_dpp v114, v114, v114 quad_perm:[1,0,3,2] row_mask:0xf bank_mask:0xf
	v_fmamk_f32 v114, v114, 0x3a800000, v234
	v_rsq_f32_e32 v118, v114
	v_pk_add_f32 v[114:115], v[22:23], 1.0 op_sel_hi:[1,0]
	v_pk_mul_f32 v[110:111], v[110:111], v[118:119] op_sel_hi:[1,0]
	v_pk_mul_f32 v[108:109], v[108:109], v[118:119] op_sel_hi:[1,0]
	v_pk_mul_f32 v[110:111], v[10:11], v[110:111]
	v_pk_mul_f32 v[108:109], v[8:9], v[108:109]
	v_pk_fma_f32 v[110:111], v[114:115], v[110:111], v[18:19]
	v_pk_fma_f32 v[108:109], v[116:117], v[108:109], v[16:17]
	v_pk_mul_f32 v[106:107], v[106:107], v[118:119] op_sel_hi:[1,0]
	v_cvt_pk_bf16_f32 v108, v108, v109
	v_cvt_pk_bf16_f32 v109, v110, v111
	v_pk_mul_f32 v[104:105], v[104:105], v[118:119] op_sel_hi:[1,0]
	global_store_dwordx2 v[112:113], v[108:109], off
	v_pk_mul_f32 v[104:105], v[0:1], v[104:105]
	v_pk_mul_f32 v[106:107], v[2:3], v[106:107]
	v_pk_add_f32 v[108:109], v[30:31], 1.0 op_sel_hi:[1,0]
	v_pk_add_f32 v[110:111], v[28:29], 1.0 op_sel_hi:[1,0]
	v_pk_fma_f32 v[106:107], v[108:109], v[106:107], v[26:27]
	v_pk_fma_f32 v[104:105], v[110:111], v[104:105], v[24:25]
	v_pk_mul_f32 v[102:103], v[102:103], v[118:119] op_sel_hi:[1,0]
	v_cvt_pk_bf16_f32 v104, v104, v105
	v_cvt_pk_bf16_f32 v105, v106, v107
	v_pk_mul_f32 v[100:101], v[100:101], v[118:119] op_sel_hi:[1,0]
	global_store_dwordx2 v[112:113], v[104:105], off offset:512
	v_pk_mul_f32 v[100:101], v[4:5], v[100:101]
	v_pk_mul_f32 v[102:103], v[6:7], v[102:103]
	v_pk_add_f32 v[104:105], v[54:55], 1.0 op_sel_hi:[1,0]
	v_pk_add_f32 v[106:107], v[52:53], 1.0 op_sel_hi:[1,0]
	v_pk_fma_f32 v[102:103], v[104:105], v[102:103], v[50:51]
	v_pk_fma_f32 v[100:101], v[106:107], v[100:101], v[48:49]
	v_pk_mul_f32 v[98:99], v[98:99], v[118:119] op_sel_hi:[1,0]
	v_cvt_pk_bf16_f32 v100, v100, v101
	v_cvt_pk_bf16_f32 v101, v102, v103
	v_pk_mul_f32 v[96:97], v[96:97], v[118:119] op_sel_hi:[1,0]
	global_store_dwordx2 v[112:113], v[100:101], off offset:1024
	v_pk_mul_f32 v[96:97], v[12:13], v[96:97]
	v_pk_mul_f32 v[98:99], v[14:15], v[98:99]
	v_pk_add_f32 v[100:101], v[78:79], 1.0 op_sel_hi:[1,0]
	v_pk_add_f32 v[102:103], v[76:77], 1.0 op_sel_hi:[1,0]
	v_pk_fma_f32 v[98:99], v[100:101], v[98:99], v[74:75]
	v_pk_fma_f32 v[96:97], v[102:103], v[96:97], v[72:73]
	s_nop 0
	v_cvt_pk_bf16_f32 v96, v96, v97
	v_cvt_pk_bf16_f32 v97, v98, v99
	global_store_dwordx2 v[112:113], v[96:97], off offset:1536
	s_or_b64 exec, exec, s[6:7]
	v_cmp_lt_i32_e32 vcc, v174, v226
	s_and_saveexec_b64 s[6:7], vcc
	s_cbranch_execnz .LBB0_1155

.LBB0_1190:
	s_or_b64 exec, exec, s[40:41]
	v_mov_b32_e32 v84, v69
	v_mov_b32_e32 v85, v65
	v_mov_b32_e32 v82, v68
	v_mov_b32_e32 v83, v64
	v_pk_mul_f32 v[84:85], v[84:85], v[84:85]
	v_mov_b32_e32 v86, v61
	v_pk_fma_f32 v[82:83], v[82:83], v[82:83], v[84:85]
	v_mov_b32_e32 v84, v70
	v_mov_b32_e32 v85, v66
	v_pk_fma_f32 v[82:83], v[84:85], v[84:85], v[82:83]
	v_mov_b32_e32 v84, v71
	v_mov_b32_e32 v85, v67
	v_mov_b32_e32 v87, v57
	v_pk_fma_f32 v[82:83], v[84:85], v[84:85], v[82:83]
	v_mov_b32_e32 v84, v60
	v_mov_b32_e32 v85, v56
	v_pk_mul_f32 v[86:87], v[86:87], v[86:87]
	v_add_f32_e32 v82, v82, v83
	v_pk_fma_f32 v[84:85], v[84:85], v[84:85], v[86:87]
	v_mov_b32_e32 v86, v62
	v_mov_b32_e32 v87, v58
	v_pk_fma_f32 v[84:85], v[86:87], v[86:87], v[84:85]
	v_mov_b32_e32 v86, v63
	v_mov_b32_e32 v87, v59
	v_pk_fma_f32 v[84:85], v[86:87], v[86:87], v[84:85]
	v_lshl_add_u64 v[80:81], v[132:133], 0, v[80:81]
	v_add_f32_e32 v82, v82, v84
	v_add_f32_e32 v82, v82, v85
	ds_bpermute_b32 v83, v228, v82
	v_pk_add_f32 v[84:85], v[20:21], 1.0 op_sel_hi:[1,0]
	s_waitcnt lgkmcnt(0)
	v_add_f32_e32 v82, v82, v83
	ds_bpermute_b32 v83, v229, v82
	s_waitcnt lgkmcnt(0)
	v_add_f32_e32 v82, v82, v83
	s_nop 1
	v_add_f32_dpp v82, v82, v82 row_ror:8 row_mask:0xf bank_mask:0xf
	s_nop 1
	v_add_f32_dpp v82, v82, v82 row_ror:4 row_mask:0xf bank_mask:0xf
	s_nop 1
	v_add_f32_dpp v82, v82, v82 quad_perm:[2,3,0,1] row_mask:0xf bank_mask:0xf
	s_nop 1
	v_add_f32_dpp v82, v82, v82 quad_perm:[1,0,3,2] row_mask:0xf bank_mask:0xf
	v_fmamk_f32 v82, v82, 0x3a800000, v234
	v_rsq_f32_e32 v86, v82
	v_pk_add_f32 v[82:83], v[22:23], 1.0 op_sel_hi:[1,0]
	v_pk_mul_f32 v[70:71], v[70:71], v[86:87] op_sel_hi:[1,0]
	v_pk_mul_f32 v[68:69], v[68:69], v[86:87] op_sel_hi:[1,0]
	v_pk_mul_f32 v[70:71], v[10:11], v[70:71]
	v_pk_mul_f32 v[68:69], v[8:9], v[68:69]
	v_pk_fma_f32 v[70:71], v[82:83], v[70:71], v[18:19]
	v_pk_fma_f32 v[68:69], v[84:85], v[68:69], v[16:17]
	v_pk_mul_f32 v[66:67], v[66:67], v[86:87] op_sel_hi:[1,0]
	v_cvt_pk_bf16_f32 v68, v68, v69
	v_cvt_pk_bf16_f32 v69, v70, v71
	v_pk_mul_f32 v[64:65], v[64:65], v[86:87] op_sel_hi:[1,0]
	global_store_dwordx2 v[80:81], v[68:69], off
	v_pk_mul_f32 v[64:65], v[0:1], v[64:65]
	v_pk_mul_f32 v[66:67], v[2:3], v[66:67]
	v_pk_add_f32 v[68:69], v[30:31], 1.0 op_sel_hi:[1,0]
	v_pk_add_f32 v[70:71], v[28:29], 1.0 op_sel_hi:[1,0]
	v_pk_fma_f32 v[66:67], v[68:69], v[66:67], v[26:27]
	v_pk_fma_f32 v[64:65], v[70:71], v[64:65], v[24:25]
	v_pk_mul_f32 v[62:63], v[62:63], v[86:87] op_sel_hi:[1,0]
	v_cvt_pk_bf16_f32 v64, v64, v65
	v_cvt_pk_bf16_f32 v65, v66, v67
	v_pk_mul_f32 v[60:61], v[60:61], v[86:87] op_sel_hi:[1,0]
	global_store_dwordx2 v[80:81], v[64:65], off offset:512
	v_pk_mul_f32 v[60:61], v[4:5], v[60:61]
	v_pk_mul_f32 v[62:63], v[6:7], v[62:63]
	v_pk_add_f32 v[64:65], v[54:55], 1.0 op_sel_hi:[1,0]
	v_pk_add_f32 v[66:67], v[52:53], 1.0 op_sel_hi:[1,0]
	v_pk_fma_f32 v[62:63], v[64:65], v[62:63], v[50:51]
	v_pk_fma_f32 v[60:61], v[66:67], v[60:61], v[48:49]
	v_pk_mul_f32 v[58:59], v[58:59], v[86:87] op_sel_hi:[1,0]
	v_cvt_pk_bf16_f32 v60, v60, v61
	v_cvt_pk_bf16_f32 v61, v62, v63
	v_pk_mul_f32 v[56:57], v[56:57], v[86:87] op_sel_hi:[1,0]
	global_store_dwordx2 v[80:81], v[60:61], off offset:1024
	v_pk_mul_f32 v[56:57], v[12:13], v[56:57]
	v_pk_mul_f32 v[58:59], v[14:15], v[58:59]
	v_pk_add_f32 v[60:61], v[78:79], 1.0 op_sel_hi:[1,0]
	v_pk_add_f32 v[62:63], v[76:77], 1.0 op_sel_hi:[1,0]
	v_pk_fma_f32 v[58:59], v[60:61], v[58:59], v[74:75]
	v_pk_fma_f32 v[56:57], v[62:63], v[56:57], v[72:73]
	s_nop 0
	v_cvt_pk_bf16_f32 v56, v56, v57
	v_cvt_pk_bf16_f32 v57, v58, v59
	global_store_dwordx2 v[80:81], v[56:57], off offset:1536
	s_or_b64 exec, exec, s[6:7]
	v_cmp_lt_i32_e32 vcc, v154, v226
	s_and_saveexec_b64 s[6:7], vcc
	s_cbranch_execz .LBB0_1131

.LBB0_1429:
	v_ashrrev_i32_e32 v17, 31, v16
	v_lshlrev_b64 v[18:19], 13, v[16:17]
	v_lshl_add_u64 v[18:19], s[60:61], 0, v[18:19]
	v_lshl_add_u64 v[18:19], v[18:19], 0, v[148:149]
	v_lshlrev_b64 v[168:169], 11, v[16:17]
	v_lshl_add_u64 v[20:21], v[18:19], 0, s[6:7]
	v_lshl_add_u64 v[22:23], v[152:153], 0, v[168:169]
	s_waitcnt vmcnt(3)
	v_lshl_add_u64 v[24:25], v[154:155], 0, v[168:169]
	v_add_co_u32_e32 v18, vcc, s19, v18
	global_load_dwordx4 v[180:183], v[22:23], off offset:16
	global_load_dwordx4 v[140:143], v[24:25], off
	v_addc_co_u32_e32 v19, vcc, 0, v19, vcc
	global_load_dwordx4 v[184:187], v[24:25], off offset:16
	global_load_dwordx4 v[136:139], v[18:19], off offset:2048
	global_load_dwordx4 v[144:147], v[22:23], off
	global_load_dwordx4 v[188:191], v[20:21], off offset:16
	v_add_u32_e32 v166, s33, v16
	v_min_i32_e32 v18, 0x2fff, v166
	v_ashrrev_i32_e32 v19, 31, v18
	v_lshlrev_b64 v[20:21], 13, v[18:19]
	v_lshl_add_u64 v[20:21], s[60:61], 0, v[20:21]
	v_lshl_add_u64 v[20:21], v[20:21], 0, v[148:149]
	v_lshlrev_b64 v[18:19], 11, v[18:19]
	v_lshl_add_u64 v[22:23], v[20:21], 0, s[6:7]
	v_lshl_add_u64 v[24:25], v[152:153], 0, v[18:19]
	v_lshl_add_u64 v[18:19], v[154:155], 0, v[18:19]
	v_add_co_u32_e32 v20, vcc, s19, v20
	v_add_u32_e32 v164, s16, v16
	global_load_dwordx4 v[124:127], v[24:25], off offset:16
	global_load_dwordx4 v[116:119], v[18:19], off
	v_addc_co_u32_e32 v21, vcc, 0, v21, vcc
	global_load_dwordx4 v[128:131], v[18:19], off offset:16
	global_load_dwordx4 v[112:115], v[20:21], off offset:2048
	global_load_dwordx4 v[120:123], v[24:25], off
	global_load_dwordx4 v[132:135], v[22:23], off offset:16
	v_min_i32_e32 v18, 0x2fff, v164
	v_ashrrev_i32_e32 v19, 31, v18
	v_lshlrev_b64 v[20:21], 13, v[18:19]
	v_lshl_add_u64 v[20:21], s[60:61], 0, v[20:21]
	v_lshl_add_u64 v[20:21], v[20:21], 0, v[148:149]
	v_lshlrev_b64 v[18:19], 11, v[18:19]
	v_lshl_add_u64 v[22:23], v[20:21], 0, s[6:7]
	v_lshl_add_u64 v[24:25], v[152:153], 0, v[18:19]
	v_lshl_add_u64 v[18:19], v[154:155], 0, v[18:19]
	v_add_co_u32_e32 v20, vcc, s19, v20
	v_add_u32_e32 v162, s71, v16
	global_load_dwordx4 v[100:103], v[24:25], off offset:16
	global_load_dwordx4 v[92:95], v[18:19], off
	v_addc_co_u32_e32 v21, vcc, 0, v21, vcc
	global_load_dwordx4 v[104:107], v[18:19], off offset:16
	global_load_dwordx4 v[88:91], v[20:21], off offset:2048
	global_load_dwordx4 v[96:99], v[24:25], off
	global_load_dwordx4 v[108:111], v[22:23], off offset:16
	v_min_i32_e32 v18, 0x2fff, v162
	v_ashrrev_i32_e32 v19, 31, v18
	v_lshlrev_b64 v[20:21], 13, v[18:19]
	v_lshl_add_u64 v[20:21], s[60:61], 0, v[20:21]
	v_lshl_add_u64 v[20:21], v[20:21], 0, v[148:149]
	v_lshlrev_b64 v[18:19], 11, v[18:19]
	v_lshl_add_u64 v[22:23], v[20:21], 0, s[6:7]
	v_lshl_add_u64 v[24:25], v[152:153], 0, v[18:19]
	v_lshl_add_u64 v[18:19], v[154:155], 0, v[18:19]
	v_add_co_u32_e32 v20, vcc, s19, v20
	v_add_u32_e32 v160, s17, v16
	global_load_dwordx4 v[76:79], v[24:25], off offset:16
	global_load_dwordx4 v[68:71], v[18:19], off
	v_addc_co_u32_e32 v21, vcc, 0, v21, vcc
	global_load_dwordx4 v[80:83], v[18:19], off offset:16
	global_load_dwordx4 v[64:67], v[20:21], off offset:2048
	global_load_dwordx4 v[72:75], v[24:25], off
	global_load_dwordx4 v[84:87], v[22:23], off offset:16
	v_min_i32_e32 v18, 0x2fff, v160
	v_ashrrev_i32_e32 v19, 31, v18
	v_lshlrev_b64 v[20:21], 13, v[18:19]
	v_lshl_add_u64 v[20:21], s[60:61], 0, v[20:21]
	v_add_u32_e32 v158, s72, v16
	v_lshl_add_u64 v[20:21], v[20:21], 0, v[148:149]
	v_lshlrev_b64 v[18:19], 11, v[18:19]
	v_min_i32_e32 v16, 0x2fff, v158
	v_lshl_add_u64 v[22:23], v[20:21], 0, s[6:7]
	v_lshl_add_u64 v[24:25], v[152:153], 0, v[18:19]
	v_lshl_add_u64 v[18:19], v[154:155], 0, v[18:19]
	v_add_co_u32_e32 v20, vcc, s19, v20
	v_ashrrev_i32_e32 v17, 31, v16
	global_load_dwordx4 v[56:59], v[24:25], off offset:16
	global_load_dwordx4 v[44:47], v[18:19], off
	v_addc_co_u32_e32 v21, vcc, 0, v21, vcc
	global_load_dwordx4 v[52:55], v[18:19], off offset:16
	global_load_dwordx4 v[40:43], v[20:21], off offset:2048
	global_load_dwordx4 v[48:51], v[24:25], off
	global_load_dwordx4 v[60:63], v[22:23], off offset:16
	v_lshlrev_b64 v[18:19], 13, v[16:17]
	v_lshl_add_u64 v[18:19], s[60:61], 0, v[18:19]
	v_lshl_add_u64 v[18:19], v[18:19], 0, v[148:149]
	s_waitcnt vmcnt(32)
	v_lshl_add_u64 v[36:37], v[18:19], 0, s[6:7]
	v_lshlrev_b64 v[16:17], 11, v[16:17]
	v_add_co_u32_e32 v18, vcc, s19, v18
	v_lshl_add_u64 v[24:25], v[152:153], 0, v[16:17]
	s_waitcnt vmcnt(29)
	v_lshlrev_b32_e32 v175, 16, v183
	s_waitcnt vmcnt(27)
	v_lshlrev_b32_e32 v173, 16, v187
	v_and_b32_e32 v172, 0xffff0000, v187
	v_and_b32_e32 v174, 0xffff0000, v183
	s_waitcnt vmcnt(24)
	v_and_b32_e32 v170, 0xffff0000, v191
	v_lshlrev_b32_e32 v3, 16, v191
	v_pk_add_f32 v[172:173], v[172:173], v[174:175]
	v_lshlrev_b32_e32 v174, 16, v190
	v_and_b32_e32 v175, 0xffff0000, v190
	v_lshlrev_b32_e32 v190, 16, v186
	v_and_b32_e32 v191, 0xffff0000, v186
	v_lshlrev_b32_e32 v186, 16, v182
	v_and_b32_e32 v187, 0xffff0000, v182
	v_pk_add_f32 v[182:183], v[186:187], v[190:191]
	v_lshlrev_b32_e32 v190, 16, v189
	v_and_b32_e32 v191, 0xffff0000, v189
	v_mul_f32_e32 v156, 0xbfb8aa3b, v190
	v_exp_f32_e32 v156, v156
	v_mul_f32_e32 v159, 0xbfb8aa3b, v191
	v_exp_f32_e32 v159, v159
	v_lshl_add_u64 v[16:17], v[154:155], 0, v[16:17]
	v_add_f32_e32 v156, 1.0, v156
	v_rcp_f32_e32 v198, v156
	v_add_f32_e32 v156, 1.0, v159
	v_rcp_f32_e32 v199, v156
	v_addc_co_u32_e32 v19, vcc, 0, v19, vcc
	global_load_dwordx4 v[32:35], v[24:25], off offset:16
	global_load_dwordx4 v[20:23], v[16:17], off
	v_pk_mul_f32 v[190:191], v[198:199], v[190:191]
	v_lshlrev_b32_e32 v198, 16, v188
	v_and_b32_e32 v199, 0xffff0000, v188
	v_mul_f32_e32 v156, 0xbfb8aa3b, v198
	v_exp_f32_e32 v156, v156
	v_mul_f32_e32 v159, 0xbfb8aa3b, v199
	v_exp_f32_e32 v159, v159
	global_load_dwordx4 v[28:31], v[16:17], off offset:16
	s_nop 0
	global_load_dwordx4 v[16:19], v[18:19], off offset:2048
	s_nop 0
	global_load_dwordx4 v[24:27], v[24:25], off
	s_nop 0
	global_load_dwordx4 v[36:39], v[36:37], off offset:16
	v_add_f32_e32 v156, 1.0, v156
	v_rcp_f32_e32 v200, v156
	v_add_f32_e32 v156, 1.0, v159
	v_rcp_f32_e32 v201, v156
	v_lshlrev_b32_e32 v194, 16, v185
	v_and_b32_e32 v195, 0xffff0000, v185
	v_lshlrev_b32_e32 v188, 16, v184
	v_and_b32_e32 v189, 0xffff0000, v184
	v_lshlrev_b32_e32 v184, 16, v180
	v_and_b32_e32 v185, 0xffff0000, v180
	v_lshlrev_b32_e32 v196, 16, v181
	v_and_b32_e32 v197, 0xffff0000, v181
	v_pk_add_f32 v[180:181], v[184:185], v[188:189]
	v_pk_mul_f32 v[188:189], v[200:201], v[198:199]
	v_lshlrev_b32_e32 v198, 16, v139
	v_and_b32_e32 v199, 0xffff0000, v139
	v_mul_f32_e32 v139, 0xbfb8aa3b, v198
	v_lshlrev_b32_e32 v200, 16, v143
	v_and_b32_e32 v201, 0xffff0000, v143
	v_exp_f32_e32 v139, v139
	v_mul_f32_e32 v143, 0xbfb8aa3b, v199
	v_exp_f32_e32 v143, v143
	v_lshlrev_b32_e32 v208, 16, v141
	v_add_f32_e32 v139, 1.0, v139
	v_rcp_f32_e32 v204, v139
	v_add_f32_e32 v139, 1.0, v143
	v_rcp_f32_e32 v205, v139
	v_and_b32_e32 v209, 0xffff0000, v141
	v_lshlrev_b32_e32 v214, 16, v140
	v_and_b32_e32 v215, 0xffff0000, v140
	v_lshlrev_b32_e32 v140, 16, v144
	v_and_b32_e32 v141, 0xffff0000, v144
	v_lshlrev_b32_e32 v210, 16, v145
	v_and_b32_e32 v211, 0xffff0000, v145
	v_pk_add_f32 v[140:141], v[140:141], v[214:215]
	v_pk_mul_f32 v[198:199], v[204:205], v[198:199]
	v_lshlrev_b32_e32 v204, 16, v138
	v_and_b32_e32 v205, 0xffff0000, v138
	v_lshlrev_b32_e32 v138, 16, v142
	v_and_b32_e32 v139, 0xffff0000, v142
	v_lshlrev_b32_e32 v142, 16, v146
	v_and_b32_e32 v143, 0xffff0000, v146
	v_pk_add_f32 v[208:209], v[210:211], v[208:209]
	v_pk_mul_f32 v[144:145], v[140:141], v[140:141]
	v_pk_add_f32 v[138:139], v[142:143], v[138:139]
	v_mul_f32_e32 v142, 0xbfb8aa3b, v204
	v_pk_mul_f32 v[210:211], v[208:209], v[208:209]
	v_add_f32_e32 v144, v144, v145
	v_exp_f32_e32 v146, v142
	v_mul_f32_e32 v142, 0xbfb8aa3b, v205
	v_add_f32_e32 v144, v210, v144
	v_lshlrev_b32_e32 v202, 16, v147
	v_and_b32_e32 v203, 0xffff0000, v147
	v_exp_f32_e32 v147, v142
	v_pk_mul_f32 v[142:143], v[138:139], v[138:139]
	v_add_f32_e32 v144, v211, v144
	v_pk_add_f32 v[200:201], v[202:203], v[200:201]
	v_add_f32_e32 v142, v142, v144
	v_pk_mul_f32 v[202:203], v[200:201], v[200:201]
	v_add_f32_e32 v142, v143, v142
	v_add_f32_e32 v142, v202, v142
	v_pk_mul_f32 v[184:185], v[180:181], v[180:181]
	v_add_f32_e32 v142, v203, v142
	v_pk_add_f32 v[194:195], v[196:197], v[194:195]
	v_add_f32_e32 v142, v184, v142
	v_pk_mul_f32 v[196:197], v[194:195], v[194:195]
	v_lshlrev_b32_e32 v206, 16, v137
	v_add_f32_e32 v142, v185, v142
	v_and_b32_e32 v207, 0xffff0000, v137
	v_mul_f32_e32 v137, 0xbfb8aa3b, v206
	v_add_f32_e32 v142, v196, v142
	v_pk_mul_f32 v[186:187], v[182:183], v[182:183]
	v_exp_f32_e32 v137, v137
	v_add_f32_e32 v142, v197, v142
	v_add_f32_e32 v142, v186, v142
	v_pk_mul_f32 v[192:193], v[172:173], v[172:173]
	v_add_f32_e32 v142, v187, v142
	v_add_f32_e32 v142, v193, v142
	v_add_f32_e32 v137, 1.0, v137
	v_add_f32_e32 v144, v192, v142
	v_rcp_f32_e32 v212, v137
	v_mul_f32_e32 v137, 0xbfb8aa3b, v207
	ds_bpermute_b32 v145, v177, v144
	v_exp_f32_e32 v137, v137
	v_lshlrev_b32_e32 v142, 16, v136
	v_and_b32_e32 v143, 0xffff0000, v136
	v_add_f32_e32 v146, 1.0, v146
	v_add_f32_e32 v137, 1.0, v137
	s_waitcnt lgkmcnt(0)
	v_add_f32_e32 v136, v144, v145
	v_rcp_f32_e32 v213, v137
	ds_bpermute_b32 v137, v178, v136
	v_mul_f32_e32 v144, 0xbfb8aa3b, v142
	v_exp_f32_e32 v144, v144
	v_mul_f32_e32 v145, 0xbfb8aa3b, v143
	v_exp_f32_e32 v145, v145
	s_waitcnt lgkmcnt(0)
	v_add_f32_e32 v156, v136, v137
	ds_bpermute_b32 v159, v179, v156
	v_add_f32_e32 v136, 1.0, v144
	v_add_f32_e32 v137, 1.0, v145
	v_rcp_f32_e32 v136, v136
	v_rcp_f32_e32 v137, v137
	s_waitcnt lgkmcnt(0)
	v_add_f32_e32 v144, v156, v159
	v_fmamk_f32 v144, v144, 0x3c000000, v176
	v_add_f32_e32 v147, 1.0, v147
	v_pk_mul_f32 v[136:137], v[136:137], v[142:143]
	v_rsq_f32_e32 v156, v144
	v_rcp_f32_e32 v146, v146
	v_rcp_f32_e32 v147, v147
	v_mov_b32_e32 v142, v156
	v_pk_mul_f32 v[140:141], v[140:141], v[142:143] op_sel_hi:[1,0]
	v_pk_mul_f32 v[138:139], v[138:139], v[142:143] op_sel_hi:[1,0]
	v_pk_mul_f32 v[140:141], v[12:13], v[140:141]
	v_pk_mul_f32 v[144:145], v[146:147], v[204:205]
	v_pk_mul_f32 v[136:137], v[136:137], v[140:141]
	v_pk_mul_f32 v[140:141], v[208:209], v[142:143] op_sel_hi:[1,0]
	v_pk_mul_f32 v[146:147], v[212:213], v[206:207]
	v_pk_mul_f32 v[140:141], v[14:15], v[140:141]
	v_pk_mul_f32 v[138:139], v[8:9], v[138:139]
	v_pk_mul_f32 v[140:141], v[146:147], v[140:141]
	v_pk_mul_f32 v[138:139], v[144:145], v[138:139]
	v_pk_mul_f32 v[144:145], v[200:201], v[142:143] op_sel_hi:[1,0]
	v_pk_mul_f32 v[146:147], v[180:181], v[142:143] op_sel_hi:[1,0]
	v_pk_mul_f32 v[180:181], v[194:195], v[142:143] op_sel_hi:[1,0]
	v_mul_f32_e32 v143, 0xbfb8aa3b, v174
	v_exp_f32_e32 v143, v143
	v_mul_f32_e32 v156, 0xbfb8aa3b, v175
	v_exp_f32_e32 v156, v156
	v_mul_f32_e32 v171, v172, v142
	v_add_f32_e32 v143, 1.0, v143
	v_rcp_f32_e32 v184, v143
	v_add_f32_e32 v143, 1.0, v156
	v_rcp_f32_e32 v185, v143
	v_pk_mul_f32 v[182:183], v[182:183], v[142:143] op_sel_hi:[1,0]
	v_mul_f32_e32 v143, 0xbfb8aa3b, v3
	v_mul_f32_e32 v156, 0xbfb8aa3b, v170
	v_exp_f32_e32 v143, v143
	v_exp_f32_e32 v156, v156
	v_pk_mul_f32 v[144:145], v[10:11], v[144:145]
	v_pk_mul_f32 v[182:183], v[0:1], v[182:183]
	v_add_f32_e32 v143, 1.0, v143
	v_add_f32_e32 v156, 1.0, v156
	v_rcp_f32_e32 v143, v143
	v_rcp_f32_e32 v156, v156
	v_pk_mul_f32 v[174:175], v[184:185], v[174:175]
	v_mul_f32_e32 v159, v173, v142
	v_mul_f32_e32 v184, v143, v3
	v_pk_mul_f32 v[142:143], v[156:157], v[170:171]
	v_pk_mul_f32 v[144:145], v[198:199], v[144:145]
	v_pk_mul_f32 v[146:147], v[4:5], v[146:147]
	v_pk_mul_f32 v[180:181], v[6:7], v[180:181]
	v_pk_mul_f32 v[174:175], v[174:175], v[182:183]
	v_mul_f32_e32 v182, v2, v159
	v_mov_b32_e32 v185, v142
	v_mov_b32_e32 v183, v143
	v_pk_mul_f32 v[146:147], v[188:189], v[146:147]
	v_pk_mul_f32 v[180:181], v[190:191], v[180:181]
	v_cvt_pk_bf16_f32 v136, v136, v137
	v_cvt_pk_bf16_f32 v137, v140, v141
	v_cvt_pk_bf16_f32 v138, v138, v139
	v_cvt_pk_bf16_f32 v139, v144, v145
	v_lshl_add_u64 v[140:141], v[150:151], 0, v[168:169]
	v_pk_mul_f32 v[142:143], v[184:185], v[182:183]
	global_store_dwordx4 v[140:141], v[136:139], off
	v_cmp_gt_i32_e32 vcc, s3, v166
	s_nop 0
	v_cvt_pk_bf16_f32 v136, v146, v147
	v_cvt_pk_bf16_f32 v137, v180, v181
	v_cvt_pk_bf16_f32 v138, v174, v175
	v_cvt_pk_bf16_f32 v139, v142, v143
	global_store_dwordx4 v[140:141], v[136:139], off offset:16
	s_and_saveexec_b64 s[14:15], vcc
	s_cbranch_execz .LBB0_1431
	s_waitcnt vmcnt(29)
	v_lshlrev_b32_e32 v139, 16, v131
	v_lshlrev_b32_e32 v141, 16, v127
	v_and_b32_e32 v138, 0xffff0000, v131
	v_and_b32_e32 v140, 0xffff0000, v127
	s_waitcnt vmcnt(26)
	v_and_b32_e32 v136, 0xffff0000, v135
	v_lshlrev_b32_e32 v3, 16, v135
	v_pk_add_f32 v[138:139], v[138:139], v[140:141]
	v_lshlrev_b32_e32 v140, 16, v134
	v_and_b32_e32 v141, 0xffff0000, v134
	v_lshlrev_b32_e32 v134, 16, v130
	v_and_b32_e32 v135, 0xffff0000, v130
	v_lshlrev_b32_e32 v130, 16, v126
	v_and_b32_e32 v131, 0xffff0000, v126
	v_pk_add_f32 v[126:127], v[130:131], v[134:135]
	v_lshlrev_b32_e32 v134, 16, v133
	v_and_b32_e32 v135, 0xffff0000, v133
	v_lshlrev_b32_e32 v144, 16, v129
	v_and_b32_e32 v145, 0xffff0000, v129
	v_mul_f32_e32 v129, 0xbfb8aa3b, v134
	v_exp_f32_e32 v129, v129
	v_mul_f32_e32 v133, 0xbfb8aa3b, v135
	v_exp_f32_e32 v133, v133
	v_lshlrev_b32_e32 v146, 16, v125
	v_add_f32_e32 v129, 1.0, v129
	v_rcp_f32_e32 v168, v129
	v_add_f32_e32 v129, 1.0, v133
	v_rcp_f32_e32 v169, v129
	v_and_b32_e32 v147, 0xffff0000, v125
	v_and_b32_e32 v133, 0xffff0000, v128
	v_lshlrev_b32_e32 v182, 16, v117
	v_pk_mul_f32 v[134:135], v[168:169], v[134:135]
	v_lshlrev_b32_e32 v168, 16, v132
	v_and_b32_e32 v169, 0xffff0000, v132
	v_mul_f32_e32 v125, 0xbfb8aa3b, v168
	v_lshlrev_b32_e32 v132, 16, v128
	v_exp_f32_e32 v125, v125
	v_mul_f32_e32 v128, 0xbfb8aa3b, v169
	v_exp_f32_e32 v129, v128
	v_lshlrev_b32_e32 v128, 16, v124
	v_add_f32_e32 v125, 1.0, v125
	v_rcp_f32_e32 v170, v125
	v_add_f32_e32 v125, 1.0, v129
	v_rcp_f32_e32 v171, v125
	v_and_b32_e32 v129, 0xffff0000, v124
	v_pk_add_f32 v[124:125], v[128:129], v[132:133]
	v_and_b32_e32 v183, 0xffff0000, v117
	v_pk_mul_f32 v[132:133], v[170:171], v[168:169]
	v_lshlrev_b32_e32 v168, 16, v115
	v_and_b32_e32 v169, 0xffff0000, v115
	v_mul_f32_e32 v115, 0xbfb8aa3b, v168
	v_lshlrev_b32_e32 v170, 16, v119
	v_and_b32_e32 v171, 0xffff0000, v119
	v_exp_f32_e32 v115, v115
	v_mul_f32_e32 v119, 0xbfb8aa3b, v169
	v_exp_f32_e32 v119, v119
	v_lshlrev_b32_e32 v188, 16, v116
	v_add_f32_e32 v115, 1.0, v115
	v_rcp_f32_e32 v174, v115
	v_add_f32_e32 v115, 1.0, v119
	v_rcp_f32_e32 v175, v115
	v_and_b32_e32 v189, 0xffff0000, v116
	v_lshlrev_b32_e32 v116, 16, v120
	v_and_b32_e32 v117, 0xffff0000, v120
	v_lshlrev_b32_e32 v184, 16, v121
	v_and_b32_e32 v185, 0xffff0000, v121
	v_pk_add_f32 v[116:117], v[116:117], v[188:189]
	v_pk_mul_f32 v[168:169], v[174:175], v[168:169]
	v_lshlrev_b32_e32 v174, 16, v114
	v_and_b32_e32 v175, 0xffff0000, v114
	v_lshlrev_b32_e32 v114, 16, v118
	v_and_b32_e32 v115, 0xffff0000, v118
	v_lshlrev_b32_e32 v118, 16, v122
	v_and_b32_e32 v119, 0xffff0000, v122
	v_pk_add_f32 v[182:183], v[184:185], v[182:183]
	v_pk_mul_f32 v[120:121], v[116:117], v[116:117]
	v_pk_add_f32 v[114:115], v[118:119], v[114:115]
	v_mul_f32_e32 v118, 0xbfb8aa3b, v174
	v_pk_mul_f32 v[184:185], v[182:183], v[182:183]
	v_add_f32_e32 v120, v120, v121
	v_exp_f32_e32 v122, v118
	v_mul_f32_e32 v118, 0xbfb8aa3b, v175
	v_add_f32_e32 v120, v184, v120
	v_lshlrev_b32_e32 v172, 16, v123
	v_and_b32_e32 v173, 0xffff0000, v123
	v_exp_f32_e32 v123, v118
	v_pk_mul_f32 v[118:119], v[114:115], v[114:115]
	v_add_f32_e32 v120, v185, v120
	v_pk_add_f32 v[170:171], v[172:173], v[170:171]
	v_add_f32_e32 v118, v118, v120
	v_pk_mul_f32 v[172:173], v[170:171], v[170:171]
	v_add_f32_e32 v118, v119, v118
	v_add_f32_e32 v118, v172, v118
	v_pk_mul_f32 v[128:129], v[124:125], v[124:125]
	v_add_f32_e32 v118, v173, v118
	v_pk_add_f32 v[144:145], v[146:147], v[144:145]
	v_add_f32_e32 v118, v128, v118
	v_pk_mul_f32 v[146:147], v[144:145], v[144:145]
	v_lshlrev_b32_e32 v180, 16, v113
	v_add_f32_e32 v118, v129, v118
	v_and_b32_e32 v181, 0xffff0000, v113
	v_mul_f32_e32 v113, 0xbfb8aa3b, v180
	v_add_f32_e32 v118, v146, v118
	v_pk_mul_f32 v[130:131], v[126:127], v[126:127]
	v_exp_f32_e32 v113, v113
	v_add_f32_e32 v118, v147, v118
	v_add_f32_e32 v118, v130, v118
	v_pk_mul_f32 v[142:143], v[138:139], v[138:139]
	v_add_f32_e32 v118, v131, v118
	v_add_f32_e32 v118, v143, v118
	v_add_f32_e32 v113, 1.0, v113
	v_add_f32_e32 v120, v142, v118
	v_rcp_f32_e32 v186, v113
	v_mul_f32_e32 v113, 0xbfb8aa3b, v181
	ds_bpermute_b32 v121, v177, v120
	v_exp_f32_e32 v113, v113
	v_lshlrev_b32_e32 v118, 16, v112
	v_and_b32_e32 v119, 0xffff0000, v112
	v_add_f32_e32 v122, 1.0, v122
	v_add_f32_e32 v113, 1.0, v113
	s_waitcnt lgkmcnt(0)
	v_add_f32_e32 v112, v120, v121
	v_rcp_f32_e32 v187, v113
	ds_bpermute_b32 v113, v178, v112
	v_mul_f32_e32 v120, 0xbfb8aa3b, v118
	v_exp_f32_e32 v120, v120
	v_mul_f32_e32 v121, 0xbfb8aa3b, v119
	v_exp_f32_e32 v121, v121
	s_waitcnt lgkmcnt(0)
	v_add_f32_e32 v128, v112, v113
	ds_bpermute_b32 v129, v179, v128
	v_add_f32_e32 v112, 1.0, v120
	v_add_f32_e32 v113, 1.0, v121
	v_rcp_f32_e32 v112, v112
	v_rcp_f32_e32 v113, v113
	s_waitcnt lgkmcnt(0)
	v_add_f32_e32 v120, v128, v129
	v_fmamk_f32 v120, v120, 0x3c000000, v176
	v_add_f32_e32 v123, 1.0, v123
	v_pk_mul_f32 v[112:113], v[112:113], v[118:119]
	v_rsq_f32_e32 v128, v120
	v_rcp_f32_e32 v122, v122
	v_rcp_f32_e32 v123, v123
	v_ashrrev_i32_e32 v167, 31, v166
	v_mov_b32_e32 v118, v128
	v_pk_mul_f32 v[116:117], v[116:117], v[118:119] op_sel_hi:[1,0]
	v_pk_mul_f32 v[114:115], v[114:115], v[118:119] op_sel_hi:[1,0]
	v_pk_mul_f32 v[116:117], v[12:13], v[116:117]
	v_pk_mul_f32 v[120:121], v[122:123], v[174:175]
	v_pk_mul_f32 v[112:113], v[112:113], v[116:117]
	v_pk_mul_f32 v[116:117], v[182:183], v[118:119] op_sel_hi:[1,0]
	v_pk_mul_f32 v[122:123], v[186:187], v[180:181]
	v_pk_mul_f32 v[116:117], v[14:15], v[116:117]
	v_pk_mul_f32 v[114:115], v[8:9], v[114:115]
	v_pk_mul_f32 v[116:117], v[122:123], v[116:117]
	v_pk_mul_f32 v[114:115], v[120:121], v[114:115]
	v_pk_mul_f32 v[120:121], v[170:171], v[118:119] op_sel_hi:[1,0]
	v_pk_mul_f32 v[122:123], v[124:125], v[118:119] op_sel_hi:[1,0]
	v_pk_mul_f32 v[124:125], v[144:145], v[118:119] op_sel_hi:[1,0]
	v_mul_f32_e32 v119, 0xbfb8aa3b, v140
	v_exp_f32_e32 v119, v119
	v_mul_f32_e32 v128, 0xbfb8aa3b, v141
	v_exp_f32_e32 v129, v128
	v_mul_f32_e32 v137, v138, v118
	v_add_f32_e32 v119, 1.0, v119
	v_rcp_f32_e32 v128, v119
	v_add_f32_e32 v119, 1.0, v129
	v_rcp_f32_e32 v129, v119
	v_pk_mul_f32 v[126:127], v[126:127], v[118:119] op_sel_hi:[1,0]
	v_mul_f32_e32 v119, 0xbfb8aa3b, v3
	v_pk_mul_f32 v[126:127], v[0:1], v[126:127]
	v_pk_mul_f32 v[128:129], v[128:129], v[140:141]
	v_exp_f32_e32 v119, v119
	v_pk_mul_f32 v[126:127], v[128:129], v[126:127]
	v_mul_f32_e32 v128, 0xbfb8aa3b, v136
	v_exp_f32_e32 v128, v128
	v_add_f32_e32 v119, 1.0, v119
	v_rcp_f32_e32 v119, v119
	v_pk_mul_f32 v[120:121], v[10:11], v[120:121]
	v_add_f32_e32 v128, 1.0, v128
	v_rcp_f32_e32 v156, v128
	v_mul_f32_e32 v129, v139, v118
	v_mul_f32_e32 v130, v119, v3
	v_pk_mul_f32 v[120:121], v[168:169], v[120:121]
	v_pk_mul_f32 v[118:119], v[156:157], v[136:137]
	v_pk_mul_f32 v[122:123], v[4:5], v[122:123]
	v_pk_mul_f32 v[124:125], v[6:7], v[124:125]
	v_mul_f32_e32 v128, v2, v129
	v_mov_b32_e32 v131, v118
	v_mov_b32_e32 v129, v119
	v_cvt_pk_bf16_f32 v112, v112, v113
	v_cvt_pk_bf16_f32 v113, v116, v117
	v_lshlrev_b64 v[116:117], 11, v[166:167]
	v_pk_mul_f32 v[122:123], v[132:133], v[122:123]
	v_pk_mul_f32 v[124:125], v[134:135], v[124:125]
	v_cvt_pk_bf16_f32 v114, v114, v115
	v_cvt_pk_bf16_f32 v115, v120, v121
	v_lshl_add_u64 v[116:117], v[150:151], 0, v[116:117]
	v_pk_mul_f32 v[118:119], v[130:131], v[128:129]
	global_store_dwordx4 v[116:117], v[112:115], off
	s_nop 1
	v_cvt_pk_bf16_f32 v112, v122, v123
	v_cvt_pk_bf16_f32 v113, v124, v125
	v_cvt_pk_bf16_f32 v114, v126, v127
	v_cvt_pk_bf16_f32 v115, v118, v119
	global_store_dwordx4 v[116:117], v[112:115], off offset:16
.LBB0_1431:
	s_or_b64 exec, exec, s[14:15]
	v_add_u32_e32 v3, s33, v166
	v_cmp_gt_i32_e32 vcc, s3, v3
	s_and_saveexec_b64 s[14:15], vcc
	s_cbranch_execz .LBB0_1433
	s_waitcnt vmcnt(23)
	v_lshlrev_b32_e32 v115, 16, v107
	v_lshlrev_b32_e32 v117, 16, v103
	v_and_b32_e32 v114, 0xffff0000, v107
	v_and_b32_e32 v116, 0xffff0000, v103
	s_waitcnt vmcnt(20)
	v_and_b32_e32 v112, 0xffff0000, v111
	v_lshlrev_b32_e32 v113, 16, v111
	v_pk_add_f32 v[114:115], v[114:115], v[116:117]
	v_lshlrev_b32_e32 v116, 16, v110
	v_and_b32_e32 v117, 0xffff0000, v110
	v_lshlrev_b32_e32 v110, 16, v106
	v_and_b32_e32 v111, 0xffff0000, v106
	v_lshlrev_b32_e32 v106, 16, v102
	v_and_b32_e32 v107, 0xffff0000, v102
	v_pk_add_f32 v[102:103], v[106:107], v[110:111]
	v_lshlrev_b32_e32 v110, 16, v109
	v_and_b32_e32 v111, 0xffff0000, v109
	v_lshlrev_b32_e32 v120, 16, v105
	v_and_b32_e32 v121, 0xffff0000, v105
	v_mul_f32_e32 v105, 0xbfb8aa3b, v110
	v_exp_f32_e32 v105, v105
	v_mul_f32_e32 v109, 0xbfb8aa3b, v111
	v_exp_f32_e32 v109, v109
	v_lshlrev_b32_e32 v122, 16, v101
	v_add_f32_e32 v105, 1.0, v105
	v_rcp_f32_e32 v124, v105
	v_add_f32_e32 v105, 1.0, v109
	v_rcp_f32_e32 v125, v105
	v_and_b32_e32 v123, 0xffff0000, v101
	v_and_b32_e32 v109, 0xffff0000, v104
	v_lshlrev_b32_e32 v134, 16, v93
	v_pk_mul_f32 v[110:111], v[124:125], v[110:111]
	v_lshlrev_b32_e32 v124, 16, v108
	v_and_b32_e32 v125, 0xffff0000, v108
	v_mul_f32_e32 v101, 0xbfb8aa3b, v124
	v_lshlrev_b32_e32 v108, 16, v104
	v_exp_f32_e32 v101, v101
	v_mul_f32_e32 v104, 0xbfb8aa3b, v125
	v_exp_f32_e32 v105, v104
	v_lshlrev_b32_e32 v104, 16, v100
	v_add_f32_e32 v101, 1.0, v101
	v_rcp_f32_e32 v126, v101
	v_add_f32_e32 v101, 1.0, v105
	v_rcp_f32_e32 v127, v101
	v_and_b32_e32 v105, 0xffff0000, v100
	v_pk_add_f32 v[100:101], v[104:105], v[108:109]
	v_and_b32_e32 v135, 0xffff0000, v93
	v_pk_mul_f32 v[108:109], v[126:127], v[124:125]
	v_lshlrev_b32_e32 v124, 16, v91
	v_and_b32_e32 v125, 0xffff0000, v91
	v_mul_f32_e32 v91, 0xbfb8aa3b, v124
	v_lshlrev_b32_e32 v126, 16, v95
	v_and_b32_e32 v127, 0xffff0000, v95
	v_exp_f32_e32 v91, v91
	v_mul_f32_e32 v95, 0xbfb8aa3b, v125
	v_exp_f32_e32 v95, v95
	v_lshlrev_b32_e32 v140, 16, v92
	v_add_f32_e32 v91, 1.0, v91
	v_rcp_f32_e32 v130, v91
	v_add_f32_e32 v91, 1.0, v95
	v_rcp_f32_e32 v131, v91
	v_and_b32_e32 v141, 0xffff0000, v92
	v_lshlrev_b32_e32 v92, 16, v96
	v_and_b32_e32 v93, 0xffff0000, v96
	v_lshlrev_b32_e32 v136, 16, v97
	v_and_b32_e32 v137, 0xffff0000, v97
	v_pk_add_f32 v[92:93], v[92:93], v[140:141]
	v_pk_mul_f32 v[124:125], v[130:131], v[124:125]
	v_lshlrev_b32_e32 v130, 16, v90
	v_and_b32_e32 v131, 0xffff0000, v90
	v_lshlrev_b32_e32 v90, 16, v94
	v_and_b32_e32 v91, 0xffff0000, v94
	v_lshlrev_b32_e32 v94, 16, v98
	v_and_b32_e32 v95, 0xffff0000, v98
	v_pk_add_f32 v[134:135], v[136:137], v[134:135]
	v_pk_mul_f32 v[96:97], v[92:93], v[92:93]
	v_pk_add_f32 v[90:91], v[94:95], v[90:91]
	v_mul_f32_e32 v94, 0xbfb8aa3b, v130
	v_pk_mul_f32 v[136:137], v[134:135], v[134:135]
	v_add_f32_e32 v96, v96, v97
	v_exp_f32_e32 v98, v94
	v_mul_f32_e32 v94, 0xbfb8aa3b, v131
	v_add_f32_e32 v96, v136, v96
	v_lshlrev_b32_e32 v128, 16, v99
	v_and_b32_e32 v129, 0xffff0000, v99
	v_exp_f32_e32 v99, v94
	v_pk_mul_f32 v[94:95], v[90:91], v[90:91]
	v_add_f32_e32 v96, v137, v96
	v_pk_add_f32 v[126:127], v[128:129], v[126:127]
	v_add_f32_e32 v94, v94, v96
	v_pk_mul_f32 v[128:129], v[126:127], v[126:127]
	v_add_f32_e32 v94, v95, v94
	v_add_f32_e32 v94, v128, v94
	v_pk_mul_f32 v[104:105], v[100:101], v[100:101]
	v_add_f32_e32 v94, v129, v94
	v_pk_add_f32 v[120:121], v[122:123], v[120:121]
	v_add_f32_e32 v94, v104, v94
	v_pk_mul_f32 v[122:123], v[120:121], v[120:121]
	v_lshlrev_b32_e32 v132, 16, v89
	v_add_f32_e32 v94, v105, v94
	v_and_b32_e32 v133, 0xffff0000, v89
	v_mul_f32_e32 v89, 0xbfb8aa3b, v132
	v_add_f32_e32 v94, v122, v94
	v_pk_mul_f32 v[106:107], v[102:103], v[102:103]
	v_exp_f32_e32 v89, v89
	v_add_f32_e32 v94, v123, v94
	v_add_f32_e32 v94, v106, v94
	v_pk_mul_f32 v[118:119], v[114:115], v[114:115]
	v_add_f32_e32 v94, v107, v94
	v_add_f32_e32 v94, v119, v94
	v_add_f32_e32 v89, 1.0, v89
	v_add_f32_e32 v96, v118, v94
	v_rcp_f32_e32 v138, v89
	v_mul_f32_e32 v89, 0xbfb8aa3b, v133
	ds_bpermute_b32 v97, v177, v96
	v_exp_f32_e32 v89, v89
	v_lshlrev_b32_e32 v94, 16, v88
	v_and_b32_e32 v95, 0xffff0000, v88
	v_add_f32_e32 v98, 1.0, v98
	v_add_f32_e32 v89, 1.0, v89
	s_waitcnt lgkmcnt(0)
	v_add_f32_e32 v88, v96, v97
	v_rcp_f32_e32 v139, v89
	ds_bpermute_b32 v89, v178, v88
	v_mul_f32_e32 v96, 0xbfb8aa3b, v94
	v_exp_f32_e32 v96, v96
	v_mul_f32_e32 v97, 0xbfb8aa3b, v95
	v_exp_f32_e32 v97, v97
	s_waitcnt lgkmcnt(0)
	v_add_f32_e32 v104, v88, v89
	ds_bpermute_b32 v105, v179, v104
	v_add_f32_e32 v88, 1.0, v96
	v_add_f32_e32 v89, 1.0, v97
	v_rcp_f32_e32 v88, v88
	v_rcp_f32_e32 v89, v89
	s_waitcnt lgkmcnt(0)
	v_add_f32_e32 v96, v104, v105
	v_fmamk_f32 v96, v96, 0x3c000000, v176
	v_add_f32_e32 v99, 1.0, v99
	v_pk_mul_f32 v[88:89], v[88:89], v[94:95]
	v_rsq_f32_e32 v104, v96
	v_rcp_f32_e32 v98, v98
	v_rcp_f32_e32 v99, v99
	v_ashrrev_i32_e32 v165, 31, v164
	v_mov_b32_e32 v94, v104
	v_pk_mul_f32 v[92:93], v[92:93], v[94:95] op_sel_hi:[1,0]
	v_pk_mul_f32 v[90:91], v[90:91], v[94:95] op_sel_hi:[1,0]
	v_pk_mul_f32 v[92:93], v[12:13], v[92:93]
	v_pk_mul_f32 v[96:97], v[98:99], v[130:131]
	v_pk_mul_f32 v[88:89], v[88:89], v[92:93]
	v_pk_mul_f32 v[92:93], v[134:135], v[94:95] op_sel_hi:[1,0]
	v_pk_mul_f32 v[98:99], v[138:139], v[132:133]
	v_pk_mul_f32 v[92:93], v[14:15], v[92:93]
	v_pk_mul_f32 v[90:91], v[8:9], v[90:91]
	v_pk_mul_f32 v[92:93], v[98:99], v[92:93]
	v_pk_mul_f32 v[90:91], v[96:97], v[90:91]
	v_pk_mul_f32 v[96:97], v[126:127], v[94:95] op_sel_hi:[1,0]
	v_pk_mul_f32 v[98:99], v[100:101], v[94:95] op_sel_hi:[1,0]
	v_pk_mul_f32 v[100:101], v[120:121], v[94:95] op_sel_hi:[1,0]
	v_mul_f32_e32 v95, 0xbfb8aa3b, v116
	v_exp_f32_e32 v95, v95
	v_mul_f32_e32 v104, 0xbfb8aa3b, v117
	v_exp_f32_e32 v105, v104
	v_pk_mul_f32 v[96:97], v[10:11], v[96:97]
	v_add_f32_e32 v95, 1.0, v95
	v_rcp_f32_e32 v104, v95
	v_add_f32_e32 v95, 1.0, v105
	v_rcp_f32_e32 v105, v95
	v_pk_mul_f32 v[102:103], v[102:103], v[94:95] op_sel_hi:[1,0]
	v_mul_f32_e32 v95, 0xbfb8aa3b, v113
	v_pk_mul_f32 v[102:103], v[0:1], v[102:103]
	v_pk_mul_f32 v[104:105], v[104:105], v[116:117]
	v_exp_f32_e32 v95, v95
	v_pk_mul_f32 v[102:103], v[104:105], v[102:103]
	v_mul_f32_e32 v104, 0xbfb8aa3b, v112
	v_exp_f32_e32 v104, v104
	v_add_f32_e32 v95, 1.0, v95
	v_rcp_f32_e32 v95, v95
	v_mul_f32_e32 v105, v115, v94
	v_add_f32_e32 v104, 1.0, v104
	v_rcp_f32_e32 v156, v104
	v_mul_f32_e32 v106, v95, v113
	v_mul_f32_e32 v113, v114, v94
	v_pk_mul_f32 v[96:97], v[124:125], v[96:97]
	v_pk_mul_f32 v[94:95], v[156:157], v[112:113]
	v_pk_mul_f32 v[98:99], v[4:5], v[98:99]
	v_pk_mul_f32 v[100:101], v[6:7], v[100:101]
	v_mul_f32_e32 v104, v2, v105
	v_mov_b32_e32 v107, v94
	v_mov_b32_e32 v105, v95
	v_cvt_pk_bf16_f32 v88, v88, v89
	v_cvt_pk_bf16_f32 v89, v92, v93
	v_lshlrev_b64 v[92:93], 11, v[164:165]
	v_pk_mul_f32 v[98:99], v[108:109], v[98:99]
	v_pk_mul_f32 v[100:101], v[110:111], v[100:101]
	v_cvt_pk_bf16_f32 v90, v90, v91
	v_cvt_pk_bf16_f32 v91, v96, v97
	v_lshl_add_u64 v[92:93], v[150:151], 0, v[92:93]
	v_pk_mul_f32 v[94:95], v[106:107], v[104:105]
	global_store_dwordx4 v[92:93], v[88:91], off
	s_nop 1
	v_cvt_pk_bf16_f32 v88, v98, v99
	v_cvt_pk_bf16_f32 v89, v100, v101
	v_cvt_pk_bf16_f32 v90, v102, v103
	v_cvt_pk_bf16_f32 v91, v94, v95
	global_store_dwordx4 v[92:93], v[88:91], off offset:16
.LBB0_1433:
	s_or_b64 exec, exec, s[14:15]
	v_add_u32_e32 v3, s33, v3
	v_cmp_gt_i32_e32 vcc, s3, v3
	s_and_saveexec_b64 s[14:15], vcc
	s_cbranch_execz .LBB0_1435
	s_waitcnt vmcnt(17)
	v_lshlrev_b32_e32 v91, 16, v83
	v_lshlrev_b32_e32 v93, 16, v79
	v_and_b32_e32 v90, 0xffff0000, v83
	v_and_b32_e32 v92, 0xffff0000, v79
	s_waitcnt vmcnt(14)
	v_and_b32_e32 v88, 0xffff0000, v87
	v_lshlrev_b32_e32 v89, 16, v87
	v_pk_add_f32 v[90:91], v[90:91], v[92:93]
	v_lshlrev_b32_e32 v92, 16, v86
	v_and_b32_e32 v93, 0xffff0000, v86
	v_lshlrev_b32_e32 v86, 16, v82
	v_and_b32_e32 v87, 0xffff0000, v82
	v_lshlrev_b32_e32 v82, 16, v78
	v_and_b32_e32 v83, 0xffff0000, v78
	v_pk_add_f32 v[78:79], v[82:83], v[86:87]
	v_lshlrev_b32_e32 v86, 16, v85
	v_and_b32_e32 v87, 0xffff0000, v85
	v_lshlrev_b32_e32 v96, 16, v81
	v_and_b32_e32 v97, 0xffff0000, v81
	v_mul_f32_e32 v81, 0xbfb8aa3b, v86
	v_exp_f32_e32 v81, v81
	v_mul_f32_e32 v85, 0xbfb8aa3b, v87
	v_exp_f32_e32 v85, v85
	v_lshlrev_b32_e32 v98, 16, v77
	v_add_f32_e32 v81, 1.0, v81
	v_rcp_f32_e32 v100, v81
	v_add_f32_e32 v81, 1.0, v85
	v_rcp_f32_e32 v101, v81
	v_and_b32_e32 v99, 0xffff0000, v77
	v_and_b32_e32 v85, 0xffff0000, v80
	v_lshlrev_b32_e32 v110, 16, v69
	v_pk_mul_f32 v[86:87], v[100:101], v[86:87]
	v_lshlrev_b32_e32 v100, 16, v84
	v_and_b32_e32 v101, 0xffff0000, v84
	v_mul_f32_e32 v77, 0xbfb8aa3b, v100
	v_lshlrev_b32_e32 v84, 16, v80
	v_exp_f32_e32 v77, v77
	v_mul_f32_e32 v80, 0xbfb8aa3b, v101
	v_exp_f32_e32 v81, v80
	v_lshlrev_b32_e32 v80, 16, v76
	v_add_f32_e32 v77, 1.0, v77
	v_rcp_f32_e32 v102, v77
	v_add_f32_e32 v77, 1.0, v81
	v_rcp_f32_e32 v103, v77
	v_and_b32_e32 v81, 0xffff0000, v76
	v_pk_add_f32 v[76:77], v[80:81], v[84:85]
	v_and_b32_e32 v111, 0xffff0000, v69
	v_pk_mul_f32 v[84:85], v[102:103], v[100:101]
	v_lshlrev_b32_e32 v100, 16, v67
	v_and_b32_e32 v101, 0xffff0000, v67
	v_mul_f32_e32 v67, 0xbfb8aa3b, v100
	v_lshlrev_b32_e32 v102, 16, v71
	v_and_b32_e32 v103, 0xffff0000, v71
	v_exp_f32_e32 v67, v67
	v_mul_f32_e32 v71, 0xbfb8aa3b, v101
	v_exp_f32_e32 v71, v71
	v_lshlrev_b32_e32 v116, 16, v68
	v_add_f32_e32 v67, 1.0, v67
	v_rcp_f32_e32 v106, v67
	v_add_f32_e32 v67, 1.0, v71
	v_rcp_f32_e32 v107, v67
	v_and_b32_e32 v117, 0xffff0000, v68
	v_lshlrev_b32_e32 v68, 16, v72
	v_and_b32_e32 v69, 0xffff0000, v72
	v_lshlrev_b32_e32 v112, 16, v73
	v_and_b32_e32 v113, 0xffff0000, v73
	v_pk_add_f32 v[68:69], v[68:69], v[116:117]
	v_pk_mul_f32 v[100:101], v[106:107], v[100:101]
	v_lshlrev_b32_e32 v106, 16, v66
	v_and_b32_e32 v107, 0xffff0000, v66
	v_lshlrev_b32_e32 v66, 16, v70
	v_and_b32_e32 v67, 0xffff0000, v70
	v_lshlrev_b32_e32 v70, 16, v74
	v_and_b32_e32 v71, 0xffff0000, v74
	v_pk_add_f32 v[110:111], v[112:113], v[110:111]
	v_pk_mul_f32 v[72:73], v[68:69], v[68:69]
	v_pk_add_f32 v[66:67], v[70:71], v[66:67]
	v_mul_f32_e32 v70, 0xbfb8aa3b, v106
	v_pk_mul_f32 v[112:113], v[110:111], v[110:111]
	v_add_f32_e32 v72, v72, v73
	v_exp_f32_e32 v74, v70
	v_mul_f32_e32 v70, 0xbfb8aa3b, v107
	v_add_f32_e32 v72, v112, v72
	v_lshlrev_b32_e32 v104, 16, v75
	v_and_b32_e32 v105, 0xffff0000, v75
	v_exp_f32_e32 v75, v70
	v_pk_mul_f32 v[70:71], v[66:67], v[66:67]
	v_add_f32_e32 v72, v113, v72
	v_pk_add_f32 v[102:103], v[104:105], v[102:103]
	v_add_f32_e32 v70, v70, v72
	v_pk_mul_f32 v[104:105], v[102:103], v[102:103]
	v_add_f32_e32 v70, v71, v70
	v_add_f32_e32 v70, v104, v70
	v_pk_mul_f32 v[80:81], v[76:77], v[76:77]
	v_add_f32_e32 v70, v105, v70
	v_pk_add_f32 v[96:97], v[98:99], v[96:97]
	v_add_f32_e32 v70, v80, v70
	v_pk_mul_f32 v[98:99], v[96:97], v[96:97]
	v_lshlrev_b32_e32 v108, 16, v65
	v_add_f32_e32 v70, v81, v70
	v_and_b32_e32 v109, 0xffff0000, v65
	v_mul_f32_e32 v65, 0xbfb8aa3b, v108
	v_add_f32_e32 v70, v98, v70
	v_pk_mul_f32 v[82:83], v[78:79], v[78:79]
	v_exp_f32_e32 v65, v65
	v_add_f32_e32 v70, v99, v70
	v_add_f32_e32 v70, v82, v70
	v_pk_mul_f32 v[94:95], v[90:91], v[90:91]
	v_add_f32_e32 v70, v83, v70
	v_add_f32_e32 v70, v95, v70
	v_add_f32_e32 v65, 1.0, v65
	v_add_f32_e32 v72, v94, v70
	v_rcp_f32_e32 v114, v65
	v_mul_f32_e32 v65, 0xbfb8aa3b, v109
	ds_bpermute_b32 v73, v177, v72
	v_exp_f32_e32 v65, v65
	v_lshlrev_b32_e32 v70, 16, v64
	v_and_b32_e32 v71, 0xffff0000, v64
	v_add_f32_e32 v74, 1.0, v74
	v_add_f32_e32 v65, 1.0, v65
	s_waitcnt lgkmcnt(0)
	v_add_f32_e32 v64, v72, v73
	v_rcp_f32_e32 v115, v65
	ds_bpermute_b32 v65, v178, v64
	v_mul_f32_e32 v72, 0xbfb8aa3b, v70
	v_exp_f32_e32 v72, v72
	v_mul_f32_e32 v73, 0xbfb8aa3b, v71
	v_exp_f32_e32 v73, v73
	s_waitcnt lgkmcnt(0)
	v_add_f32_e32 v80, v64, v65
	ds_bpermute_b32 v81, v179, v80
	v_add_f32_e32 v64, 1.0, v72
	v_add_f32_e32 v65, 1.0, v73
	v_rcp_f32_e32 v64, v64
	v_rcp_f32_e32 v65, v65
	s_waitcnt lgkmcnt(0)
	v_add_f32_e32 v72, v80, v81
	v_fmamk_f32 v72, v72, 0x3c000000, v176
	v_add_f32_e32 v75, 1.0, v75
	v_pk_mul_f32 v[64:65], v[64:65], v[70:71]
	v_rsq_f32_e32 v80, v72
	v_rcp_f32_e32 v74, v74
	v_rcp_f32_e32 v75, v75
	v_ashrrev_i32_e32 v163, 31, v162
	v_mov_b32_e32 v70, v80
	v_pk_mul_f32 v[68:69], v[68:69], v[70:71] op_sel_hi:[1,0]
	v_pk_mul_f32 v[66:67], v[66:67], v[70:71] op_sel_hi:[1,0]
	v_pk_mul_f32 v[68:69], v[12:13], v[68:69]
	v_pk_mul_f32 v[72:73], v[74:75], v[106:107]
	v_pk_mul_f32 v[64:65], v[64:65], v[68:69]
	v_pk_mul_f32 v[68:69], v[110:111], v[70:71] op_sel_hi:[1,0]
	v_pk_mul_f32 v[74:75], v[114:115], v[108:109]
	v_pk_mul_f32 v[68:69], v[14:15], v[68:69]
	v_pk_mul_f32 v[66:67], v[8:9], v[66:67]
	v_pk_mul_f32 v[68:69], v[74:75], v[68:69]
	v_pk_mul_f32 v[66:67], v[72:73], v[66:67]
	v_pk_mul_f32 v[72:73], v[102:103], v[70:71] op_sel_hi:[1,0]
	v_pk_mul_f32 v[74:75], v[76:77], v[70:71] op_sel_hi:[1,0]
	v_pk_mul_f32 v[76:77], v[96:97], v[70:71] op_sel_hi:[1,0]
	v_mul_f32_e32 v71, 0xbfb8aa3b, v92
	v_exp_f32_e32 v71, v71
	v_mul_f32_e32 v80, 0xbfb8aa3b, v93
	v_exp_f32_e32 v81, v80
	v_pk_mul_f32 v[72:73], v[10:11], v[72:73]
	v_add_f32_e32 v71, 1.0, v71
	v_rcp_f32_e32 v80, v71
	v_add_f32_e32 v71, 1.0, v81
	v_rcp_f32_e32 v81, v71
	v_pk_mul_f32 v[78:79], v[78:79], v[70:71] op_sel_hi:[1,0]
	v_mul_f32_e32 v71, 0xbfb8aa3b, v89
	v_pk_mul_f32 v[78:79], v[0:1], v[78:79]
	v_pk_mul_f32 v[80:81], v[80:81], v[92:93]
	v_exp_f32_e32 v71, v71
	v_pk_mul_f32 v[78:79], v[80:81], v[78:79]
	v_mul_f32_e32 v80, 0xbfb8aa3b, v88
	v_exp_f32_e32 v80, v80
	v_add_f32_e32 v71, 1.0, v71
	v_rcp_f32_e32 v71, v71
	v_mul_f32_e32 v81, v91, v70
	v_add_f32_e32 v80, 1.0, v80
	v_rcp_f32_e32 v156, v80
	v_mul_f32_e32 v82, v71, v89
	v_mul_f32_e32 v89, v90, v70
	v_pk_mul_f32 v[72:73], v[100:101], v[72:73]
	v_pk_mul_f32 v[70:71], v[156:157], v[88:89]
	v_pk_mul_f32 v[74:75], v[4:5], v[74:75]
	v_pk_mul_f32 v[76:77], v[6:7], v[76:77]
	v_mul_f32_e32 v80, v2, v81
	v_mov_b32_e32 v83, v70
	v_mov_b32_e32 v81, v71
	v_cvt_pk_bf16_f32 v64, v64, v65
	v_cvt_pk_bf16_f32 v65, v68, v69
	v_lshlrev_b64 v[68:69], 11, v[162:163]
	v_pk_mul_f32 v[74:75], v[84:85], v[74:75]
	v_pk_mul_f32 v[76:77], v[86:87], v[76:77]
	v_cvt_pk_bf16_f32 v66, v66, v67
	v_cvt_pk_bf16_f32 v67, v72, v73
	v_lshl_add_u64 v[68:69], v[150:151], 0, v[68:69]
	v_pk_mul_f32 v[70:71], v[82:83], v[80:81]
	global_store_dwordx4 v[68:69], v[64:67], off
	s_nop 1
	v_cvt_pk_bf16_f32 v64, v74, v75
	v_cvt_pk_bf16_f32 v65, v76, v77
	v_cvt_pk_bf16_f32 v66, v78, v79
	v_cvt_pk_bf16_f32 v67, v70, v71
	global_store_dwordx4 v[68:69], v[64:67], off offset:16
.LBB0_1435:
	s_or_b64 exec, exec, s[14:15]
	v_add_u32_e32 v3, s33, v3
	v_cmp_gt_i32_e32 vcc, s3, v3
	s_and_saveexec_b64 s[14:15], vcc
	s_cbranch_execz .LBB0_1437
	s_waitcnt vmcnt(11)
	v_and_b32_e32 v69, 0xffff0000, v55
	v_and_b32_e32 v68, 0xffff0000, v59
	s_waitcnt vmcnt(8)
	v_lshlrev_b32_e32 v65, 16, v63
	v_and_b32_e32 v64, 0xffff0000, v63
	v_lshlrev_b32_e32 v63, 16, v59
	v_pk_add_f32 v[68:69], v[68:69], 0 op_sel_hi:[1,0]
	v_add_f32_e32 v67, 0, v63
	v_mov_b32_e32 v66, v68
	v_mov_b32_e32 v70, v69
	v_lshlrev_b32_e32 v68, 16, v62
	v_and_b32_e32 v69, 0xffff0000, v62
	v_lshlrev_b32_e32 v62, 16, v58
	v_and_b32_e32 v63, 0xffff0000, v58
	v_lshlrev_b32_e32 v55, 16, v55
	v_pk_add_f32 v[58:59], v[62:63], 0 op_sel_hi:[1,0]
	v_lshlrev_b32_e32 v62, 16, v54
	v_and_b32_e32 v63, 0xffff0000, v54
	v_add_f32_e32 v71, 0, v55
	v_pk_add_f32 v[54:55], v[62:63], 0 op_sel_hi:[1,0]
	v_lshlrev_b32_e32 v62, 16, v61
	v_and_b32_e32 v63, 0xffff0000, v61
	v_lshlrev_b32_e32 v72, 16, v57
	v_and_b32_e32 v73, 0xffff0000, v57
	v_mul_f32_e32 v57, 0xbfb8aa3b, v62
	v_exp_f32_e32 v57, v57
	v_mul_f32_e32 v61, 0xbfb8aa3b, v63
	v_exp_f32_e32 v61, v61
	v_lshlrev_b32_e32 v74, 16, v53
	v_and_b32_e32 v75, 0xffff0000, v53
	v_add_f32_e32 v53, 1.0, v57
	v_rcp_f32_e32 v76, v53
	v_add_f32_e32 v53, 1.0, v61
	v_rcp_f32_e32 v77, v53
	v_and_b32_e32 v61, 0xffff0000, v56
	v_and_b32_e32 v79, 0xffff0000, v51
	v_lshlrev_b32_e32 v92, 16, v48
	v_pk_mul_f32 v[62:63], v[76:77], v[62:63]
	v_lshlrev_b32_e32 v76, 16, v60
	v_and_b32_e32 v77, 0xffff0000, v60
	v_lshlrev_b32_e32 v60, 16, v56
	v_pk_add_f32 v[56:57], v[60:61], 0 op_sel_hi:[1,0]
	v_mul_f32_e32 v53, 0xbfb8aa3b, v76
	v_mul_f32_e32 v61, 0xbfb8aa3b, v77
	v_exp_f32_e32 v53, v53
	v_exp_f32_e32 v78, v61
	v_lshlrev_b32_e32 v60, 16, v52
	v_and_b32_e32 v61, 0xffff0000, v52
	v_add_f32_e32 v52, 1.0, v53
	v_add_f32_e32 v53, 1.0, v78
	v_rcp_f32_e32 v52, v52
	v_rcp_f32_e32 v53, v53
	v_lshlrev_b32_e32 v78, 16, v51
	v_and_b32_e32 v93, 0xffff0000, v48
	v_lshlrev_b32_e32 v86, 16, v49
	v_pk_mul_f32 v[52:53], v[52:53], v[76:77]
	v_lshlrev_b32_e32 v76, 16, v43
	v_and_b32_e32 v77, 0xffff0000, v43
	v_mul_f32_e32 v43, 0xbfb8aa3b, v76
	v_exp_f32_e32 v43, v43
	v_mul_f32_e32 v51, 0xbfb8aa3b, v77
	v_exp_f32_e32 v51, v51
	v_and_b32_e32 v87, 0xffff0000, v49
	v_add_f32_e32 v43, 1.0, v43
	v_rcp_f32_e32 v82, v43
	v_add_f32_e32 v43, 1.0, v51
	v_rcp_f32_e32 v83, v43
	v_pk_add_f32 v[48:49], v[92:93], 0 op_sel_hi:[1,0]
	v_lshlrev_b32_e32 v92, 16, v44
	v_and_b32_e32 v93, 0xffff0000, v44
	v_lshlrev_b32_e32 v88, 16, v45
	v_and_b32_e32 v89, 0xffff0000, v45
	v_pk_add_f32 v[44:45], v[92:93], 0 op_sel_hi:[1,0]
	v_pk_mul_f32 v[76:77], v[82:83], v[76:77]
	v_lshlrev_b32_e32 v82, 16, v42
	v_and_b32_e32 v83, 0xffff0000, v42
	v_lshlrev_b32_e32 v42, 16, v50
	v_and_b32_e32 v43, 0xffff0000, v50
	v_lshlrev_b32_e32 v50, 16, v46
	v_and_b32_e32 v51, 0xffff0000, v46
	v_pk_add_f32 v[86:87], v[86:87], 0 op_sel_hi:[1,0]
	v_pk_add_f32 v[88:89], v[88:89], 0 op_sel_hi:[1,0]
	v_pk_add_f32 v[44:45], v[48:49], v[44:45]
	v_lshlrev_b32_e32 v80, 16, v47
	v_and_b32_e32 v81, 0xffff0000, v47
	v_pk_add_f32 v[42:43], v[42:43], 0 op_sel_hi:[1,0]
	v_pk_add_f32 v[46:47], v[50:51], 0 op_sel_hi:[1,0]
	v_pk_add_f32 v[86:87], v[86:87], v[88:89]
	v_pk_mul_f32 v[48:49], v[44:45], v[44:45]
	v_pk_add_f32 v[42:43], v[42:43], v[46:47]
	v_mul_f32_e32 v46, 0xbfb8aa3b, v82
	v_pk_mul_f32 v[88:89], v[86:87], v[86:87]
	v_add_f32_e32 v48, v48, v49
	v_exp_f32_e32 v50, v46
	v_mul_f32_e32 v46, 0xbfb8aa3b, v83
	v_add_f32_e32 v48, v88, v48
	v_pk_add_f32 v[78:79], v[78:79], 0 op_sel_hi:[1,0]
	v_pk_add_f32 v[80:81], v[80:81], 0 op_sel_hi:[1,0]
	v_exp_f32_e32 v51, v46
	v_pk_mul_f32 v[46:47], v[42:43], v[42:43]
	v_add_f32_e32 v48, v89, v48
	v_pk_add_f32 v[78:79], v[78:79], v[80:81]
	v_add_f32_e32 v46, v46, v48
	v_pk_add_f32 v[60:61], v[60:61], 0 op_sel_hi:[1,0]
	v_pk_mul_f32 v[80:81], v[78:79], v[78:79]
	v_add_f32_e32 v46, v47, v46
	v_pk_add_f32 v[56:57], v[56:57], v[60:61]
	v_add_f32_e32 v46, v80, v46
	v_pk_add_f32 v[72:73], v[72:73], 0 op_sel_hi:[1,0]
	v_pk_add_f32 v[74:75], v[74:75], 0 op_sel_hi:[1,0]
	v_pk_mul_f32 v[60:61], v[56:57], v[56:57]
	v_add_f32_e32 v46, v81, v46
	v_pk_add_f32 v[72:73], v[72:73], v[74:75]
	v_add_f32_e32 v46, v60, v46
	v_pk_mul_f32 v[74:75], v[72:73], v[72:73]
	v_lshlrev_b32_e32 v84, 16, v41
	v_add_f32_e32 v46, v61, v46
	v_pk_add_f32 v[54:55], v[58:59], v[54:55]
	v_and_b32_e32 v85, 0xffff0000, v41
	v_mul_f32_e32 v41, 0xbfb8aa3b, v84
	v_add_f32_e32 v46, v74, v46
	v_pk_mul_f32 v[58:59], v[54:55], v[54:55]
	v_exp_f32_e32 v41, v41
	v_add_f32_e32 v46, v75, v46
	v_pk_add_f32 v[66:67], v[66:67], v[70:71]
	v_add_f32_e32 v46, v58, v46
	v_pk_mul_f32 v[70:71], v[66:67], v[66:67]
	v_add_f32_e32 v46, v59, v46
	v_add_f32_e32 v46, v71, v46
	v_add_f32_e32 v41, 1.0, v41
	v_add_f32_e32 v48, v70, v46
	v_rcp_f32_e32 v90, v41
	v_mul_f32_e32 v41, 0xbfb8aa3b, v85
	ds_bpermute_b32 v49, v177, v48
	v_exp_f32_e32 v41, v41
	v_lshlrev_b32_e32 v46, 16, v40
	v_and_b32_e32 v47, 0xffff0000, v40
	v_add_f32_e32 v50, 1.0, v50
	v_add_f32_e32 v41, 1.0, v41
	s_waitcnt lgkmcnt(0)
	v_add_f32_e32 v40, v48, v49
	v_rcp_f32_e32 v91, v41
	ds_bpermute_b32 v41, v178, v40
	v_mul_f32_e32 v48, 0xbfb8aa3b, v46
	v_exp_f32_e32 v48, v48
	v_mul_f32_e32 v49, 0xbfb8aa3b, v47
	v_exp_f32_e32 v49, v49
	s_waitcnt lgkmcnt(0)
	v_add_f32_e32 v58, v40, v41
	ds_bpermute_b32 v59, v179, v58
	v_add_f32_e32 v40, 1.0, v48
	v_add_f32_e32 v41, 1.0, v49
	v_rcp_f32_e32 v40, v40
	v_rcp_f32_e32 v41, v41
	s_waitcnt lgkmcnt(0)
	v_add_f32_e32 v48, v58, v59
	v_fmamk_f32 v48, v48, 0x3c000000, v176
	v_add_f32_e32 v51, 1.0, v51
	v_pk_mul_f32 v[40:41], v[40:41], v[46:47]
	v_rsq_f32_e32 v58, v48
	v_rcp_f32_e32 v50, v50
	v_rcp_f32_e32 v51, v51
	v_ashrrev_i32_e32 v161, 31, v160
	v_mov_b32_e32 v46, v58
	v_pk_mul_f32 v[44:45], v[44:45], v[46:47] op_sel_hi:[1,0]
	v_pk_mul_f32 v[48:49], v[50:51], v[82:83]
	v_pk_mul_f32 v[44:45], v[12:13], v[44:45]
	v_pk_mul_f32 v[50:51], v[90:91], v[84:85]
	v_pk_mul_f32 v[40:41], v[40:41], v[44:45]
	v_pk_mul_f32 v[44:45], v[86:87], v[46:47] op_sel_hi:[1,0]
	v_pk_mul_f32 v[42:43], v[42:43], v[46:47] op_sel_hi:[1,0]
	v_pk_mul_f32 v[44:45], v[14:15], v[44:45]
	v_pk_mul_f32 v[42:43], v[8:9], v[42:43]
	v_pk_mul_f32 v[44:45], v[50:51], v[44:45]
	v_pk_mul_f32 v[50:51], v[56:57], v[46:47] op_sel_hi:[1,0]
	v_pk_mul_f32 v[42:43], v[48:49], v[42:43]
	v_pk_mul_f32 v[50:51], v[4:5], v[50:51]
	v_pk_mul_f32 v[48:49], v[78:79], v[46:47] op_sel_hi:[1,0]
	v_pk_mul_f32 v[50:51], v[52:53], v[50:51]
	v_pk_mul_f32 v[52:53], v[72:73], v[46:47] op_sel_hi:[1,0]
	v_mul_f32_e32 v47, 0xbfb8aa3b, v68
	v_exp_f32_e32 v47, v47
	v_mul_f32_e32 v56, 0xbfb8aa3b, v69
	v_exp_f32_e32 v57, v56
	v_pk_mul_f32 v[48:49], v[10:11], v[48:49]
	v_add_f32_e32 v47, 1.0, v47
	v_rcp_f32_e32 v56, v47
	v_add_f32_e32 v47, 1.0, v57
	v_rcp_f32_e32 v57, v47
	v_pk_mul_f32 v[54:55], v[54:55], v[46:47] op_sel_hi:[1,0]
	v_mul_f32_e32 v47, 0xbfb8aa3b, v65
	v_pk_mul_f32 v[54:55], v[0:1], v[54:55]
	v_pk_mul_f32 v[56:57], v[56:57], v[68:69]
	v_exp_f32_e32 v47, v47
	v_pk_mul_f32 v[54:55], v[56:57], v[54:55]
	v_mul_f32_e32 v56, 0xbfb8aa3b, v64
	v_exp_f32_e32 v56, v56
	v_add_f32_e32 v47, 1.0, v47
	v_rcp_f32_e32 v47, v47
	v_mul_f32_e32 v57, v67, v46
	v_add_f32_e32 v56, 1.0, v56
	v_rcp_f32_e32 v156, v56
	v_mul_f32_e32 v58, v47, v65
	v_mul_f32_e32 v65, v66, v46
	v_pk_mul_f32 v[48:49], v[76:77], v[48:49]
	v_pk_mul_f32 v[46:47], v[156:157], v[64:65]
	v_pk_mul_f32 v[52:53], v[6:7], v[52:53]
	v_mul_f32_e32 v56, v2, v57
	v_mov_b32_e32 v59, v46
	v_mov_b32_e32 v57, v47
	v_cvt_pk_bf16_f32 v40, v40, v41
	v_cvt_pk_bf16_f32 v41, v44, v45
	v_lshlrev_b64 v[44:45], 11, v[160:161]
	v_pk_mul_f32 v[52:53], v[62:63], v[52:53]
	v_cvt_pk_bf16_f32 v42, v42, v43
	v_cvt_pk_bf16_f32 v43, v48, v49
	v_lshl_add_u64 v[44:45], v[150:151], 0, v[44:45]
	v_pk_mul_f32 v[46:47], v[58:59], v[56:57]
	global_store_dwordx4 v[44:45], v[40:43], off
	s_nop 1
	v_cvt_pk_bf16_f32 v40, v50, v51
	v_cvt_pk_bf16_f32 v41, v52, v53
	v_cvt_pk_bf16_f32 v42, v54, v55
	v_cvt_pk_bf16_f32 v43, v46, v47
	global_store_dwordx4 v[44:45], v[40:43], off offset:16
.LBB0_1437:
	s_or_b64 exec, exec, s[14:15]
	v_add_u32_e32 v3, s33, v3
	v_cmp_gt_i32_e32 vcc, s3, v3
	s_and_saveexec_b64 s[14:15], vcc
	s_cbranch_execz .LBB0_1428
	s_waitcnt vmcnt(5)
	v_and_b32_e32 v45, 0xffff0000, v31
	v_and_b32_e32 v44, 0xffff0000, v35
	s_waitcnt vmcnt(2)
	v_lshlrev_b32_e32 v41, 16, v39
	v_and_b32_e32 v40, 0xffff0000, v39
	v_lshlrev_b32_e32 v39, 16, v35
	v_pk_add_f32 v[44:45], v[44:45], 0 op_sel_hi:[1,0]
	v_add_f32_e32 v43, 0, v39
	v_mov_b32_e32 v42, v44
	v_mov_b32_e32 v46, v45
	v_lshlrev_b32_e32 v44, 16, v38
	v_and_b32_e32 v45, 0xffff0000, v38
	v_lshlrev_b32_e32 v38, 16, v34
	v_and_b32_e32 v39, 0xffff0000, v34
	v_lshlrev_b32_e32 v31, 16, v31
	v_pk_add_f32 v[34:35], v[38:39], 0 op_sel_hi:[1,0]
	v_lshlrev_b32_e32 v38, 16, v30
	v_and_b32_e32 v39, 0xffff0000, v30
	v_add_f32_e32 v47, 0, v31
	v_pk_add_f32 v[30:31], v[38:39], 0 op_sel_hi:[1,0]
	v_lshlrev_b32_e32 v38, 16, v37
	v_and_b32_e32 v39, 0xffff0000, v37
	v_lshlrev_b32_e32 v48, 16, v33
	v_and_b32_e32 v49, 0xffff0000, v33
	v_mul_f32_e32 v33, 0xbfb8aa3b, v38
	v_exp_f32_e32 v33, v33
	v_mul_f32_e32 v37, 0xbfb8aa3b, v39
	v_exp_f32_e32 v37, v37
	v_lshlrev_b32_e32 v50, 16, v29
	v_and_b32_e32 v51, 0xffff0000, v29
	v_add_f32_e32 v29, 1.0, v33
	v_rcp_f32_e32 v52, v29
	v_add_f32_e32 v29, 1.0, v37
	v_rcp_f32_e32 v53, v29
	v_and_b32_e32 v37, 0xffff0000, v32
	v_and_b32_e32 v55, 0xffff0000, v27
	v_lshlrev_b32_e32 v68, 16, v24
	v_pk_mul_f32 v[38:39], v[52:53], v[38:39]
	v_lshlrev_b32_e32 v52, 16, v36
	v_and_b32_e32 v53, 0xffff0000, v36
	v_lshlrev_b32_e32 v36, 16, v32
	v_pk_add_f32 v[32:33], v[36:37], 0 op_sel_hi:[1,0]
	v_mul_f32_e32 v29, 0xbfb8aa3b, v52
	v_mul_f32_e32 v37, 0xbfb8aa3b, v53
	v_exp_f32_e32 v29, v29
	v_exp_f32_e32 v54, v37
	v_lshlrev_b32_e32 v36, 16, v28
	v_and_b32_e32 v37, 0xffff0000, v28
	v_add_f32_e32 v28, 1.0, v29
	v_add_f32_e32 v29, 1.0, v54
	v_rcp_f32_e32 v28, v28
	v_rcp_f32_e32 v29, v29
	v_lshlrev_b32_e32 v54, 16, v27
	v_and_b32_e32 v69, 0xffff0000, v24
	v_lshlrev_b32_e32 v62, 16, v25
	v_pk_mul_f32 v[28:29], v[28:29], v[52:53]
	v_lshlrev_b32_e32 v52, 16, v19
	v_and_b32_e32 v53, 0xffff0000, v19
	v_mul_f32_e32 v19, 0xbfb8aa3b, v52
	v_exp_f32_e32 v19, v19
	v_mul_f32_e32 v27, 0xbfb8aa3b, v53
	v_exp_f32_e32 v27, v27
	v_and_b32_e32 v63, 0xffff0000, v25
	v_add_f32_e32 v19, 1.0, v19
	v_rcp_f32_e32 v58, v19
	v_add_f32_e32 v19, 1.0, v27
	v_rcp_f32_e32 v59, v19
	v_pk_add_f32 v[24:25], v[68:69], 0 op_sel_hi:[1,0]
	v_lshlrev_b32_e32 v68, 16, v20
	v_and_b32_e32 v69, 0xffff0000, v20
	v_lshlrev_b32_e32 v64, 16, v21
	v_and_b32_e32 v65, 0xffff0000, v21
	v_pk_add_f32 v[20:21], v[68:69], 0 op_sel_hi:[1,0]
	v_pk_mul_f32 v[52:53], v[58:59], v[52:53]
	v_lshlrev_b32_e32 v58, 16, v18
	v_and_b32_e32 v59, 0xffff0000, v18
	v_lshlrev_b32_e32 v18, 16, v26
	v_and_b32_e32 v19, 0xffff0000, v26
	v_lshlrev_b32_e32 v26, 16, v22
	v_and_b32_e32 v27, 0xffff0000, v22
	v_pk_add_f32 v[62:63], v[62:63], 0 op_sel_hi:[1,0]
	v_pk_add_f32 v[64:65], v[64:65], 0 op_sel_hi:[1,0]
	v_pk_add_f32 v[20:21], v[24:25], v[20:21]
	v_lshlrev_b32_e32 v56, 16, v23
	v_and_b32_e32 v57, 0xffff0000, v23
	v_pk_add_f32 v[18:19], v[18:19], 0 op_sel_hi:[1,0]
	v_pk_add_f32 v[22:23], v[26:27], 0 op_sel_hi:[1,0]
	v_pk_add_f32 v[62:63], v[62:63], v[64:65]
	v_pk_mul_f32 v[24:25], v[20:21], v[20:21]
	v_pk_add_f32 v[18:19], v[18:19], v[22:23]
	v_mul_f32_e32 v22, 0xbfb8aa3b, v58
	v_pk_mul_f32 v[64:65], v[62:63], v[62:63]
	v_add_f32_e32 v24, v24, v25
	v_exp_f32_e32 v26, v22
	v_mul_f32_e32 v22, 0xbfb8aa3b, v59
	v_add_f32_e32 v24, v64, v24
	v_pk_add_f32 v[54:55], v[54:55], 0 op_sel_hi:[1,0]
	v_pk_add_f32 v[56:57], v[56:57], 0 op_sel_hi:[1,0]
	v_exp_f32_e32 v27, v22
	v_pk_mul_f32 v[22:23], v[18:19], v[18:19]
	v_add_f32_e32 v24, v65, v24
	v_pk_add_f32 v[54:55], v[54:55], v[56:57]
	v_add_f32_e32 v22, v22, v24
	v_pk_add_f32 v[36:37], v[36:37], 0 op_sel_hi:[1,0]
	v_pk_mul_f32 v[56:57], v[54:55], v[54:55]
	v_add_f32_e32 v22, v23, v22
	v_pk_add_f32 v[32:33], v[32:33], v[36:37]
	v_add_f32_e32 v22, v56, v22
	v_pk_add_f32 v[48:49], v[48:49], 0 op_sel_hi:[1,0]
	v_pk_add_f32 v[50:51], v[50:51], 0 op_sel_hi:[1,0]
	v_pk_mul_f32 v[36:37], v[32:33], v[32:33]
	v_add_f32_e32 v22, v57, v22
	v_pk_add_f32 v[48:49], v[48:49], v[50:51]
	v_add_f32_e32 v22, v36, v22
	v_pk_mul_f32 v[50:51], v[48:49], v[48:49]
	v_lshlrev_b32_e32 v60, 16, v17
	v_add_f32_e32 v22, v37, v22
	v_pk_add_f32 v[30:31], v[34:35], v[30:31]
	v_and_b32_e32 v61, 0xffff0000, v17
	v_mul_f32_e32 v17, 0xbfb8aa3b, v60
	v_add_f32_e32 v22, v50, v22
	v_pk_mul_f32 v[34:35], v[30:31], v[30:31]
	v_exp_f32_e32 v17, v17
	v_add_f32_e32 v22, v51, v22
	v_pk_add_f32 v[42:43], v[42:43], v[46:47]
	v_add_f32_e32 v22, v34, v22
	v_pk_mul_f32 v[46:47], v[42:43], v[42:43]
	v_add_f32_e32 v22, v35, v22
	v_add_f32_e32 v22, v47, v22
	v_add_f32_e32 v17, 1.0, v17
	v_add_f32_e32 v24, v46, v22
	v_rcp_f32_e32 v66, v17
	v_mul_f32_e32 v17, 0xbfb8aa3b, v61
	ds_bpermute_b32 v25, v177, v24
	v_exp_f32_e32 v17, v17
	v_lshlrev_b32_e32 v22, 16, v16
	v_and_b32_e32 v23, 0xffff0000, v16
	v_add_f32_e32 v26, 1.0, v26
	v_add_f32_e32 v17, 1.0, v17
	s_waitcnt lgkmcnt(0)
	v_add_f32_e32 v16, v24, v25
	v_rcp_f32_e32 v67, v17
	ds_bpermute_b32 v17, v178, v16
	v_mul_f32_e32 v24, 0xbfb8aa3b, v22
	v_exp_f32_e32 v24, v24
	v_mul_f32_e32 v25, 0xbfb8aa3b, v23
	v_exp_f32_e32 v25, v25
	s_waitcnt lgkmcnt(0)
	v_add_f32_e32 v34, v16, v17
	ds_bpermute_b32 v35, v179, v34
	v_add_f32_e32 v16, 1.0, v24
	v_add_f32_e32 v17, 1.0, v25
	v_rcp_f32_e32 v16, v16
	v_rcp_f32_e32 v17, v17
	s_waitcnt lgkmcnt(0)
	v_add_f32_e32 v24, v34, v35
	v_fmamk_f32 v24, v24, 0x3c000000, v176
	v_add_f32_e32 v27, 1.0, v27
	v_pk_mul_f32 v[16:17], v[16:17], v[22:23]
	v_rsq_f32_e32 v34, v24
	v_rcp_f32_e32 v26, v26
	v_rcp_f32_e32 v27, v27
	v_ashrrev_i32_e32 v159, 31, v158
	v_mov_b32_e32 v22, v34
	v_pk_mul_f32 v[20:21], v[20:21], v[22:23] op_sel_hi:[1,0]
	v_pk_mul_f32 v[24:25], v[26:27], v[58:59]
	v_pk_mul_f32 v[20:21], v[12:13], v[20:21]
	v_pk_mul_f32 v[26:27], v[66:67], v[60:61]
	v_pk_mul_f32 v[16:17], v[16:17], v[20:21]
	v_pk_mul_f32 v[20:21], v[62:63], v[22:23] op_sel_hi:[1,0]
	v_pk_mul_f32 v[18:19], v[18:19], v[22:23] op_sel_hi:[1,0]
	v_pk_mul_f32 v[20:21], v[14:15], v[20:21]
	v_pk_mul_f32 v[18:19], v[8:9], v[18:19]
	v_pk_mul_f32 v[20:21], v[26:27], v[20:21]
	v_pk_mul_f32 v[26:27], v[32:33], v[22:23] op_sel_hi:[1,0]
	v_pk_mul_f32 v[18:19], v[24:25], v[18:19]
	v_pk_mul_f32 v[26:27], v[4:5], v[26:27]
	v_pk_mul_f32 v[24:25], v[54:55], v[22:23] op_sel_hi:[1,0]
	v_pk_mul_f32 v[26:27], v[28:29], v[26:27]
	v_pk_mul_f32 v[28:29], v[48:49], v[22:23] op_sel_hi:[1,0]
	v_mul_f32_e32 v23, 0xbfb8aa3b, v44
	v_exp_f32_e32 v23, v23
	v_mul_f32_e32 v32, 0xbfb8aa3b, v45
	v_exp_f32_e32 v33, v32
	v_pk_mul_f32 v[24:25], v[10:11], v[24:25]
	v_add_f32_e32 v23, 1.0, v23
	v_rcp_f32_e32 v32, v23
	v_add_f32_e32 v23, 1.0, v33
	v_rcp_f32_e32 v33, v23
	v_pk_mul_f32 v[30:31], v[30:31], v[22:23] op_sel_hi:[1,0]
	v_mul_f32_e32 v23, 0xbfb8aa3b, v41
	v_pk_mul_f32 v[30:31], v[0:1], v[30:31]
	v_pk_mul_f32 v[32:33], v[32:33], v[44:45]
	v_exp_f32_e32 v23, v23
	v_pk_mul_f32 v[30:31], v[32:33], v[30:31]
	v_mul_f32_e32 v32, 0xbfb8aa3b, v40
	v_exp_f32_e32 v32, v32
	v_add_f32_e32 v23, 1.0, v23
	v_rcp_f32_e32 v23, v23
	v_mul_f32_e32 v33, v43, v22
	v_add_f32_e32 v32, 1.0, v32
	v_rcp_f32_e32 v156, v32
	v_mul_f32_e32 v34, v23, v41
	v_mul_f32_e32 v41, v42, v22
	v_pk_mul_f32 v[24:25], v[52:53], v[24:25]
	v_pk_mul_f32 v[22:23], v[156:157], v[40:41]
	v_pk_mul_f32 v[28:29], v[6:7], v[28:29]
	v_mul_f32_e32 v32, v2, v33
	v_mov_b32_e32 v35, v22
	v_mov_b32_e32 v33, v23
	v_cvt_pk_bf16_f32 v16, v16, v17
	v_cvt_pk_bf16_f32 v17, v20, v21
	v_lshlrev_b64 v[20:21], 11, v[158:159]
	v_pk_mul_f32 v[28:29], v[38:39], v[28:29]
	v_cvt_pk_bf16_f32 v18, v18, v19
	v_cvt_pk_bf16_f32 v19, v24, v25
	v_lshl_add_u64 v[20:21], v[150:151], 0, v[20:21]
	v_pk_mul_f32 v[22:23], v[34:35], v[32:33]
	global_store_dwordx4 v[20:21], v[16:19], off
	s_nop 1
	v_cvt_pk_bf16_f32 v16, v26, v27
	v_cvt_pk_bf16_f32 v17, v28, v29
	v_cvt_pk_bf16_f32 v18, v30, v31
	v_cvt_pk_bf16_f32 v19, v22, v23
	global_store_dwordx4 v[20:21], v[16:19], off offset:16
	s_branch .LBB0_1428

.LBB0_1559:
	v_add_u32_e32 v35, s90, v128
	s_waitcnt vmcnt(6)
	v_add_co_u32_e32 v36, vcc, s10, v24
	s_waitcnt vmcnt(4)
	v_min_i32_e32 v38, 0x2fff, v35
	v_addc_co_u32_e32 v37, vcc, -1, v25, vcc
	global_load_dwordx2 v[130:131], v[24:25], off
	global_load_dwordx2 v[132:133], v[36:37], off
	v_ashrrev_i32_e32 v39, 31, v38
	v_lshlrev_b64 v[38:39], 11, v[38:39]
	v_lshl_add_u64 v[40:41], v[16:17], 0, v[38:39]
	v_lshl_add_u64 v[38:39], v[18:19], 0, v[38:39]
	global_load_dwordx2 v[134:135], v[24:25], off offset:-512
	global_load_dwordx2 v[136:137], v[36:37], off offset:-512
	global_load_dwordx2 v[106:107], v[40:41], off
	global_load_dwordx2 v[110:111], v[40:41], off offset:512
	global_load_dwordx2 v[114:115], v[40:41], off offset:1024
	global_load_dwordx2 v[118:119], v[40:41], off offset:1536
	global_load_dwordx2 v[108:109], v[38:39], off
	global_load_dwordx2 v[112:113], v[38:39], off offset:512
	global_load_dwordx2 v[116:117], v[38:39], off offset:1024
	global_load_dwordx2 v[120:121], v[38:39], off offset:1536
	global_load_dwordx2 v[138:139], v[24:25], off offset:-1024
	global_load_dwordx2 v[140:141], v[36:37], off offset:-1024
	v_add_u32_e32 v88, s90, v129
	v_min_i32_e32 v38, 0x2fff, v88
	v_ashrrev_i32_e32 v39, 31, v38
	v_lshlrev_b64 v[38:39], 11, v[38:39]
	v_lshl_add_u64 v[40:41], v[16:17], 0, v[38:39]
	v_lshl_add_u64 v[38:39], v[18:19], 0, v[38:39]
	global_load_dwordx2 v[142:143], v[24:25], off offset:-1536
	global_load_dwordx2 v[102:103], v[40:41], off
	global_load_dwordx2 v[98:99], v[40:41], off offset:512
	global_load_dwordx2 v[94:95], v[40:41], off offset:1024
	global_load_dwordx2 v[90:91], v[40:41], off offset:1536
	global_load_dwordx2 v[144:145], v[36:37], off offset:-1536
	global_load_dwordx2 v[104:105], v[38:39], off
	global_load_dwordx2 v[100:101], v[38:39], off offset:512
	global_load_dwordx2 v[96:97], v[38:39], off offset:1024
	global_load_dwordx2 v[92:93], v[38:39], off offset:1536
	v_add_u32_e32 v70, s90, v30
	v_min_i32_e32 v36, 0x2fff, v70
	v_ashrrev_i32_e32 v37, 31, v36
	v_lshlrev_b64 v[36:37], 11, v[36:37]
	v_lshl_add_u64 v[38:39], v[16:17], 0, v[36:37]
	v_lshl_add_u64 v[36:37], v[18:19], 0, v[36:37]
	v_add_u32_e32 v52, s90, v29
	global_load_dwordx2 v[84:85], v[38:39], off
	global_load_dwordx2 v[80:81], v[38:39], off offset:512
	global_load_dwordx2 v[76:77], v[38:39], off offset:1024
	global_load_dwordx2 v[72:73], v[38:39], off offset:1536
	global_load_dwordx2 v[86:87], v[36:37], off
	global_load_dwordx2 v[82:83], v[36:37], off offset:512
	global_load_dwordx2 v[78:79], v[36:37], off offset:1024
	global_load_dwordx2 v[74:75], v[36:37], off offset:1536
	v_min_i32_e32 v36, 0x2fff, v52
	v_ashrrev_i32_e32 v37, 31, v36
	v_lshlrev_b64 v[36:37], 11, v[36:37]
	v_lshl_add_u64 v[38:39], v[16:17], 0, v[36:37]
	v_lshl_add_u64 v[36:37], v[18:19], 0, v[36:37]
	v_add_u32_e32 v34, s90, v28
	global_load_dwordx2 v[66:67], v[38:39], off
	global_load_dwordx2 v[62:63], v[38:39], off offset:512
	global_load_dwordx2 v[58:59], v[38:39], off offset:1024
	global_load_dwordx2 v[54:55], v[38:39], off offset:1536
	global_load_dwordx2 v[68:69], v[36:37], off
	global_load_dwordx2 v[64:65], v[36:37], off offset:512
	global_load_dwordx2 v[60:61], v[36:37], off offset:1024
	global_load_dwordx2 v[56:57], v[36:37], off offset:1536
	v_min_i32_e32 v36, 0x2fff, v34
	v_ashrrev_i32_e32 v37, 31, v36
	v_lshlrev_b64 v[36:37], 11, v[36:37]
	v_lshl_add_u64 v[38:39], v[16:17], 0, v[36:37]
	v_lshl_add_u64 v[146:147], v[18:19], 0, v[36:37]
	global_load_dwordx2 v[48:49], v[38:39], off
	global_load_dwordx2 v[44:45], v[38:39], off offset:512
	global_load_dwordx2 v[40:41], v[38:39], off offset:1024
	global_load_dwordx2 v[36:37], v[38:39], off offset:1536
	global_load_dwordx2 v[50:51], v[146:147], off
	global_load_dwordx2 v[46:47], v[146:147], off offset:512
	global_load_dwordx2 v[42:43], v[146:147], off offset:1024
	s_nop 0
	global_load_dwordx2 v[38:39], v[146:147], off offset:1536
	s_waitcnt vmcnt(47)
	v_lshlrev_b32_e32 v146, 16, v130
	v_and_b32_e32 v147, 0xffff0000, v130
	v_lshlrev_b32_e32 v130, 16, v131
	v_and_b32_e32 v131, 0xffff0000, v131
	s_waitcnt vmcnt(46)
	v_lshlrev_b32_e32 v148, 16, v132
	v_and_b32_e32 v149, 0xffff0000, v132
	v_lshlrev_b32_e32 v132, 16, v133
	v_and_b32_e32 v133, 0xffff0000, v133
	v_pk_add_f32 v[150:151], v[130:131], v[132:133]
	s_waitcnt vmcnt(45)
	v_lshlrev_b32_e32 v130, 16, v134
	v_and_b32_e32 v131, 0xffff0000, v134
	v_lshlrev_b32_e32 v132, 16, v135
	v_and_b32_e32 v133, 0xffff0000, v135
	s_waitcnt vmcnt(44)
	v_lshlrev_b32_e32 v134, 16, v136
	v_and_b32_e32 v135, 0xffff0000, v136
	v_lshlrev_b32_e32 v136, 16, v137
	v_and_b32_e32 v137, 0xffff0000, v137
	v_pk_add_f32 v[136:137], v[132:133], v[136:137]
	v_pk_add_f32 v[134:135], v[130:131], v[134:135]
	s_waitcnt vmcnt(35)
	v_lshlrev_b32_e32 v130, 16, v138
	v_and_b32_e32 v131, 0xffff0000, v138
	v_lshlrev_b32_e32 v132, 16, v139
	v_and_b32_e32 v133, 0xffff0000, v139
	s_waitcnt vmcnt(34)
	v_lshlrev_b32_e32 v138, 16, v140
	v_and_b32_e32 v139, 0xffff0000, v140
	v_lshlrev_b32_e32 v140, 16, v141
	v_and_b32_e32 v141, 0xffff0000, v141
	v_pk_add_f32 v[140:141], v[132:133], v[140:141]
	v_pk_add_f32 v[138:139], v[130:131], v[138:139]
	s_waitcnt vmcnt(33)
	v_lshlrev_b32_e32 v130, 16, v142
	v_and_b32_e32 v131, 0xffff0000, v142
	v_lshlrev_b32_e32 v132, 16, v143
	v_and_b32_e32 v133, 0xffff0000, v143
	s_waitcnt vmcnt(28)
	v_lshlrev_b32_e32 v142, 16, v144
	v_and_b32_e32 v143, 0xffff0000, v144
	v_lshlrev_b32_e32 v144, 16, v145
	v_and_b32_e32 v145, 0xffff0000, v145
	v_pk_add_f32 v[130:131], v[130:131], v[142:143]
	v_pk_add_f32 v[132:133], v[132:133], v[144:145]
	v_mov_b32_e32 v144, v139
	v_mov_b32_e32 v145, v131
	v_mov_b32_e32 v142, v138
	v_mov_b32_e32 v143, v130
	v_pk_mul_f32 v[144:145], v[144:145], v[144:145]
	v_pk_add_f32 v[146:147], v[146:147], v[148:149]
	v_pk_fma_f32 v[142:143], v[142:143], v[142:143], v[144:145]
	v_mov_b32_e32 v144, v140
	v_mov_b32_e32 v145, v132
	v_pk_fma_f32 v[142:143], v[144:145], v[144:145], v[142:143]
	v_mov_b32_e32 v144, v141
	v_mov_b32_e32 v145, v133
	v_mov_b32_e32 v148, v147
	v_mov_b32_e32 v149, v135
	v_pk_fma_f32 v[142:143], v[144:145], v[144:145], v[142:143]
	v_mov_b32_e32 v144, v146
	v_mov_b32_e32 v145, v134
	v_pk_mul_f32 v[148:149], v[148:149], v[148:149]
	v_add_f32_e32 v53, v142, v143
	v_pk_fma_f32 v[144:145], v[144:145], v[144:145], v[148:149]
	v_mov_b32_e32 v148, v150
	v_mov_b32_e32 v149, v136
	v_pk_fma_f32 v[144:145], v[148:149], v[148:149], v[144:145]
	v_mov_b32_e32 v148, v151
	v_mov_b32_e32 v149, v137
	v_pk_fma_f32 v[144:145], v[148:149], v[148:149], v[144:145]
	s_nop 0
	v_add_f32_e32 v53, v145, v53
	v_add_f32_e32 v53, v144, v53
	ds_bpermute_b32 v71, v122, v53
	v_lshl_add_u64 v[144:145], v[32:33], 0, v[22:23]
	s_waitcnt lgkmcnt(0)
	v_add_f32_e32 v53, v53, v71
	ds_bpermute_b32 v71, v123, v53
	s_waitcnt lgkmcnt(0)
	v_add_f32_e32 v53, v53, v71
	s_nop 1
	v_add_f32_dpp v53, v53, v53 row_ror:8 row_mask:0xf bank_mask:0xf
	s_nop 1
	v_add_f32_dpp v53, v53, v53 row_ror:4 row_mask:0xf bank_mask:0xf
	s_nop 1
	v_add_f32_dpp v53, v53, v53 quad_perm:[2,3,0,1] row_mask:0xf bank_mask:0xf
	s_nop 1
	v_add_f32_dpp v53, v53, v53 quad_perm:[1,0,3,2] row_mask:0xf bank_mask:0xf
	v_fmamk_f32 v53, v53, 0x3a800000, v31
	v_rsq_f32_e32 v53, v53
	s_nop 0
	v_mov_b32_e32 v142, v53
	v_pk_mul_f32 v[130:131], v[130:131], v[142:143] op_sel_hi:[1,0]
	v_pk_mul_f32 v[132:133], v[132:133], v[142:143] op_sel_hi:[1,0]
	v_pk_mul_f32 v[130:131], v[0:1], v[130:131]
	v_pk_mul_f32 v[132:133], v[2:3], v[132:133]
	global_store_dwordx4 v[144:145], v[130:133], off nt
	v_cmp_gt_i32_e32 vcc, s8, v35
	s_nop 0
	v_pk_mul_f32 v[130:131], v[138:139], v[142:143] op_sel_hi:[1,0]
	v_pk_mul_f32 v[132:133], v[140:141], v[142:143] op_sel_hi:[1,0]
	v_pk_mul_f32 v[130:131], v[4:5], v[130:131]
	v_pk_mul_f32 v[132:133], v[6:7], v[132:133]
	global_store_dwordx4 v[144:145], v[130:133], off offset:1024 nt
	s_nop 1
	v_pk_mul_f32 v[130:131], v[134:135], v[142:143] op_sel_hi:[1,0]
	v_pk_mul_f32 v[132:133], v[136:137], v[142:143] op_sel_hi:[1,0]
	v_pk_mul_f32 v[130:131], v[8:9], v[130:131]
	v_pk_mul_f32 v[132:133], v[10:11], v[132:133]
	global_store_dwordx4 v[144:145], v[130:133], off offset:2048 nt
	s_nop 1
	v_pk_mul_f32 v[130:131], v[146:147], v[142:143] op_sel_hi:[1,0]
	v_pk_mul_f32 v[132:133], v[150:151], v[142:143] op_sel_hi:[1,0]
	v_pk_mul_f32 v[130:131], v[12:13], v[130:131]
	v_pk_mul_f32 v[132:133], v[14:15], v[132:133]
	global_store_dwordx4 v[144:145], v[130:133], off offset:3072 nt
	s_and_saveexec_b64 s[6:7], vcc
	s_cbranch_execz .LBB0_1561
	v_lshlrev_b32_e32 v130, 16, v118
	v_and_b32_e32 v131, 0xffff0000, v118
	v_lshlrev_b32_e32 v118, 16, v119
	v_and_b32_e32 v119, 0xffff0000, v119
	v_lshlrev_b32_e32 v132, 16, v120
	v_and_b32_e32 v133, 0xffff0000, v120
	v_lshlrev_b32_e32 v120, 16, v121
	v_and_b32_e32 v121, 0xffff0000, v121
	v_pk_add_f32 v[118:119], v[118:119], v[120:121]
	v_pk_add_f32 v[120:121], v[130:131], v[132:133]
	v_lshlrev_b32_e32 v130, 16, v114
	v_and_b32_e32 v131, 0xffff0000, v114
	v_lshlrev_b32_e32 v114, 16, v115
	v_and_b32_e32 v115, 0xffff0000, v115
	v_lshlrev_b32_e32 v132, 16, v116
	v_and_b32_e32 v133, 0xffff0000, v116
	v_lshlrev_b32_e32 v116, 16, v117
	v_and_b32_e32 v117, 0xffff0000, v117
	v_pk_add_f32 v[114:115], v[114:115], v[116:117]
	v_pk_add_f32 v[116:117], v[130:131], v[132:133]
	v_lshlrev_b32_e32 v130, 16, v110
	v_and_b32_e32 v131, 0xffff0000, v110
	v_lshlrev_b32_e32 v110, 16, v111
	v_and_b32_e32 v111, 0xffff0000, v111
	v_lshlrev_b32_e32 v132, 16, v112
	v_and_b32_e32 v133, 0xffff0000, v112
	v_lshlrev_b32_e32 v112, 16, v113
	v_and_b32_e32 v113, 0xffff0000, v113
	v_pk_add_f32 v[110:111], v[110:111], v[112:113]
	v_pk_add_f32 v[112:113], v[130:131], v[132:133]
	v_lshlrev_b32_e32 v130, 16, v106
	v_and_b32_e32 v131, 0xffff0000, v106
	v_lshlrev_b32_e32 v106, 16, v107
	v_and_b32_e32 v107, 0xffff0000, v107
	v_lshlrev_b32_e32 v132, 16, v108
	v_and_b32_e32 v133, 0xffff0000, v108
	v_lshlrev_b32_e32 v108, 16, v109
	v_and_b32_e32 v109, 0xffff0000, v109
	v_pk_add_f32 v[106:107], v[106:107], v[108:109]
	v_pk_add_f32 v[108:109], v[130:131], v[132:133]
	v_mov_b32_e32 v133, v113
	v_mov_b32_e32 v132, v109
	v_mov_b32_e32 v130, v108
	v_mov_b32_e32 v131, v112
	v_pk_mul_f32 v[132:133], v[132:133], v[132:133]
	v_mov_b32_e32 v134, v117
	v_pk_fma_f32 v[130:131], v[130:131], v[130:131], v[132:133]
	v_mov_b32_e32 v132, v106
	v_mov_b32_e32 v133, v110
	v_pk_fma_f32 v[130:131], v[132:133], v[132:133], v[130:131]
	v_mov_b32_e32 v132, v107
	v_mov_b32_e32 v133, v111
	v_mov_b32_e32 v135, v121
	v_pk_fma_f32 v[130:131], v[132:133], v[132:133], v[130:131]
	v_mov_b32_e32 v132, v116
	v_mov_b32_e32 v133, v120
	v_pk_mul_f32 v[134:135], v[134:135], v[134:135]
	v_add_f32_e32 v53, v130, v131
	v_pk_fma_f32 v[132:133], v[132:133], v[132:133], v[134:135]
	v_mov_b32_e32 v134, v114
	v_mov_b32_e32 v135, v118
	v_pk_fma_f32 v[132:133], v[134:135], v[134:135], v[132:133]
	v_mov_b32_e32 v134, v115
	v_mov_b32_e32 v135, v119
	v_pk_fma_f32 v[132:133], v[134:135], v[134:135], v[132:133]
	s_nop 0
	v_add_f32_e32 v53, v53, v132
	v_add_f32_e32 v53, v53, v133
	ds_bpermute_b32 v71, v122, v53
	v_lshl_add_u64 v[132:133], v[32:33], 0, v[26:27]
	s_waitcnt lgkmcnt(0)
	v_add_f32_e32 v53, v53, v71
	ds_bpermute_b32 v71, v123, v53
	s_waitcnt lgkmcnt(0)
	v_add_f32_e32 v53, v53, v71
	s_nop 1
	v_add_f32_dpp v53, v53, v53 row_ror:8 row_mask:0xf bank_mask:0xf
	s_nop 1
	v_add_f32_dpp v53, v53, v53 row_ror:4 row_mask:0xf bank_mask:0xf
	s_nop 1
	v_add_f32_dpp v53, v53, v53 quad_perm:[2,3,0,1] row_mask:0xf bank_mask:0xf
	s_nop 1
	v_add_f32_dpp v53, v53, v53 quad_perm:[1,0,3,2] row_mask:0xf bank_mask:0xf
	v_fmamk_f32 v53, v53, 0x3a800000, v31
	v_rsq_f32_e32 v53, v53
	s_nop 0
	v_mov_b32_e32 v130, v53
	v_pk_mul_f32 v[134:135], v[108:109], v[130:131] op_sel_hi:[1,0]
	v_pk_mul_f32 v[106:107], v[106:107], v[130:131] op_sel_hi:[1,0]
	s_nop 0
	v_pk_mul_f32 v[108:109], v[2:3], v[106:107]
	v_pk_mul_f32 v[106:107], v[0:1], v[134:135]
	global_store_dwordx4 v[132:133], v[106:109], off nt
	s_nop 1
	v_pk_mul_f32 v[106:107], v[112:113], v[130:131] op_sel_hi:[1,0]
	v_pk_mul_f32 v[108:109], v[110:111], v[130:131] op_sel_hi:[1,0]
	v_pk_mul_f32 v[106:107], v[4:5], v[106:107]
	v_pk_mul_f32 v[108:109], v[6:7], v[108:109]
	global_store_dwordx4 v[132:133], v[106:109], off offset:1024 nt
	s_nop 1
	v_pk_mul_f32 v[106:107], v[116:117], v[130:131] op_sel_hi:[1,0]
	v_pk_mul_f32 v[108:109], v[114:115], v[130:131] op_sel_hi:[1,0]
	v_pk_mul_f32 v[106:107], v[8:9], v[106:107]
	v_pk_mul_f32 v[108:109], v[10:11], v[108:109]
	global_store_dwordx4 v[132:133], v[106:109], off offset:2048 nt
	s_nop 1
	v_pk_mul_f32 v[106:107], v[120:121], v[130:131] op_sel_hi:[1,0]
	v_pk_mul_f32 v[108:109], v[118:119], v[130:131] op_sel_hi:[1,0]
	v_pk_mul_f32 v[106:107], v[12:13], v[106:107]
	v_pk_mul_f32 v[108:109], v[14:15], v[108:109]
	global_store_dwordx4 v[132:133], v[106:109], off offset:3072 nt
.LBB0_1561:
	s_or_b64 exec, exec, s[6:7]
	v_add_u32_e32 v35, s33, v35
	v_cmp_gt_i32_e32 vcc, s8, v35
	s_and_saveexec_b64 s[6:7], vcc
	s_cbranch_execz .LBB0_1563
	s_waitcnt vmcnt(31)
	v_lshlrev_b32_e32 v106, 16, v104
	v_and_b32_e32 v107, 0xffff0000, v104
	v_lshlrev_b32_e32 v104, 16, v105
	v_and_b32_e32 v105, 0xffff0000, v105
	v_lshlrev_b32_e32 v108, 16, v102
	v_and_b32_e32 v109, 0xffff0000, v102
	v_lshlrev_b32_e32 v102, 16, v103
	v_and_b32_e32 v103, 0xffff0000, v103
	v_pk_add_f32 v[102:103], v[102:103], v[104:105]
	v_pk_add_f32 v[104:105], v[108:109], v[106:107]
	s_waitcnt vmcnt(30)
	v_lshlrev_b32_e32 v106, 16, v100
	v_and_b32_e32 v107, 0xffff0000, v100
	v_lshlrev_b32_e32 v100, 16, v101
	v_and_b32_e32 v101, 0xffff0000, v101
	v_lshlrev_b32_e32 v108, 16, v98
	v_and_b32_e32 v109, 0xffff0000, v98
	v_lshlrev_b32_e32 v98, 16, v99
	v_and_b32_e32 v99, 0xffff0000, v99
	v_pk_add_f32 v[98:99], v[98:99], v[100:101]
	v_pk_add_f32 v[100:101], v[108:109], v[106:107]
	s_waitcnt vmcnt(29)
	v_lshlrev_b32_e32 v106, 16, v96
	v_and_b32_e32 v107, 0xffff0000, v96
	v_lshlrev_b32_e32 v96, 16, v97
	v_and_b32_e32 v97, 0xffff0000, v97
	v_lshlrev_b32_e32 v108, 16, v94
	v_and_b32_e32 v109, 0xffff0000, v94
	v_lshlrev_b32_e32 v94, 16, v95
	v_and_b32_e32 v95, 0xffff0000, v95
	v_pk_add_f32 v[94:95], v[94:95], v[96:97]
	v_pk_add_f32 v[96:97], v[108:109], v[106:107]
	s_waitcnt vmcnt(28)
	v_lshlrev_b32_e32 v106, 16, v92
	v_and_b32_e32 v107, 0xffff0000, v92
	v_lshlrev_b32_e32 v108, 16, v90
	v_and_b32_e32 v109, 0xffff0000, v90
	v_lshlrev_b32_e32 v92, 16, v93
	v_and_b32_e32 v93, 0xffff0000, v93
	v_lshlrev_b32_e32 v90, 16, v91
	v_and_b32_e32 v91, 0xffff0000, v91
	v_pk_add_f32 v[106:107], v[108:109], v[106:107]
	v_mov_b32_e32 v108, v105
	v_mov_b32_e32 v109, v101
	v_pk_add_f32 v[92:93], v[90:91], v[92:93]
	v_mov_b32_e32 v90, v104
	v_mov_b32_e32 v91, v100
	v_pk_mul_f32 v[108:109], v[108:109], v[108:109]
	v_mov_b32_e32 v110, v97
	v_pk_fma_f32 v[90:91], v[90:91], v[90:91], v[108:109]
	v_mov_b32_e32 v108, v102
	v_mov_b32_e32 v109, v98
	v_pk_fma_f32 v[90:91], v[108:109], v[108:109], v[90:91]
	v_mov_b32_e32 v108, v103
	v_mov_b32_e32 v109, v99
	v_mov_b32_e32 v111, v107
	v_pk_fma_f32 v[90:91], v[108:109], v[108:109], v[90:91]
	v_mov_b32_e32 v108, v96
	v_mov_b32_e32 v109, v106
	v_pk_mul_f32 v[110:111], v[110:111], v[110:111]
	v_add_f32_e32 v53, v90, v91
	v_pk_fma_f32 v[108:109], v[108:109], v[108:109], v[110:111]
	v_mov_b32_e32 v110, v94
	v_mov_b32_e32 v111, v92
	v_pk_fma_f32 v[108:109], v[110:111], v[110:111], v[108:109]
	v_mov_b32_e32 v110, v95
	v_mov_b32_e32 v111, v93
	v_pk_fma_f32 v[108:109], v[110:111], v[110:111], v[108:109]
	v_ashrrev_i32_e32 v89, 31, v88
	v_add_f32_e32 v53, v53, v108
	v_add_f32_e32 v53, v53, v109
	ds_bpermute_b32 v71, v122, v53
	v_lshlrev_b64 v[88:89], 12, v[88:89]
	v_lshl_add_u64 v[110:111], v[20:21], 0, v[88:89]
	s_waitcnt lgkmcnt(0)
	v_add_f32_e32 v53, v53, v71
	ds_bpermute_b32 v71, v123, v53
	s_waitcnt lgkmcnt(0)
	v_add_f32_e32 v53, v53, v71
	s_nop 1
	v_add_f32_dpp v53, v53, v53 row_ror:8 row_mask:0xf bank_mask:0xf
	s_nop 1
	v_add_f32_dpp v53, v53, v53 row_ror:4 row_mask:0xf bank_mask:0xf
	s_nop 1
	v_add_f32_dpp v53, v53, v53 quad_perm:[2,3,0,1] row_mask:0xf bank_mask:0xf
	s_nop 1
	v_add_f32_dpp v53, v53, v53 quad_perm:[1,0,3,2] row_mask:0xf bank_mask:0xf
	v_fmamk_f32 v53, v53, 0x3a800000, v31
	v_rsq_f32_e32 v53, v53
	s_nop 0
	v_mov_b32_e32 v108, v53
	v_pk_mul_f32 v[88:89], v[104:105], v[108:109] op_sel_hi:[1,0]
	v_pk_mul_f32 v[90:91], v[102:103], v[108:109] op_sel_hi:[1,0]
	v_pk_mul_f32 v[88:89], v[0:1], v[88:89]
	v_pk_mul_f32 v[90:91], v[2:3], v[90:91]
	global_store_dwordx4 v[110:111], v[88:91], off nt
	s_nop 1
	v_pk_mul_f32 v[88:89], v[100:101], v[108:109] op_sel_hi:[1,0]
	v_pk_mul_f32 v[90:91], v[98:99], v[108:109] op_sel_hi:[1,0]
	v_pk_mul_f32 v[88:89], v[4:5], v[88:89]
	v_pk_mul_f32 v[90:91], v[6:7], v[90:91]
	global_store_dwordx4 v[110:111], v[88:91], off offset:1024 nt
	s_nop 1
	v_pk_mul_f32 v[88:89], v[96:97], v[108:109] op_sel_hi:[1,0]
	v_pk_mul_f32 v[90:91], v[94:95], v[108:109] op_sel_hi:[1,0]
	v_pk_mul_f32 v[88:89], v[8:9], v[88:89]
	v_pk_mul_f32 v[90:91], v[10:11], v[90:91]
	global_store_dwordx4 v[110:111], v[88:91], off offset:2048 nt
	s_nop 1
	v_pk_mul_f32 v[88:89], v[106:107], v[108:109] op_sel_hi:[1,0]
	v_pk_mul_f32 v[90:91], v[92:93], v[108:109] op_sel_hi:[1,0]
	v_pk_mul_f32 v[88:89], v[12:13], v[88:89]
	v_pk_mul_f32 v[90:91], v[14:15], v[90:91]
	global_store_dwordx4 v[110:111], v[88:91], off offset:3072 nt
.LBB0_1563:
	s_or_b64 exec, exec, s[6:7]
	v_add_u32_e32 v35, s33, v35
	v_cmp_gt_i32_e32 vcc, s8, v35
	s_and_saveexec_b64 s[6:7], vcc
	s_cbranch_execz .LBB0_1565
	s_waitcnt vmcnt(23)
	v_lshlrev_b32_e32 v88, 16, v86
	v_and_b32_e32 v89, 0xffff0000, v86
	v_lshlrev_b32_e32 v86, 16, v87
	v_and_b32_e32 v87, 0xffff0000, v87
	v_lshlrev_b32_e32 v90, 16, v84
	v_and_b32_e32 v91, 0xffff0000, v84
	v_lshlrev_b32_e32 v84, 16, v85
	v_and_b32_e32 v85, 0xffff0000, v85
	v_pk_add_f32 v[84:85], v[84:85], v[86:87]
	v_pk_add_f32 v[86:87], v[90:91], v[88:89]
	s_waitcnt vmcnt(22)
	v_lshlrev_b32_e32 v88, 16, v82
	v_and_b32_e32 v89, 0xffff0000, v82
	v_lshlrev_b32_e32 v82, 16, v83
	v_and_b32_e32 v83, 0xffff0000, v83
	v_lshlrev_b32_e32 v90, 16, v80
	v_and_b32_e32 v91, 0xffff0000, v80
	v_lshlrev_b32_e32 v80, 16, v81
	v_and_b32_e32 v81, 0xffff0000, v81
	v_pk_add_f32 v[80:81], v[80:81], v[82:83]
	v_pk_add_f32 v[82:83], v[90:91], v[88:89]
	s_waitcnt vmcnt(21)
	v_lshlrev_b32_e32 v88, 16, v78
	v_and_b32_e32 v89, 0xffff0000, v78
	v_lshlrev_b32_e32 v78, 16, v79
	v_and_b32_e32 v79, 0xffff0000, v79
	v_lshlrev_b32_e32 v90, 16, v76
	v_and_b32_e32 v91, 0xffff0000, v76
	v_lshlrev_b32_e32 v76, 16, v77
	v_and_b32_e32 v77, 0xffff0000, v77
	v_pk_add_f32 v[76:77], v[76:77], v[78:79]
	v_pk_add_f32 v[78:79], v[90:91], v[88:89]
	s_waitcnt vmcnt(20)
	v_lshlrev_b32_e32 v88, 16, v74
	v_and_b32_e32 v89, 0xffff0000, v74
	v_lshlrev_b32_e32 v90, 16, v72
	v_and_b32_e32 v91, 0xffff0000, v72
	v_lshlrev_b32_e32 v74, 16, v75
	v_and_b32_e32 v75, 0xffff0000, v75
	v_lshlrev_b32_e32 v72, 16, v73
	v_and_b32_e32 v73, 0xffff0000, v73
	v_pk_add_f32 v[88:89], v[90:91], v[88:89]
	v_mov_b32_e32 v90, v87
	v_mov_b32_e32 v91, v83
	v_pk_add_f32 v[74:75], v[72:73], v[74:75]
	v_mov_b32_e32 v72, v86
	v_mov_b32_e32 v73, v82
	v_pk_mul_f32 v[90:91], v[90:91], v[90:91]
	v_mov_b32_e32 v92, v79
	v_pk_fma_f32 v[72:73], v[72:73], v[72:73], v[90:91]
	v_mov_b32_e32 v90, v84
	v_mov_b32_e32 v91, v80
	v_pk_fma_f32 v[72:73], v[90:91], v[90:91], v[72:73]
	v_mov_b32_e32 v90, v85
	v_mov_b32_e32 v91, v81
	v_mov_b32_e32 v93, v89
	v_pk_fma_f32 v[72:73], v[90:91], v[90:91], v[72:73]
	v_mov_b32_e32 v90, v78
	v_mov_b32_e32 v91, v88
	v_pk_mul_f32 v[92:93], v[92:93], v[92:93]
	v_add_f32_e32 v53, v72, v73
	v_pk_fma_f32 v[90:91], v[90:91], v[90:91], v[92:93]
	v_mov_b32_e32 v92, v76
	v_mov_b32_e32 v93, v74
	v_pk_fma_f32 v[90:91], v[92:93], v[92:93], v[90:91]
	v_mov_b32_e32 v92, v77
	v_mov_b32_e32 v93, v75
	v_pk_fma_f32 v[90:91], v[92:93], v[92:93], v[90:91]
	s_nop 0
	v_add_f32_e32 v53, v53, v90
	v_add_f32_e32 v53, v53, v91
	ds_bpermute_b32 v71, v122, v53
	s_waitcnt lgkmcnt(0)
	v_add_f32_e32 v53, v53, v71
	ds_bpermute_b32 v71, v123, v53
	s_waitcnt lgkmcnt(0)
	v_add_f32_e32 v53, v53, v71
	s_nop 1
	v_add_f32_dpp v53, v53, v53 row_ror:8 row_mask:0xf bank_mask:0xf
	s_nop 1
	v_add_f32_dpp v53, v53, v53 row_ror:4 row_mask:0xf bank_mask:0xf
	s_nop 1
	v_add_f32_dpp v53, v53, v53 quad_perm:[2,3,0,1] row_mask:0xf bank_mask:0xf
	s_nop 1
	v_add_f32_dpp v53, v53, v53 quad_perm:[1,0,3,2] row_mask:0xf bank_mask:0xf
	v_fmamk_f32 v53, v53, 0x3a800000, v31
	v_rsq_f32_e32 v53, v53
	v_ashrrev_i32_e32 v71, 31, v70
	v_lshlrev_b64 v[70:71], 12, v[70:71]
	v_lshl_add_u64 v[92:93], v[20:21], 0, v[70:71]
	v_mov_b32_e32 v90, v53
	v_pk_mul_f32 v[70:71], v[86:87], v[90:91] op_sel_hi:[1,0]
	v_pk_mul_f32 v[72:73], v[84:85], v[90:91] op_sel_hi:[1,0]
	v_pk_mul_f32 v[70:71], v[0:1], v[70:71]
	v_pk_mul_f32 v[72:73], v[2:3], v[72:73]
	global_store_dwordx4 v[92:93], v[70:73], off nt
	s_nop 1
	v_pk_mul_f32 v[70:71], v[82:83], v[90:91] op_sel_hi:[1,0]
	v_pk_mul_f32 v[72:73], v[80:81], v[90:91] op_sel_hi:[1,0]
	v_pk_mul_f32 v[70:71], v[4:5], v[70:71]
	v_pk_mul_f32 v[72:73], v[6:7], v[72:73]
	global_store_dwordx4 v[92:93], v[70:73], off offset:1024 nt
	s_nop 1
	v_pk_mul_f32 v[70:71], v[78:79], v[90:91] op_sel_hi:[1,0]
	v_pk_mul_f32 v[72:73], v[76:77], v[90:91] op_sel_hi:[1,0]
	v_pk_mul_f32 v[70:71], v[8:9], v[70:71]
	v_pk_mul_f32 v[72:73], v[10:11], v[72:73]
	global_store_dwordx4 v[92:93], v[70:73], off offset:2048 nt
	s_nop 1
	v_pk_mul_f32 v[70:71], v[88:89], v[90:91] op_sel_hi:[1,0]
	v_pk_mul_f32 v[72:73], v[74:75], v[90:91] op_sel_hi:[1,0]
	v_pk_mul_f32 v[70:71], v[12:13], v[70:71]
	v_pk_mul_f32 v[72:73], v[14:15], v[72:73]
	global_store_dwordx4 v[92:93], v[70:73], off offset:3072 nt
.LBB0_1565:
	s_or_b64 exec, exec, s[6:7]
	v_add_u32_e32 v35, s33, v35
	v_cmp_gt_i32_e32 vcc, s8, v35
	s_and_saveexec_b64 s[6:7], vcc
	s_cbranch_execz .LBB0_1567
	s_waitcnt vmcnt(15)
	v_lshlrev_b32_e32 v70, 16, v68
	v_and_b32_e32 v71, 0xffff0000, v68
	v_lshlrev_b32_e32 v68, 16, v69
	v_and_b32_e32 v69, 0xffff0000, v69
	v_lshlrev_b32_e32 v72, 16, v66
	v_and_b32_e32 v73, 0xffff0000, v66
	v_lshlrev_b32_e32 v66, 16, v67
	v_and_b32_e32 v67, 0xffff0000, v67
	v_pk_add_f32 v[66:67], v[66:67], v[68:69]
	v_pk_add_f32 v[68:69], v[72:73], v[70:71]
	s_waitcnt vmcnt(14)
	v_lshlrev_b32_e32 v70, 16, v64
	v_and_b32_e32 v71, 0xffff0000, v64
	v_lshlrev_b32_e32 v64, 16, v65
	v_and_b32_e32 v65, 0xffff0000, v65
	v_lshlrev_b32_e32 v72, 16, v62
	v_and_b32_e32 v73, 0xffff0000, v62
	v_lshlrev_b32_e32 v62, 16, v63
	v_and_b32_e32 v63, 0xffff0000, v63
	v_pk_add_f32 v[62:63], v[62:63], v[64:65]
	v_pk_add_f32 v[64:65], v[72:73], v[70:71]
	s_waitcnt vmcnt(13)
	v_lshlrev_b32_e32 v70, 16, v60
	v_and_b32_e32 v71, 0xffff0000, v60
	v_lshlrev_b32_e32 v60, 16, v61
	v_and_b32_e32 v61, 0xffff0000, v61
	v_lshlrev_b32_e32 v72, 16, v58
	v_and_b32_e32 v73, 0xffff0000, v58
	v_lshlrev_b32_e32 v58, 16, v59
	v_and_b32_e32 v59, 0xffff0000, v59
	v_pk_add_f32 v[58:59], v[58:59], v[60:61]
	v_pk_add_f32 v[60:61], v[72:73], v[70:71]
	s_waitcnt vmcnt(12)
	v_lshlrev_b32_e32 v70, 16, v56
	v_and_b32_e32 v71, 0xffff0000, v56
	v_lshlrev_b32_e32 v72, 16, v54
	v_and_b32_e32 v73, 0xffff0000, v54
	v_lshlrev_b32_e32 v56, 16, v57
	v_and_b32_e32 v57, 0xffff0000, v57
	v_lshlrev_b32_e32 v54, 16, v55
	v_and_b32_e32 v55, 0xffff0000, v55
	v_pk_add_f32 v[70:71], v[72:73], v[70:71]
	v_mov_b32_e32 v72, v69
	v_mov_b32_e32 v73, v65
	v_pk_add_f32 v[56:57], v[54:55], v[56:57]
	v_mov_b32_e32 v54, v68
	v_mov_b32_e32 v55, v64
	v_pk_mul_f32 v[72:73], v[72:73], v[72:73]
	v_mov_b32_e32 v74, v61
	v_pk_fma_f32 v[54:55], v[54:55], v[54:55], v[72:73]
	v_mov_b32_e32 v72, v66
	v_mov_b32_e32 v73, v62
	v_pk_fma_f32 v[54:55], v[72:73], v[72:73], v[54:55]
	v_mov_b32_e32 v72, v67
	v_mov_b32_e32 v73, v63
	v_mov_b32_e32 v75, v71
	v_pk_fma_f32 v[54:55], v[72:73], v[72:73], v[54:55]
	v_mov_b32_e32 v72, v60
	v_mov_b32_e32 v73, v70
	v_pk_mul_f32 v[74:75], v[74:75], v[74:75]
	v_add_f32_e32 v53, v54, v55
	v_pk_fma_f32 v[72:73], v[72:73], v[72:73], v[74:75]
	v_mov_b32_e32 v74, v58
	v_mov_b32_e32 v75, v56
	v_pk_fma_f32 v[72:73], v[74:75], v[74:75], v[72:73]
	v_mov_b32_e32 v74, v59
	v_mov_b32_e32 v75, v57
	v_pk_fma_f32 v[72:73], v[74:75], v[74:75], v[72:73]
	s_nop 0
	v_add_f32_e32 v53, v53, v72
	v_add_f32_e32 v53, v53, v73
	ds_bpermute_b32 v54, v122, v53
	s_waitcnt lgkmcnt(0)
	v_add_f32_e32 v53, v53, v54
	ds_bpermute_b32 v54, v123, v53
	s_waitcnt lgkmcnt(0)
	v_add_f32_e32 v53, v53, v54
	s_nop 1
	v_add_f32_dpp v53, v53, v53 row_ror:8 row_mask:0xf bank_mask:0xf
	s_nop 1
	v_add_f32_dpp v53, v53, v53 row_ror:4 row_mask:0xf bank_mask:0xf
	s_nop 1
	v_add_f32_dpp v53, v53, v53 quad_perm:[2,3,0,1] row_mask:0xf bank_mask:0xf
	s_nop 1
	v_add_f32_dpp v53, v53, v53 quad_perm:[1,0,3,2] row_mask:0xf bank_mask:0xf
	v_fmamk_f32 v53, v53, 0x3a800000, v31
	v_rsq_f32_e32 v54, v53
	v_ashrrev_i32_e32 v53, 31, v52
	v_lshlrev_b64 v[52:53], 12, v[52:53]
	v_lshl_add_u64 v[74:75], v[20:21], 0, v[52:53]
	v_mov_b32_e32 v72, v54
	v_pk_mul_f32 v[52:53], v[68:69], v[72:73] op_sel_hi:[1,0]
	v_pk_mul_f32 v[54:55], v[66:67], v[72:73] op_sel_hi:[1,0]
	v_pk_mul_f32 v[52:53], v[0:1], v[52:53]
	v_pk_mul_f32 v[54:55], v[2:3], v[54:55]
	global_store_dwordx4 v[74:75], v[52:55], off nt
	s_nop 1
	v_pk_mul_f32 v[52:53], v[64:65], v[72:73] op_sel_hi:[1,0]
	v_pk_mul_f32 v[54:55], v[62:63], v[72:73] op_sel_hi:[1,0]
	v_pk_mul_f32 v[52:53], v[4:5], v[52:53]
	v_pk_mul_f32 v[54:55], v[6:7], v[54:55]
	global_store_dwordx4 v[74:75], v[52:55], off offset:1024 nt
	s_nop 1
	v_pk_mul_f32 v[52:53], v[60:61], v[72:73] op_sel_hi:[1,0]
	v_pk_mul_f32 v[54:55], v[58:59], v[72:73] op_sel_hi:[1,0]
	v_pk_mul_f32 v[52:53], v[8:9], v[52:53]
	v_pk_mul_f32 v[54:55], v[10:11], v[54:55]
	global_store_dwordx4 v[74:75], v[52:55], off offset:2048 nt
	s_nop 1
	v_pk_mul_f32 v[52:53], v[70:71], v[72:73] op_sel_hi:[1,0]
	v_pk_mul_f32 v[54:55], v[56:57], v[72:73] op_sel_hi:[1,0]
	v_pk_mul_f32 v[52:53], v[12:13], v[52:53]
	v_pk_mul_f32 v[54:55], v[14:15], v[54:55]
	global_store_dwordx4 v[74:75], v[52:55], off offset:3072 nt
.LBB0_1567:
	s_or_b64 exec, exec, s[6:7]
	s_nop 0
	v_add_u32_e32 v52, s33, v35
	v_cmp_gt_i32_e32 vcc, s8, v52
	s_and_saveexec_b64 s[6:7], vcc
	s_cbranch_execz .LBB0_1558
	s_waitcnt vmcnt(7)
	v_lshlrev_b32_e32 v54, 16, v50
	v_and_b32_e32 v55, 0xffff0000, v50
	v_lshlrev_b32_e32 v50, 16, v51
	v_and_b32_e32 v51, 0xffff0000, v51
	v_lshlrev_b32_e32 v56, 16, v48
	v_and_b32_e32 v57, 0xffff0000, v48
	v_lshlrev_b32_e32 v48, 16, v49
	v_and_b32_e32 v49, 0xffff0000, v49
	v_pk_add_f32 v[48:49], v[48:49], v[50:51]
	v_pk_add_f32 v[50:51], v[56:57], v[54:55]
	s_waitcnt vmcnt(6)
	v_lshlrev_b32_e32 v54, 16, v46
	v_and_b32_e32 v55, 0xffff0000, v46
	v_lshlrev_b32_e32 v46, 16, v47
	v_and_b32_e32 v47, 0xffff0000, v47
	v_lshlrev_b32_e32 v56, 16, v44
	v_and_b32_e32 v57, 0xffff0000, v44
	v_lshlrev_b32_e32 v44, 16, v45
	v_and_b32_e32 v45, 0xffff0000, v45
	v_pk_add_f32 v[44:45], v[44:45], v[46:47]
	v_pk_add_f32 v[46:47], v[56:57], v[54:55]
	s_waitcnt vmcnt(5)
	v_lshlrev_b32_e32 v54, 16, v42
	v_and_b32_e32 v55, 0xffff0000, v42
	v_lshlrev_b32_e32 v42, 16, v43
	v_and_b32_e32 v43, 0xffff0000, v43
	v_lshlrev_b32_e32 v56, 16, v40
	v_and_b32_e32 v57, 0xffff0000, v40
	v_lshlrev_b32_e32 v40, 16, v41
	v_and_b32_e32 v41, 0xffff0000, v41
	v_pk_add_f32 v[40:41], v[40:41], v[42:43]
	v_pk_add_f32 v[42:43], v[56:57], v[54:55]
	s_waitcnt vmcnt(4)
	v_lshlrev_b32_e32 v54, 16, v38
	v_and_b32_e32 v55, 0xffff0000, v38
	v_lshlrev_b32_e32 v56, 16, v36
	v_and_b32_e32 v57, 0xffff0000, v36
	v_lshlrev_b32_e32 v38, 16, v39
	v_and_b32_e32 v39, 0xffff0000, v39
	v_lshlrev_b32_e32 v36, 16, v37
	v_and_b32_e32 v37, 0xffff0000, v37
	v_pk_add_f32 v[54:55], v[56:57], v[54:55]
	v_mov_b32_e32 v56, v51
	v_mov_b32_e32 v57, v47
	v_pk_add_f32 v[38:39], v[36:37], v[38:39]
	v_mov_b32_e32 v36, v50
	v_mov_b32_e32 v37, v46
	v_pk_mul_f32 v[56:57], v[56:57], v[56:57]
	v_mov_b32_e32 v58, v43
	v_pk_fma_f32 v[36:37], v[36:37], v[36:37], v[56:57]
	v_mov_b32_e32 v56, v48
	v_mov_b32_e32 v57, v44
	v_pk_fma_f32 v[36:37], v[56:57], v[56:57], v[36:37]
	v_mov_b32_e32 v56, v49
	v_mov_b32_e32 v57, v45
	v_mov_b32_e32 v59, v55
	v_pk_fma_f32 v[36:37], v[56:57], v[56:57], v[36:37]
	v_mov_b32_e32 v56, v42
	v_mov_b32_e32 v57, v54
	v_pk_mul_f32 v[58:59], v[58:59], v[58:59]
	v_add_f32_e32 v35, v36, v37
	v_pk_fma_f32 v[56:57], v[56:57], v[56:57], v[58:59]
	v_mov_b32_e32 v58, v40
	v_mov_b32_e32 v59, v38
	v_pk_fma_f32 v[56:57], v[58:59], v[58:59], v[56:57]
	v_mov_b32_e32 v58, v41
	v_mov_b32_e32 v59, v39
	v_pk_fma_f32 v[56:57], v[58:59], v[58:59], v[56:57]
	s_nop 0
	v_add_f32_e32 v35, v35, v56
	v_add_f32_e32 v35, v35, v57
	ds_bpermute_b32 v36, v122, v35
	s_waitcnt lgkmcnt(0)
	v_add_f32_e32 v35, v35, v36
	ds_bpermute_b32 v36, v123, v35
	s_waitcnt lgkmcnt(0)
	v_add_f32_e32 v35, v35, v36
	s_nop 1
	v_add_f32_dpp v35, v35, v35 row_ror:8 row_mask:0xf bank_mask:0xf
	s_nop 1
	v_add_f32_dpp v35, v35, v35 row_ror:4 row_mask:0xf bank_mask:0xf
	s_nop 1
	v_add_f32_dpp v35, v35, v35 quad_perm:[2,3,0,1] row_mask:0xf bank_mask:0xf
	s_nop 1
	v_add_f32_dpp v35, v35, v35 quad_perm:[1,0,3,2] row_mask:0xf bank_mask:0xf
	v_fmamk_f32 v35, v35, 0x3a800000, v31
	v_rsq_f32_e32 v36, v35
	v_ashrrev_i32_e32 v35, 31, v34
	v_lshlrev_b64 v[34:35], 12, v[34:35]
	v_lshl_add_u64 v[58:59], v[20:21], 0, v[34:35]
	v_mov_b32_e32 v56, v36
	v_pk_mul_f32 v[34:35], v[50:51], v[56:57] op_sel_hi:[1,0]
	v_pk_mul_f32 v[36:37], v[48:49], v[56:57] op_sel_hi:[1,0]
	v_pk_mul_f32 v[34:35], v[0:1], v[34:35]
	v_pk_mul_f32 v[36:37], v[2:3], v[36:37]
	global_store_dwordx4 v[58:59], v[34:37], off nt
	s_nop 1
	v_pk_mul_f32 v[34:35], v[46:47], v[56:57] op_sel_hi:[1,0]
	v_pk_mul_f32 v[36:37], v[44:45], v[56:57] op_sel_hi:[1,0]
	v_pk_mul_f32 v[34:35], v[4:5], v[34:35]
	v_pk_mul_f32 v[36:37], v[6:7], v[36:37]
	global_store_dwordx4 v[58:59], v[34:37], off offset:1024 nt
	s_nop 1
	v_pk_mul_f32 v[34:35], v[42:43], v[56:57] op_sel_hi:[1,0]
	v_pk_mul_f32 v[36:37], v[40:41], v[56:57] op_sel_hi:[1,0]
	v_pk_mul_f32 v[34:35], v[8:9], v[34:35]
	v_pk_mul_f32 v[36:37], v[10:11], v[36:37]
	global_store_dwordx4 v[58:59], v[34:37], off offset:2048 nt
	s_nop 1
	v_pk_mul_f32 v[34:35], v[54:55], v[56:57] op_sel_hi:[1,0]
	v_pk_mul_f32 v[36:37], v[38:39], v[56:57] op_sel_hi:[1,0]
	v_pk_mul_f32 v[34:35], v[12:13], v[34:35]
	v_pk_mul_f32 v[36:37], v[14:15], v[36:37]
	global_store_dwordx4 v[58:59], v[34:37], off offset:3072 nt
	s_branch .LBB0_1558
